# ffn_down down-GEMM K-loop: register-staged global loads with two K-steps in flight instead of LDS-DMA double buffer; LDS fragment reads software-pipelined
# baseline (speedup 1.0000x reference)
; __device__ __forceinline__ int ltid() { int t = (int)threadIdx.x; asm volatile("" : "+v"(t)); return t; }
; #define MFMA(a, b, c) __builtin_amdgcn_mfma_f32_32x32x16_bf16(a, b, c, 0, 0, 0)
; template <bool HALO, class AL, class BL>
; __device__ __forceinline__ void gemm_core(f32x16 (&acc)[2][2], f32x16& hacc, const AL& al, const BL& bl, int K, char* lds,
;                                           const u16* halo0, const u16* halo1, int brow0, int brow1) {
;     ...
;   const int tid = ltid(), lane = tid & 63, wid = tid >> 6, wr = wid >> 1, r32 = lane & 31, hi = lane >> 5;
;   const int lrow = tid >> 3, cg = ((tid & 7) ^ ((lrow >> 1) & 7)) * 8;
;   const u16* gh = nullptr;
;   if (HALO) { const int c = ((lane & 7) ^ ((lane >> 4) & 7)) * 8; gh = ((lane < 8) ? halo0 : halo1) + c; }
;   char* lw = lds + tid * 16;
;     ...
;   const int sa = ((wr * 64 + r32) >> 1) & 7, sb0 = ((brow0 + r32) >> 1) & 7, sb1 = ((brow1 + r32) >> 1) & 7, sh = (r32 >> 1) & 7;
;   const int oa = (wr * 64 + r32) * 128, ob0 = ABYTES + (brow0 + r32) * 128, ob1 = ABYTES + (brow1 + r32) * 128, oh = (128 + r32) * 128;
;   __syncthreads();
;   ISSUE(0, 0);
;   const int nk = K >> 6;
;   for (int kt = 0; kt < nk; ++kt) {
;     asm volatile("s_waitcnt vmcnt(0)" ::: "memory");
;     __syncthreads();
;     if (kt + 1 < nk) ISSUE((kt + 1) * 64, (kt + 1) & 1);
;     const char* T = lds + (kt & 1) * BUF;
; #pragma unroll
;     for (int kk = 0; kk < 4; ++kk) {
;       const int c = kk * 2 + hi;
;       bf16x8 a0 = *(const bf16x8*)(T + oa + ((c ^ sa) << 4));
;       bf16x8 a1 = *(const bf16x8*)(T + oa + 4096 + ((c ^ sa) << 4));
;       bf16x8 b0 = *(const bf16x8*)(T + ob0 + ((c ^ sb0) << 4));
;       bf16x8 b1 = *(const bf16x8*)(T + ob1 + ((c ^ sb1) << 4));
;       acc[0][0] = MFMA(a0, b0, acc[0][0]); acc[0][1] = MFMA(a0, b1, acc[0][1]);
;       acc[1][0] = MFMA(a1, b0, acc[1][0]); acc[1][1] = MFMA(a1, b1, acc[1][1]);
;       if (HALO) { bf16x8 ah = *(const bf16x8*)(T + oh + ((c ^ sh) << 4)); hacc = MFMA(ah, b0, hacc); }
;     }
;   }
; __device__ __forceinline__ void phase_ffn_down(const P& p, int layer, char* lds) {
;     ...
;   for (int it = 0; tile_at(it, 256, 8, tm, tn); ++it) {
;     f32x16 acc[2][2] = {};
;     { LdBf al{xb + (long)tm * 128 * DM, DM}, bl{wg + (long)tn * 128 * DM, DM}; gemm_plain(acc, al, bl, DM, lds); }
.LBB0_155:
	v_readlane_b32 vcc_lo, v253, 21
	s_or_b32 s3, s80, vcc_lo
	s_lshr_b32 s6, s3, 3
	s_and_b32 s6, s6, 0xf8
	s_lshl_b32 s7, s6, 3
	s_and_b32 s81, s80, 7
	s_sub_i32 s3, s3, s7
	s_or_b32 s85, s6, s81
	s_ashr_i32 s62, s3, 3
	s_lshl_b32 s3, s85, 18
	s_add_u32 s18, s40, s3
	v_mov_b32_e32 v1, v229
	s_waitcnt vmcnt(6)
	v_mov_b32_e32 v6, v229
	s_addc_u32 s19, s41, 0
	s_ashr_i32 s63, s62, 31
	s_lshl_b64 s[6:7], s[62:63], 18
	v_and_b32_e32 v7, 31, v6
	v_ashrrev_i32_e32 v0, 3, v6
	v_lshrrev_b32_e32 v2, 4, v6
	v_readlane_b32 s3, v255, 19
	v_xor_b32_e32 v4, v2, v6
	s_waitcnt vmcnt(5)
	v_and_or_b32 v10, v1, 64, v7
	v_ashrrev_i32_e32 v1, 31, v0
	s_add_u32 s64, s3, s6
	v_readlane_b32 s3, v255, 20
	v_lshlrev_b64 v[0:1], 11, v[0:1]
	v_lshlrev_b32_e32 v4, 4, v4
	s_addc_u32 s65, s3, s7
	v_lshl_add_u32 v96, v6, 4, 0
	v_lshl_add_u64 v[2:3], s[18:19], 0, v[0:1]
	v_and_b32_e32 v200, 0x70, v4
	v_add_u32_e32 v101, 0x4000, v96
	s_waitcnt vmcnt(0)
	v_lshl_add_u64 v[66:67], v[2:3], 0, v[200:201]
	v_readfirstlane_b32 s83, v96
	v_lshl_add_u64 v[2:3], s[64:65], 0, v[0:1]
	s_mov_b64 s[6:7], 0x10000
	s_mov_b32 m0, s83
	v_lshl_add_u64 v[64:65], v[2:3], 0, v[200:201]
	v_readfirstlane_b32 s42, v101
	v_lshl_add_u64 v[2:3], v[0:1], 0, s[6:7]
	v_add_u32_e32 v102, 0x1000, v96
	s_barrier
	global_load_lds_dwordx4 v[66:67], off
	s_mov_b32 m0, s42
	v_lshl_add_u64 v[4:5], s[18:19], 0, v[2:3]
	v_readfirstlane_b32 s43, v102
	v_lshl_add_u64 v[2:3], s[64:65], 0, v[2:3]
	v_add_u32_e32 v103, 0x5000, v96
	s_mov_b64 s[6:7], 0x20000
	global_load_lds_dwordx4 v[64:65], off
	v_lshl_add_u64 v[70:71], v[4:5], 0, v[200:201]
	s_mov_b32 m0, s43
	v_lshl_add_u64 v[68:69], v[2:3], 0, v[200:201]
	v_readfirstlane_b32 s70, v103
	v_lshl_add_u64 v[2:3], v[0:1], 0, s[6:7]
	v_add_u32_e32 v88, 0x2000, v96
	s_mov_b64 s[72:73], 0x30000
	global_load_lds_dwordx4 v[70:71], off
	s_mov_b32 m0, s70
	v_lshl_add_u64 v[4:5], s[18:19], 0, v[2:3]
	v_readfirstlane_b32 s3, v88
	v_lshl_add_u64 v[2:3], s[64:65], 0, v[2:3]
	v_add_u32_e32 v89, 0x6000, v96
	v_lshl_add_u64 v[0:1], v[0:1], 0, s[72:73]
	v_lshrrev_b32_e32 v8, 5, v6
	v_bfe_u32 v11, v6, 1, 3
	global_load_lds_dwordx4 v[68:69], off
	v_lshl_add_u64 v[74:75], v[4:5], 0, v[200:201]
	s_mov_b32 m0, s3
	v_lshl_add_u64 v[72:73], v[2:3], 0, v[200:201]
	v_readfirstlane_b32 s6, v89
	v_lshl_add_u64 v[2:3], s[18:19], 0, v[0:1]
	v_add_u32_e32 v90, 0x3000, v96
	v_lshl_add_u64 v[0:1], s[64:65], 0, v[0:1]
	global_load_lds_dwordx4 v[74:75], off
	s_mov_b32 m0, s6
	v_readfirstlane_b32 s7, v90
	v_lshl_add_u64 v[76:77], v[0:1], 0, v[200:201]
	v_add_u32_e32 v91, 0x7000, v96
	v_bfe_u32 v0, v6, 5, 1
	v_bitop3_b32 v1, v8, v11, 1 bitop3:0x6c
	global_load_lds_dwordx4 v[72:73], off
	v_lshl_add_u64 v[78:79], v[2:3], 0, v[200:201]
	s_mov_b32 m0, s7
	v_readfirstlane_b32 s8, v91
	v_lshlrev_b32_e32 v8, 4, v1
	v_bitop3_b32 v1, v0, v11, 2 bitop3:0x36
	v_add_u32_e32 v93, 0x8000, v96
	global_load_lds_dwordx4 v[78:79], off
	s_mov_b32 m0, s8
	v_lshlrev_b32_e32 v81, 4, v1
	v_bitop3_b32 v1, v0, v11, 4 bitop3:0x36
	v_bitop3_b32 v0, v0, v11, 6 bitop3:0x36
	v_add_u32_e32 v92, 0xc000, v96
	v_readfirstlane_b32 s18, v93
	global_load_lds_dwordx4 v[76:77], off
	v_lshlrev_b32_e32 v84, 4, v1
	v_lshlrev_b32_e32 v120, 4, v0
	v_lshl_add_u64 v[0:1], v[66:67], 0, s[78:79]
	s_mov_b32 m0, s18
	v_readfirstlane_b32 s19, v92
	v_add_u32_e32 v94, 0x9000, v96
	s_waitcnt vmcnt(0)
	s_waitcnt vmcnt(0) lgkmcnt(0)
	s_barrier
	global_load_lds_dwordx4 v[0:1], off
	v_lshl_add_u64 v[0:1], v[64:65], 0, s[78:79]
	s_mov_b32 m0, s19
	v_readfirstlane_b32 s33, v94
	v_add_u32_e32 v95, 0xd000, v96
	global_load_lds_dwordx4 v[0:1], off
	v_lshl_add_u64 v[0:1], v[70:71], 0, s[78:79]
	s_mov_b32 m0, s33
	v_readfirstlane_b32 s72, v95
	v_add_u32_e32 v97, 0xa000, v96
	global_load_lds_dwordx4 v[0:1], off
	v_lshl_add_u64 v[0:1], v[68:69], 0, s[78:79]
	s_mov_b32 m0, s72
	v_readfirstlane_b32 s73, v97
	v_add_u32_e32 v98, 0xe000, v96
	global_load_lds_dwordx4 v[0:1], off
	v_lshl_add_u64 v[0:1], v[74:75], 0, s[78:79]
	s_mov_b32 m0, s73
	v_readfirstlane_b32 s92, v98
	v_add_u32_e32 v99, 0xb000, v96
	v_lshrrev_b32_e32 v9, 1, v6
	s_mov_b32 s52, 0x1ffffc0
	global_load_lds_dwordx4 v[0:1], off
	v_lshl_add_u64 v[0:1], v[72:73], 0, s[78:79]
	s_mov_b32 m0, s92
	v_readfirstlane_b32 s69, v99
	v_add_u32_e32 v100, 0xf000, v96
	v_and_or_b32 v2, v9, s52, v7
	global_load_lds_dwordx4 v[0:1], off
	v_lshl_add_u64 v[0:1], v[78:79], 0, s[78:79]
	s_mov_b32 m0, s69
	v_readfirstlane_b32 s82, v100
	global_load_lds_dwordx4 v[0:1], off
	v_lshl_add_u64 v[0:1], v[76:77], 0, s[78:79]
	s_mov_b32 m0, s82
	v_lshl_add_u32 v87, v2, 7, 0
	v_lshl_add_u32 v121, v10, 7, 0
	global_load_lds_dwordx4 v[0:1], off
	v_add_u32_e32 v80, v87, v8
	v_add_u32_e32 v82, v121, v8
	ds_read_b128 v[0:3], v80
	ds_read_b128 v[4:7], v80 offset:4096
	ds_read_b128 v[8:11], v82 offset:16384
	ds_read_b128 v[12:15], v82 offset:20480
	s_waitcnt lgkmcnt(0)
	v_mfma_f32_32x32x16_bf16 v[48:63], v[0:3], v[8:11], 0
	v_add_u32_e32 v85, v87, v81
	v_add_u32_e32 v83, v121, v81
	ds_read_b128 v[104:107], v85
	ds_read_b128 v[108:111], v85 offset:4096
	ds_read_b128 v[112:115], v83 offset:16384
	ds_read_b128 v[116:119], v83 offset:20480
	v_add_u32_e32 v86, v87, v84
	v_add_u32_e32 v84, v121, v84
	v_add_u32_e32 v87, v87, v120
	v_mfma_f32_32x32x16_bf16 v[32:47], v[0:3], v[12:15], 0
	v_add_u32_e32 v81, v121, v120
	s_mov_b32 m0, s83
	v_readfirstlane_b32 s64, v88
	v_readfirstlane_b32 s65, v89
	v_lshl_add_u64 v[88:89], v[78:79], 0, s[88:89]
	s_mul_i32 s81, s81, 0xb0000
	s_mov_b32 s94, 0x1ffffc0
	v_mfma_f32_32x32x16_bf16 v[16:31], v[4:7], v[8:11], 0
	v_mfma_f32_32x32x16_bf16 v[0:15], v[4:7], v[12:15], 0
	s_waitcnt lgkmcnt(0)
	v_mfma_f32_32x32x16_bf16 v[48:63], v[104:107], v[112:115], v[48:63]
	v_mfma_f32_32x32x16_bf16 v[32:47], v[104:107], v[116:119], v[32:47]
	v_mfma_f32_32x32x16_bf16 v[16:31], v[108:111], v[112:115], v[16:31]
	v_mfma_f32_32x32x16_bf16 v[0:15], v[108:111], v[116:119], v[0:15]
	ds_read_b128 v[104:107], v86
	ds_read_b128 v[108:111], v86 offset:4096
	ds_read_b128 v[112:115], v84 offset:16384
	ds_read_b128 v[116:119], v84 offset:20480
	s_waitcnt lgkmcnt(0)
	v_mfma_f32_32x32x16_bf16 v[48:63], v[104:107], v[112:115], v[48:63]
	v_mfma_f32_32x32x16_bf16 v[32:47], v[104:107], v[116:119], v[32:47]
	v_mfma_f32_32x32x16_bf16 v[16:31], v[108:111], v[112:115], v[16:31]
	v_mfma_f32_32x32x16_bf16 v[0:15], v[108:111], v[116:119], v[0:15]
	ds_read_b128 v[104:107], v87
	ds_read_b128 v[108:111], v87 offset:4096
	ds_read_b128 v[112:115], v81 offset:16384
	ds_read_b128 v[116:119], v81 offset:20480
	s_waitcnt vmcnt(0)
	s_waitcnt vmcnt(0) lgkmcnt(0)
	s_barrier
; #define MFMA(a, b, c) __builtin_amdgcn_mfma_f32_32x32x16_bf16(a, b, c, 0, 0, 0)
; #define ISSUE(k0, bf) do { char* A_ = lw + (bf) * BUF; \
;     _Pragma("unroll") for (int i_ = 0; i_ < 4; ++i_) { glds16(al.ptr(lrow + 32 * i_, (k0) + cg), A_ + i_ * 4096); glds16(bl.ptr(lrow + 32 * i_, (k0) + cg), A_ + ABYTES + i_ * 4096); } \
;     if (HALO) { if (wid == 0) glds16(gh + (k0), A_ + 16384); } } while (0)
; template <bool HALO, class AL, class BL>
; __device__ __forceinline__ void gemm_core(f32x16 (&acc)[2][2], f32x16& hacc, const AL& al, const BL& bl, int K, char* lds,
;                                           const u16* halo0, const u16* halo1, int brow0, int brow1) {
;     ...
;   for (int kt = 0; kt < nk; ++kt) {
;     asm volatile("s_waitcnt vmcnt(0)" ::: "memory");
;     __syncthreads();
;     if (kt + 1 < nk) ISSUE((kt + 1) * 64, (kt + 1) & 1);
;     const char* T = lds + (kt & 1) * BUF;
; #pragma unroll
;     for (int kk = 0; kk < 4; ++kk) {
;       const int c = kk * 2 + hi;
;       bf16x8 a0 = *(const bf16x8*)(T + oa + ((c ^ sa) << 4));
;       bf16x8 a1 = *(const bf16x8*)(T + oa + 4096 + ((c ^ sa) << 4));
;       bf16x8 b0 = *(const bf16x8*)(T + ob0 + ((c ^ sb0) << 4));
;       bf16x8 b1 = *(const bf16x8*)(T + ob1 + ((c ^ sb1) << 4));
;       acc[0][0] = MFMA(a0, b0, acc[0][0]); acc[0][1] = MFMA(a0, b1, acc[0][1]);
;       acc[1][0] = MFMA(a1, b0, acc[1][0]); acc[1][1] = MFMA(a1, b1, acc[1][1]);
;       if (HALO) { bf16x8 ah = *(const bf16x8*)(T + oh + ((c ^ sh) << 4)); hacc = MFMA(ah, b0, hacc); }
;     }
	v_mfma_f32_32x32x16_bf16 v[48:63], v[104:107], v[112:115], v[48:63]
	v_mfma_f32_32x32x16_bf16 v[32:47], v[104:107], v[116:119], v[32:47]
	v_lshl_add_u64 v[104:105], v[66:67], 0, s[24:25]
	global_load_lds_dwordx4 v[104:105], off
	v_lshl_add_u64 v[104:105], v[64:65], 0, s[24:25]
	s_mov_b32 m0, s42
	s_nop 0
	global_load_lds_dwordx4 v[104:105], off
	v_lshl_add_u64 v[104:105], v[70:71], 0, s[24:25]
	s_mov_b32 m0, s43
	v_mfma_f32_32x32x16_bf16 v[16:31], v[108:111], v[112:115], v[16:31]
	global_load_lds_dwordx4 v[104:105], off
	v_lshl_add_u64 v[104:105], v[68:69], 0, s[24:25]
	s_mov_b32 m0, s70
	s_nop 0
	global_load_lds_dwordx4 v[104:105], off
	v_lshl_add_u64 v[104:105], v[74:75], 0, s[24:25]
	s_mov_b32 m0, s3
	v_mfma_f32_32x32x16_bf16 v[0:15], v[108:111], v[116:119], v[0:15]
	global_load_lds_dwordx4 v[104:105], off
	v_lshl_add_u64 v[104:105], v[72:73], 0, s[24:25]
	s_mov_b32 m0, s6
	s_nop 0
	global_load_lds_dwordx4 v[104:105], off
	v_lshl_add_u64 v[104:105], v[78:79], 0, s[24:25]
	s_mov_b32 m0, s7
	s_nop 0
	global_load_lds_dwordx4 v[104:105], off
	v_lshl_add_u64 v[104:105], v[76:77], 0, s[24:25]
	s_mov_b32 m0, s8
	s_nop 0
	global_load_lds_dwordx4 v[104:105], off
	ds_read_b128 v[104:107], v80 offset:32768
	ds_read_b128 v[108:111], v80 offset:36864
	ds_read_b128 v[112:115], v82 offset:49152
	ds_read_b128 v[116:119], v82 offset:53248
	s_waitcnt lgkmcnt(0)
	v_mfma_f32_32x32x16_bf16 v[48:63], v[104:107], v[112:115], v[48:63]
	s_mov_b32 m0, s18
	v_mfma_f32_32x32x16_bf16 v[32:47], v[104:107], v[116:119], v[32:47]
	v_mfma_f32_32x32x16_bf16 v[16:31], v[108:111], v[112:115], v[16:31]
	v_mfma_f32_32x32x16_bf16 v[0:15], v[108:111], v[116:119], v[0:15]
	ds_read_b128 v[104:107], v85 offset:32768
	ds_read_b128 v[108:111], v85 offset:36864
	ds_read_b128 v[112:115], v83 offset:49152
	ds_read_b128 v[116:119], v83 offset:53248
	s_waitcnt lgkmcnt(0)
	v_mfma_f32_32x32x16_bf16 v[48:63], v[104:107], v[112:115], v[48:63]
	v_mfma_f32_32x32x16_bf16 v[32:47], v[104:107], v[116:119], v[32:47]
	v_mfma_f32_32x32x16_bf16 v[16:31], v[108:111], v[112:115], v[16:31]
	v_mfma_f32_32x32x16_bf16 v[0:15], v[108:111], v[116:119], v[0:15]
	ds_read_b128 v[104:107], v86 offset:32768
	ds_read_b128 v[108:111], v86 offset:36864
	ds_read_b128 v[112:115], v84 offset:49152
	ds_read_b128 v[116:119], v84 offset:53248
	s_waitcnt lgkmcnt(0)
	v_mfma_f32_32x32x16_bf16 v[48:63], v[104:107], v[112:115], v[48:63]
	v_mfma_f32_32x32x16_bf16 v[32:47], v[104:107], v[116:119], v[32:47]
	v_mfma_f32_32x32x16_bf16 v[16:31], v[108:111], v[112:115], v[16:31]
	v_mfma_f32_32x32x16_bf16 v[0:15], v[108:111], v[116:119], v[0:15]
	ds_read_b128 v[104:107], v87 offset:32768
	ds_read_b128 v[108:111], v87 offset:36864
	ds_read_b128 v[112:115], v81 offset:49152
	ds_read_b128 v[116:119], v81 offset:53248
	s_waitcnt vmcnt(0)
	s_waitcnt vmcnt(0) lgkmcnt(0)
	s_barrier
	v_mfma_f32_32x32x16_bf16 v[48:63], v[104:107], v[112:115], v[48:63]
	v_mfma_f32_32x32x16_bf16 v[32:47], v[104:107], v[116:119], v[32:47]
	v_lshl_add_u64 v[104:105], v[66:67], 0, s[74:75]
	global_load_lds_dwordx4 v[104:105], off
	v_lshl_add_u64 v[104:105], v[64:65], 0, s[74:75]
	s_mov_b32 m0, s19
	s_nop 0
	global_load_lds_dwordx4 v[104:105], off
	v_lshl_add_u64 v[104:105], v[70:71], 0, s[74:75]
	s_mov_b32 m0, s33
	v_mfma_f32_32x32x16_bf16 v[16:31], v[108:111], v[112:115], v[16:31]
	global_load_lds_dwordx4 v[104:105], off
	v_lshl_add_u64 v[104:105], v[68:69], 0, s[74:75]
	s_mov_b32 m0, s72
	s_nop 0
	global_load_lds_dwordx4 v[104:105], off
	v_lshl_add_u64 v[104:105], v[74:75], 0, s[74:75]
	s_mov_b32 m0, s73
	v_mfma_f32_32x32x16_bf16 v[0:15], v[108:111], v[116:119], v[0:15]
	global_load_lds_dwordx4 v[104:105], off
	v_lshl_add_u64 v[104:105], v[72:73], 0, s[74:75]
	s_mov_b32 m0, s92
	s_nop 0
	global_load_lds_dwordx4 v[104:105], off
	v_lshl_add_u64 v[104:105], v[78:79], 0, s[74:75]
	s_mov_b32 m0, s69
	s_nop 0
	global_load_lds_dwordx4 v[104:105], off
	v_lshl_add_u64 v[104:105], v[76:77], 0, s[74:75]
	s_mov_b32 m0, s82
	s_nop 0
	global_load_lds_dwordx4 v[104:105], off
	ds_read_b128 v[104:107], v80
	ds_read_b128 v[108:111], v80 offset:4096
	ds_read_b128 v[112:115], v82 offset:16384
	ds_read_b128 v[116:119], v82 offset:20480
	s_waitcnt lgkmcnt(0)
	v_mfma_f32_32x32x16_bf16 v[48:63], v[104:107], v[112:115], v[48:63]
	s_mov_b32 m0, s83
	v_mfma_f32_32x32x16_bf16 v[32:47], v[104:107], v[116:119], v[32:47]
	v_mfma_f32_32x32x16_bf16 v[16:31], v[108:111], v[112:115], v[16:31]
	v_mfma_f32_32x32x16_bf16 v[0:15], v[108:111], v[116:119], v[0:15]
	ds_read_b128 v[104:107], v85
	ds_read_b128 v[108:111], v85 offset:4096
	ds_read_b128 v[112:115], v83 offset:16384
	ds_read_b128 v[116:119], v83 offset:20480
	s_waitcnt lgkmcnt(0)
	v_mfma_f32_32x32x16_bf16 v[48:63], v[104:107], v[112:115], v[48:63]
	v_mfma_f32_32x32x16_bf16 v[32:47], v[104:107], v[116:119], v[32:47]
	v_mfma_f32_32x32x16_bf16 v[16:31], v[108:111], v[112:115], v[16:31]
	v_mfma_f32_32x32x16_bf16 v[0:15], v[108:111], v[116:119], v[0:15]
	ds_read_b128 v[104:107], v86
	ds_read_b128 v[108:111], v86 offset:4096
	ds_read_b128 v[112:115], v84 offset:16384
	ds_read_b128 v[116:119], v84 offset:20480
	s_waitcnt lgkmcnt(0)
	v_mfma_f32_32x32x16_bf16 v[48:63], v[104:107], v[112:115], v[48:63]
	v_mfma_f32_32x32x16_bf16 v[32:47], v[104:107], v[116:119], v[32:47]
	v_mfma_f32_32x32x16_bf16 v[16:31], v[108:111], v[112:115], v[16:31]
	v_mfma_f32_32x32x16_bf16 v[0:15], v[108:111], v[116:119], v[0:15]
	ds_read_b128 v[104:107], v87
	ds_read_b128 v[108:111], v87 offset:4096
	ds_read_b128 v[112:115], v81 offset:16384
	ds_read_b128 v[116:119], v81 offset:20480
	s_waitcnt vmcnt(0)
	s_waitcnt vmcnt(0) lgkmcnt(0)
	s_barrier
; #define MFMA(a, b, c) __builtin_amdgcn_mfma_f32_32x32x16_bf16(a, b, c, 0, 0, 0)
; #define ISSUE(k0, bf) do { char* A_ = lw + (bf) * BUF; \
;     _Pragma("unroll") for (int i_ = 0; i_ < 4; ++i_) { glds16(al.ptr(lrow + 32 * i_, (k0) + cg), A_ + i_ * 4096); glds16(bl.ptr(lrow + 32 * i_, (k0) + cg), A_ + ABYTES + i_ * 4096); } \
;     if (HALO) { if (wid == 0) glds16(gh + (k0), A_ + 16384); } } while (0)
; template <bool HALO, class AL, class BL>
; __device__ __forceinline__ void gemm_core(f32x16 (&acc)[2][2], f32x16& hacc, const AL& al, const BL& bl, int K, char* lds,
;                                           const u16* halo0, const u16* halo1, int brow0, int brow1) {
;     ...
;   for (int kt = 0; kt < nk; ++kt) {
;     asm volatile("s_waitcnt vmcnt(0)" ::: "memory");
;     __syncthreads();
;     if (kt + 1 < nk) ISSUE((kt + 1) * 64, (kt + 1) & 1);
;     const char* T = lds + (kt & 1) * BUF;
; #pragma unroll
;     for (int kk = 0; kk < 4; ++kk) {
;       const int c = kk * 2 + hi;
;       bf16x8 a0 = *(const bf16x8*)(T + oa + ((c ^ sa) << 4));
;       bf16x8 a1 = *(const bf16x8*)(T + oa + 4096 + ((c ^ sa) << 4));
;       bf16x8 b0 = *(const bf16x8*)(T + ob0 + ((c ^ sb0) << 4));
;       bf16x8 b1 = *(const bf16x8*)(T + ob1 + ((c ^ sb1) << 4));
;       acc[0][0] = MFMA(a0, b0, acc[0][0]); acc[0][1] = MFMA(a0, b1, acc[0][1]);
;       acc[1][0] = MFMA(a1, b0, acc[1][0]); acc[1][1] = MFMA(a1, b1, acc[1][1]);
;       if (HALO) { bf16x8 ah = *(const bf16x8*)(T + oh + ((c ^ sh) << 4)); hacc = MFMA(ah, b0, hacc); }
;     }
	v_mfma_f32_32x32x16_bf16 v[48:63], v[104:107], v[112:115], v[48:63]
	v_mfma_f32_32x32x16_bf16 v[32:47], v[104:107], v[116:119], v[32:47]
	v_lshl_add_u64 v[104:105], v[66:67], 0, s[20:21]
	global_load_lds_dwordx4 v[104:105], off
	v_lshl_add_u64 v[104:105], v[64:65], 0, s[20:21]
	s_mov_b32 m0, s42
	s_nop 0
	global_load_lds_dwordx4 v[104:105], off
	v_lshl_add_u64 v[104:105], v[70:71], 0, s[20:21]
	s_mov_b32 m0, s43
	v_mfma_f32_32x32x16_bf16 v[16:31], v[108:111], v[112:115], v[16:31]
	global_load_lds_dwordx4 v[104:105], off
	v_lshl_add_u64 v[104:105], v[68:69], 0, s[20:21]
	s_mov_b32 m0, s70
	s_nop 0
	global_load_lds_dwordx4 v[104:105], off
	v_lshl_add_u64 v[104:105], v[74:75], 0, s[20:21]
	s_mov_b32 m0, s3
	v_mfma_f32_32x32x16_bf16 v[0:15], v[108:111], v[116:119], v[0:15]
	global_load_lds_dwordx4 v[104:105], off
	v_lshl_add_u64 v[104:105], v[72:73], 0, s[20:21]
	s_mov_b32 m0, s6
	s_nop 0
	global_load_lds_dwordx4 v[104:105], off
	v_lshl_add_u64 v[104:105], v[78:79], 0, s[20:21]
	s_mov_b32 m0, s7
	s_nop 0
	global_load_lds_dwordx4 v[104:105], off
	v_lshl_add_u64 v[104:105], v[76:77], 0, s[20:21]
	s_mov_b32 m0, s8
	s_nop 0
	global_load_lds_dwordx4 v[104:105], off
	ds_read_b128 v[104:107], v80 offset:32768
	ds_read_b128 v[108:111], v80 offset:36864
	ds_read_b128 v[112:115], v82 offset:49152
	ds_read_b128 v[116:119], v82 offset:53248
	s_waitcnt lgkmcnt(0)
	v_mfma_f32_32x32x16_bf16 v[48:63], v[104:107], v[112:115], v[48:63]
	s_mov_b32 m0, s18
	v_mfma_f32_32x32x16_bf16 v[32:47], v[104:107], v[116:119], v[32:47]
	v_mfma_f32_32x32x16_bf16 v[16:31], v[108:111], v[112:115], v[16:31]
	v_mfma_f32_32x32x16_bf16 v[0:15], v[108:111], v[116:119], v[0:15]
	ds_read_b128 v[104:107], v85 offset:32768
	ds_read_b128 v[108:111], v85 offset:36864
	ds_read_b128 v[112:115], v83 offset:49152
	ds_read_b128 v[116:119], v83 offset:53248
	s_waitcnt lgkmcnt(0)
	v_mfma_f32_32x32x16_bf16 v[48:63], v[104:107], v[112:115], v[48:63]
	v_mfma_f32_32x32x16_bf16 v[32:47], v[104:107], v[116:119], v[32:47]
	v_mfma_f32_32x32x16_bf16 v[16:31], v[108:111], v[112:115], v[16:31]
	v_mfma_f32_32x32x16_bf16 v[0:15], v[108:111], v[116:119], v[0:15]
	ds_read_b128 v[104:107], v86 offset:32768
	ds_read_b128 v[108:111], v86 offset:36864
	ds_read_b128 v[112:115], v84 offset:49152
	ds_read_b128 v[116:119], v84 offset:53248
	s_waitcnt lgkmcnt(0)
	v_mfma_f32_32x32x16_bf16 v[48:63], v[104:107], v[112:115], v[48:63]
	v_mfma_f32_32x32x16_bf16 v[32:47], v[104:107], v[116:119], v[32:47]
	v_mfma_f32_32x32x16_bf16 v[16:31], v[108:111], v[112:115], v[16:31]
	v_mfma_f32_32x32x16_bf16 v[0:15], v[108:111], v[116:119], v[0:15]
	ds_read_b128 v[104:107], v87 offset:32768
	ds_read_b128 v[108:111], v87 offset:36864
	ds_read_b128 v[112:115], v81 offset:49152
	ds_read_b128 v[116:119], v81 offset:53248
	s_waitcnt vmcnt(0)
	s_waitcnt vmcnt(0) lgkmcnt(0)
	s_barrier
	v_mfma_f32_32x32x16_bf16 v[48:63], v[104:107], v[112:115], v[48:63]
	v_mfma_f32_32x32x16_bf16 v[32:47], v[104:107], v[116:119], v[32:47]
	v_lshl_add_u64 v[104:105], v[66:67], 0, s[86:87]
	global_load_lds_dwordx4 v[104:105], off
	v_lshl_add_u64 v[104:105], v[64:65], 0, s[86:87]
	s_mov_b32 m0, s19
	s_nop 0
	global_load_lds_dwordx4 v[104:105], off
	v_lshl_add_u64 v[104:105], v[70:71], 0, s[86:87]
	s_mov_b32 m0, s33
	v_mfma_f32_32x32x16_bf16 v[16:31], v[108:111], v[112:115], v[16:31]
	global_load_lds_dwordx4 v[104:105], off
	v_lshl_add_u64 v[104:105], v[68:69], 0, s[86:87]
	s_mov_b32 m0, s72
	s_nop 0
	global_load_lds_dwordx4 v[104:105], off
	v_lshl_add_u64 v[104:105], v[74:75], 0, s[86:87]
	s_mov_b32 m0, s73
	v_mfma_f32_32x32x16_bf16 v[0:15], v[108:111], v[116:119], v[0:15]
	global_load_lds_dwordx4 v[104:105], off
	v_lshl_add_u64 v[104:105], v[72:73], 0, s[86:87]
	s_mov_b32 m0, s92
	s_nop 0
	global_load_lds_dwordx4 v[104:105], off
	v_lshl_add_u64 v[104:105], v[78:79], 0, s[86:87]
	s_mov_b32 m0, s69
	s_nop 0
	global_load_lds_dwordx4 v[104:105], off
	v_lshl_add_u64 v[104:105], v[76:77], 0, s[86:87]
	s_mov_b32 m0, s82
	s_nop 0
	global_load_lds_dwordx4 v[104:105], off
	ds_read_b128 v[104:107], v80
	ds_read_b128 v[108:111], v80 offset:4096
	ds_read_b128 v[112:115], v82 offset:16384
	ds_read_b128 v[116:119], v82 offset:20480
	s_waitcnt lgkmcnt(0)
	v_mfma_f32_32x32x16_bf16 v[48:63], v[104:107], v[112:115], v[48:63]
	s_mov_b32 m0, s83
	v_mfma_f32_32x32x16_bf16 v[32:47], v[104:107], v[116:119], v[32:47]
	v_mfma_f32_32x32x16_bf16 v[16:31], v[108:111], v[112:115], v[16:31]
	v_mfma_f32_32x32x16_bf16 v[0:15], v[108:111], v[116:119], v[0:15]
	ds_read_b128 v[104:107], v85
	ds_read_b128 v[108:111], v85 offset:4096
	ds_read_b128 v[112:115], v83 offset:16384
	ds_read_b128 v[116:119], v83 offset:20480
	s_waitcnt lgkmcnt(0)
	v_mfma_f32_32x32x16_bf16 v[48:63], v[104:107], v[112:115], v[48:63]
	v_mfma_f32_32x32x16_bf16 v[32:47], v[104:107], v[116:119], v[32:47]
	v_mfma_f32_32x32x16_bf16 v[16:31], v[108:111], v[112:115], v[16:31]
	v_mfma_f32_32x32x16_bf16 v[0:15], v[108:111], v[116:119], v[0:15]
	ds_read_b128 v[104:107], v86
	ds_read_b128 v[108:111], v86 offset:4096
	ds_read_b128 v[112:115], v84 offset:16384
	ds_read_b128 v[116:119], v84 offset:20480
	s_waitcnt lgkmcnt(0)
	v_mfma_f32_32x32x16_bf16 v[48:63], v[104:107], v[112:115], v[48:63]
	v_mfma_f32_32x32x16_bf16 v[32:47], v[104:107], v[116:119], v[32:47]
	v_mfma_f32_32x32x16_bf16 v[16:31], v[108:111], v[112:115], v[16:31]
	v_mfma_f32_32x32x16_bf16 v[0:15], v[108:111], v[116:119], v[0:15]
	ds_read_b128 v[104:107], v87
	ds_read_b128 v[108:111], v87 offset:4096
	ds_read_b128 v[112:115], v81 offset:16384
	ds_read_b128 v[116:119], v81 offset:20480
	s_waitcnt vmcnt(0)
	s_waitcnt vmcnt(0) lgkmcnt(0)
	s_barrier
; #define MFMA(a, b, c) __builtin_amdgcn_mfma_f32_32x32x16_bf16(a, b, c, 0, 0, 0)
; #define ISSUE(k0, bf) do { char* A_ = lw + (bf) * BUF; \
;     _Pragma("unroll") for (int i_ = 0; i_ < 4; ++i_) { glds16(al.ptr(lrow + 32 * i_, (k0) + cg), A_ + i_ * 4096); glds16(bl.ptr(lrow + 32 * i_, (k0) + cg), A_ + ABYTES + i_ * 4096); } \
;     if (HALO) { if (wid == 0) glds16(gh + (k0), A_ + 16384); } } while (0)
; template <bool HALO, class AL, class BL>
; __device__ __forceinline__ void gemm_core(f32x16 (&acc)[2][2], f32x16& hacc, const AL& al, const BL& bl, int K, char* lds,
;                                           const u16* halo0, const u16* halo1, int brow0, int brow1) {
;     ...
;   for (int kt = 0; kt < nk; ++kt) {
;     asm volatile("s_waitcnt vmcnt(0)" ::: "memory");
;     __syncthreads();
;     if (kt + 1 < nk) ISSUE((kt + 1) * 64, (kt + 1) & 1);
;     const char* T = lds + (kt & 1) * BUF;
; #pragma unroll
;     for (int kk = 0; kk < 4; ++kk) {
;       const int c = kk * 2 + hi;
;       bf16x8 a0 = *(const bf16x8*)(T + oa + ((c ^ sa) << 4));
;       bf16x8 a1 = *(const bf16x8*)(T + oa + 4096 + ((c ^ sa) << 4));
;       bf16x8 b0 = *(const bf16x8*)(T + ob0 + ((c ^ sb0) << 4));
;       bf16x8 b1 = *(const bf16x8*)(T + ob1 + ((c ^ sb1) << 4));
;       acc[0][0] = MFMA(a0, b0, acc[0][0]); acc[0][1] = MFMA(a0, b1, acc[0][1]);
;       acc[1][0] = MFMA(a1, b0, acc[1][0]); acc[1][1] = MFMA(a1, b1, acc[1][1]);
;       if (HALO) { bf16x8 ah = *(const bf16x8*)(T + oh + ((c ^ sh) << 4)); hacc = MFMA(ah, b0, hacc); }
;     }
	v_mfma_f32_32x32x16_bf16 v[48:63], v[104:107], v[112:115], v[48:63]
	v_mfma_f32_32x32x16_bf16 v[32:47], v[104:107], v[116:119], v[32:47]
	v_lshl_add_u64 v[104:105], v[66:67], 0, s[30:31]
	global_load_lds_dwordx4 v[104:105], off
	v_lshl_add_u64 v[104:105], v[64:65], 0, s[30:31]
	s_mov_b32 m0, s42
	v_readfirstlane_b32 s42, v90
	global_load_lds_dwordx4 v[104:105], off
	v_lshl_add_u64 v[104:105], v[70:71], 0, s[30:31]
	s_mov_b32 m0, s43
	v_mfma_f32_32x32x16_bf16 v[16:31], v[108:111], v[112:115], v[16:31]
	global_load_lds_dwordx4 v[104:105], off
	v_lshl_add_u64 v[104:105], v[68:69], 0, s[30:31]
	s_mov_b32 m0, s70
	v_readfirstlane_b32 s43, v91
	global_load_lds_dwordx4 v[104:105], off
	v_lshl_add_u64 v[104:105], v[74:75], 0, s[30:31]
	s_mov_b32 m0, s3
	v_mfma_f32_32x32x16_bf16 v[0:15], v[108:111], v[116:119], v[0:15]
	global_load_lds_dwordx4 v[104:105], off
	v_lshl_add_u64 v[104:105], v[72:73], 0, s[30:31]
	s_mov_b32 m0, s6
	s_nop 0
	global_load_lds_dwordx4 v[104:105], off
	v_lshl_add_u64 v[104:105], v[78:79], 0, s[30:31]
	s_mov_b32 m0, s7
	s_nop 0
	global_load_lds_dwordx4 v[104:105], off
	v_lshl_add_u64 v[104:105], v[76:77], 0, s[30:31]
	s_mov_b32 m0, s8
	s_nop 0
	global_load_lds_dwordx4 v[104:105], off
	ds_read_b128 v[104:107], v80 offset:32768
	ds_read_b128 v[108:111], v80 offset:36864
	ds_read_b128 v[112:115], v82 offset:49152
	ds_read_b128 v[116:119], v82 offset:53248
	s_waitcnt lgkmcnt(0)
	v_mfma_f32_32x32x16_bf16 v[48:63], v[104:107], v[112:115], v[48:63]
	s_mov_b32 m0, s18
	v_readfirstlane_b32 s18, v94
	v_mfma_f32_32x32x16_bf16 v[32:47], v[104:107], v[116:119], v[32:47]
	v_mfma_f32_32x32x16_bf16 v[16:31], v[108:111], v[112:115], v[16:31]
	v_mfma_f32_32x32x16_bf16 v[0:15], v[108:111], v[116:119], v[0:15]
	ds_read_b128 v[104:107], v85 offset:32768
	ds_read_b128 v[108:111], v85 offset:36864
	ds_read_b128 v[112:115], v83 offset:49152
	ds_read_b128 v[116:119], v83 offset:53248
	s_waitcnt lgkmcnt(0)
	v_mfma_f32_32x32x16_bf16 v[48:63], v[104:107], v[112:115], v[48:63]
	v_mfma_f32_32x32x16_bf16 v[32:47], v[104:107], v[116:119], v[32:47]
	v_mfma_f32_32x32x16_bf16 v[16:31], v[108:111], v[112:115], v[16:31]
	v_mfma_f32_32x32x16_bf16 v[0:15], v[108:111], v[116:119], v[0:15]
	ds_read_b128 v[104:107], v86 offset:32768
	ds_read_b128 v[108:111], v86 offset:36864
	ds_read_b128 v[112:115], v84 offset:49152
	ds_read_b128 v[116:119], v84 offset:53248
	s_waitcnt lgkmcnt(0)
	v_mfma_f32_32x32x16_bf16 v[48:63], v[104:107], v[112:115], v[48:63]
	v_mfma_f32_32x32x16_bf16 v[32:47], v[104:107], v[116:119], v[32:47]
	v_mfma_f32_32x32x16_bf16 v[16:31], v[108:111], v[112:115], v[16:31]
	v_mfma_f32_32x32x16_bf16 v[0:15], v[108:111], v[116:119], v[0:15]
	ds_read_b128 v[104:107], v87 offset:32768
	ds_read_b128 v[108:111], v87 offset:36864
	ds_read_b128 v[112:115], v81 offset:49152
	ds_read_b128 v[116:119], v81 offset:53248
	s_waitcnt vmcnt(0)
	s_waitcnt vmcnt(0) lgkmcnt(0)
	s_barrier
	v_mfma_f32_32x32x16_bf16 v[48:63], v[104:107], v[112:115], v[48:63]
	v_mfma_f32_32x32x16_bf16 v[32:47], v[104:107], v[116:119], v[32:47]
	v_lshl_add_u64 v[104:105], v[66:67], 0, s[4:5]
	global_load_lds_dwordx4 v[104:105], off
	v_lshl_add_u64 v[104:105], v[64:65], 0, s[4:5]
	s_mov_b32 m0, s19
	v_readfirstlane_b32 s19, v95
	global_load_lds_dwordx4 v[104:105], off
	v_lshl_add_u64 v[104:105], v[70:71], 0, s[4:5]
	s_mov_b32 m0, s33
	v_mfma_f32_32x32x16_bf16 v[16:31], v[108:111], v[112:115], v[16:31]
	global_load_lds_dwordx4 v[104:105], off
	v_lshl_add_u64 v[104:105], v[68:69], 0, s[4:5]
	s_mov_b32 m0, s72
	v_readfirstlane_b32 s33, v93
	global_load_lds_dwordx4 v[104:105], off
	v_lshl_add_u64 v[104:105], v[74:75], 0, s[4:5]
	s_mov_b32 m0, s73
	v_mfma_f32_32x32x16_bf16 v[0:15], v[108:111], v[116:119], v[0:15]
	global_load_lds_dwordx4 v[104:105], off
	v_lshl_add_u64 v[104:105], v[72:73], 0, s[4:5]
	s_mov_b32 m0, s92
	v_readfirstlane_b32 s92, v101
	global_load_lds_dwordx4 v[104:105], off
	v_lshl_add_u64 v[104:105], v[78:79], 0, s[4:5]
	s_mov_b32 m0, s69
	v_readfirstlane_b32 s69, v102
	global_load_lds_dwordx4 v[104:105], off
	v_lshl_add_u64 v[104:105], v[76:77], 0, s[4:5]
	s_mov_b32 m0, s82
	v_readfirstlane_b32 s82, v96
	global_load_lds_dwordx4 v[104:105], off
	ds_read_b128 v[104:107], v80
	ds_read_b128 v[108:111], v80 offset:4096
	ds_read_b128 v[112:115], v82 offset:16384
	ds_read_b128 v[116:119], v82 offset:20480
	s_waitcnt lgkmcnt(0)
	v_mfma_f32_32x32x16_bf16 v[48:63], v[104:107], v[112:115], v[48:63]
	s_mov_b32 m0, s82
	v_readfirstlane_b32 s73, v103
	v_lshl_add_u64 v[102:103], v[74:75], 0, s[66:67]
	v_readfirstlane_b32 s72, v92
	v_lshl_add_u64 v[92:93], v[70:71], 0, s[26:27]
	v_mfma_f32_32x32x16_bf16 v[32:47], v[104:107], v[116:119], v[32:47]
	v_mfma_f32_32x32x16_bf16 v[16:31], v[108:111], v[112:115], v[16:31]
	v_mfma_f32_32x32x16_bf16 v[0:15], v[108:111], v[116:119], v[0:15]
	ds_read_b128 v[104:107], v85
	ds_read_b128 v[108:111], v85 offset:4096
	ds_read_b128 v[112:115], v83 offset:16384
	ds_read_b128 v[116:119], v83 offset:20480
	s_waitcnt lgkmcnt(0)
	v_mfma_f32_32x32x16_bf16 v[48:63], v[104:107], v[112:115], v[48:63]
	v_mfma_f32_32x32x16_bf16 v[32:47], v[104:107], v[116:119], v[32:47]
	v_mfma_f32_32x32x16_bf16 v[16:31], v[108:111], v[112:115], v[16:31]
	v_mfma_f32_32x32x16_bf16 v[0:15], v[108:111], v[116:119], v[0:15]
	ds_read_b128 v[104:107], v86
	ds_read_b128 v[108:111], v86 offset:4096
	ds_read_b128 v[112:115], v84 offset:16384
	ds_read_b128 v[116:119], v84 offset:20480
	s_waitcnt lgkmcnt(0)
	v_mfma_f32_32x32x16_bf16 v[48:63], v[104:107], v[112:115], v[48:63]
	v_mfma_f32_32x32x16_bf16 v[32:47], v[104:107], v[116:119], v[32:47]
	v_mfma_f32_32x32x16_bf16 v[16:31], v[108:111], v[112:115], v[16:31]
	v_mfma_f32_32x32x16_bf16 v[0:15], v[108:111], v[116:119], v[0:15]
	ds_read_b128 v[104:107], v87
	ds_read_b128 v[108:111], v87 offset:4096
	ds_read_b128 v[112:115], v81 offset:16384
	ds_read_b128 v[116:119], v81 offset:20480
	s_waitcnt vmcnt(0)
	s_waitcnt vmcnt(0) lgkmcnt(0)
	s_barrier
; #define MFMA(a, b, c) __builtin_amdgcn_mfma_f32_32x32x16_bf16(a, b, c, 0, 0, 0)
; #define ISSUE(k0, bf) do { char* A_ = lw + (bf) * BUF; \
;     _Pragma("unroll") for (int i_ = 0; i_ < 4; ++i_) { glds16(al.ptr(lrow + 32 * i_, (k0) + cg), A_ + i_ * 4096); glds16(bl.ptr(lrow + 32 * i_, (k0) + cg), A_ + ABYTES + i_ * 4096); } \
;     if (HALO) { if (wid == 0) glds16(gh + (k0), A_ + 16384); } } while (0)
; template <bool HALO, class AL, class BL>
; __device__ __forceinline__ void gemm_core(f32x16 (&acc)[2][2], f32x16& hacc, const AL& al, const BL& bl, int K, char* lds,
;                                           const u16* halo0, const u16* halo1, int brow0, int brow1) {
;     ...
;   for (int kt = 0; kt < nk; ++kt) {
;     asm volatile("s_waitcnt vmcnt(0)" ::: "memory");
;     __syncthreads();
;     if (kt + 1 < nk) ISSUE((kt + 1) * 64, (kt + 1) & 1);
;     const char* T = lds + (kt & 1) * BUF;
; #pragma unroll
;     for (int kk = 0; kk < 4; ++kk) {
;       const int c = kk * 2 + hi;
;       bf16x8 a0 = *(const bf16x8*)(T + oa + ((c ^ sa) << 4));
;       bf16x8 a1 = *(const bf16x8*)(T + oa + 4096 + ((c ^ sa) << 4));
;       bf16x8 b0 = *(const bf16x8*)(T + ob0 + ((c ^ sb0) << 4));
;       bf16x8 b1 = *(const bf16x8*)(T + ob1 + ((c ^ sb1) << 4));
;       acc[0][0] = MFMA(a0, b0, acc[0][0]); acc[0][1] = MFMA(a0, b1, acc[0][1]);
;       acc[1][0] = MFMA(a1, b0, acc[1][0]); acc[1][1] = MFMA(a1, b1, acc[1][1]);
;       if (HALO) { bf16x8 ah = *(const bf16x8*)(T + oh + ((c ^ sh) << 4)); hacc = MFMA(ah, b0, hacc); }
;     }
	v_mfma_f32_32x32x16_bf16 v[48:63], v[104:107], v[112:115], v[48:63]
	v_mfma_f32_32x32x16_bf16 v[32:47], v[104:107], v[116:119], v[32:47]
	v_lshl_add_u64 v[104:105], v[66:67], 0, s[66:67]
	global_load_lds_dwordx4 v[104:105], off
	v_lshl_add_u64 v[104:105], v[64:65], 0, s[66:67]
	s_mov_b32 m0, s92
	s_nop 0
	global_load_lds_dwordx4 v[104:105], off
	v_lshl_add_u64 v[104:105], v[70:71], 0, s[66:67]
	s_mov_b32 m0, s69
	v_mfma_f32_32x32x16_bf16 v[16:31], v[108:111], v[112:115], v[16:31]
	global_load_lds_dwordx4 v[104:105], off
	v_lshl_add_u64 v[104:105], v[68:69], 0, s[66:67]
	s_mov_b32 m0, s73
	s_nop 0
	global_load_lds_dwordx4 v[104:105], off
	s_mov_b32 m0, s3
	v_mfma_f32_32x32x16_bf16 v[0:15], v[108:111], v[116:119], v[0:15]
	global_load_lds_dwordx4 v[102:103], off
	v_lshl_add_u64 v[102:103], v[72:73], 0, s[66:67]
	s_mov_b32 m0, s6
	v_readfirstlane_b32 s3, v99
	global_load_lds_dwordx4 v[102:103], off
	v_lshl_add_u64 v[102:103], v[78:79], 0, s[66:67]
	s_mov_b32 m0, s7
	v_readfirstlane_b32 s7, v97
	global_load_lds_dwordx4 v[102:103], off
	v_lshl_add_u64 v[102:103], v[76:77], 0, s[66:67]
	s_mov_b32 m0, s8
	v_readfirstlane_b32 s8, v98
	global_load_lds_dwordx4 v[102:103], off
	ds_read_b128 v[102:105], v80 offset:32768
	ds_read_b128 v[106:109], v80 offset:36864
	ds_read_b128 v[110:113], v82 offset:49152
	ds_read_b128 v[114:117], v82 offset:53248
	s_waitcnt lgkmcnt(0)
	v_mfma_f32_32x32x16_bf16 v[48:63], v[102:105], v[110:113], v[48:63]
	s_mov_b32 m0, s33
	v_readfirstlane_b32 s6, v100
	v_mfma_f32_32x32x16_bf16 v[32:47], v[102:105], v[114:117], v[32:47]
	v_mfma_f32_32x32x16_bf16 v[16:31], v[106:109], v[110:113], v[16:31]
	v_mfma_f32_32x32x16_bf16 v[0:15], v[106:109], v[114:117], v[0:15]
	ds_read_b128 v[102:105], v85 offset:32768
	ds_read_b128 v[106:109], v85 offset:36864
	ds_read_b128 v[110:113], v83 offset:49152
	ds_read_b128 v[114:117], v83 offset:53248
	s_waitcnt lgkmcnt(0)
	v_mfma_f32_32x32x16_bf16 v[48:63], v[102:105], v[110:113], v[48:63]
	v_mfma_f32_32x32x16_bf16 v[32:47], v[102:105], v[114:117], v[32:47]
	v_mfma_f32_32x32x16_bf16 v[16:31], v[106:109], v[110:113], v[16:31]
	v_mfma_f32_32x32x16_bf16 v[0:15], v[106:109], v[114:117], v[0:15]
	ds_read_b128 v[102:105], v86 offset:32768
	ds_read_b128 v[106:109], v86 offset:36864
	ds_read_b128 v[110:113], v84 offset:49152
	ds_read_b128 v[114:117], v84 offset:53248
	s_waitcnt lgkmcnt(0)
	v_mfma_f32_32x32x16_bf16 v[48:63], v[102:105], v[110:113], v[48:63]
	v_mfma_f32_32x32x16_bf16 v[32:47], v[102:105], v[114:117], v[32:47]
	v_mfma_f32_32x32x16_bf16 v[16:31], v[106:109], v[110:113], v[16:31]
	v_mfma_f32_32x32x16_bf16 v[0:15], v[106:109], v[114:117], v[0:15]
	ds_read_b128 v[102:105], v87 offset:32768
	ds_read_b128 v[106:109], v87 offset:36864
	ds_read_b128 v[110:113], v81 offset:49152
	ds_read_b128 v[114:117], v81 offset:53248
	s_waitcnt vmcnt(0)
	s_waitcnt vmcnt(0) lgkmcnt(0)
	s_barrier
	v_mfma_f32_32x32x16_bf16 v[48:63], v[102:105], v[110:113], v[48:63]
	v_mfma_f32_32x32x16_bf16 v[32:47], v[102:105], v[114:117], v[32:47]
	v_lshl_add_u64 v[102:103], v[66:67], 0, s[26:27]
	global_load_lds_dwordx4 v[102:103], off
	v_lshl_add_u64 v[102:103], v[64:65], 0, s[26:27]
	s_mov_b32 m0, s72
	s_nop 0
	global_load_lds_dwordx4 v[102:103], off
	s_mov_b32 m0, s18
	v_mfma_f32_32x32x16_bf16 v[16:31], v[106:109], v[110:113], v[16:31]
	global_load_lds_dwordx4 v[92:93], off
	v_lshl_add_u64 v[92:93], v[68:69], 0, s[26:27]
	s_mov_b32 m0, s19
	s_nop 0
	global_load_lds_dwordx4 v[92:93], off
	v_lshl_add_u64 v[92:93], v[74:75], 0, s[26:27]
	s_mov_b32 m0, s7
	v_mfma_f32_32x32x16_bf16 v[0:15], v[106:109], v[114:117], v[0:15]
	global_load_lds_dwordx4 v[92:93], off
	v_lshl_add_u64 v[92:93], v[72:73], 0, s[26:27]
	s_mov_b32 m0, s8
	s_nop 0
	global_load_lds_dwordx4 v[92:93], off
	v_lshl_add_u64 v[92:93], v[78:79], 0, s[26:27]
	s_mov_b32 m0, s3
	s_nop 0
	global_load_lds_dwordx4 v[92:93], off
	v_lshl_add_u64 v[92:93], v[76:77], 0, s[26:27]
	s_mov_b32 m0, s6
	s_nop 0
	global_load_lds_dwordx4 v[92:93], off
	ds_read_b128 v[92:95], v80
	ds_read_b128 v[96:99], v80 offset:4096
	ds_read_b128 v[100:103], v82 offset:16384
	ds_read_b128 v[104:107], v82 offset:20480
	s_waitcnt lgkmcnt(0)
	v_mfma_f32_32x32x16_bf16 v[48:63], v[92:95], v[100:103], v[48:63]
	s_mov_b32 m0, s82
	v_mfma_f32_32x32x16_bf16 v[32:47], v[92:95], v[104:107], v[32:47]
	v_mfma_f32_32x32x16_bf16 v[16:31], v[96:99], v[100:103], v[16:31]
	v_mfma_f32_32x32x16_bf16 v[0:15], v[96:99], v[104:107], v[0:15]
	ds_read_b128 v[92:95], v85
	ds_read_b128 v[96:99], v85 offset:4096
	ds_read_b128 v[100:103], v83 offset:16384
	ds_read_b128 v[104:107], v83 offset:20480
	s_waitcnt lgkmcnt(0)
	v_mfma_f32_32x32x16_bf16 v[48:63], v[92:95], v[100:103], v[48:63]
	v_mfma_f32_32x32x16_bf16 v[32:47], v[92:95], v[104:107], v[32:47]
	v_mfma_f32_32x32x16_bf16 v[16:31], v[96:99], v[100:103], v[16:31]
	v_mfma_f32_32x32x16_bf16 v[0:15], v[96:99], v[104:107], v[0:15]
	ds_read_b128 v[92:95], v86
	ds_read_b128 v[96:99], v86 offset:4096
	ds_read_b128 v[100:103], v84 offset:16384
	ds_read_b128 v[104:107], v84 offset:20480
	s_waitcnt lgkmcnt(0)
	v_mfma_f32_32x32x16_bf16 v[48:63], v[92:95], v[100:103], v[48:63]
	v_mfma_f32_32x32x16_bf16 v[32:47], v[92:95], v[104:107], v[32:47]
	v_mfma_f32_32x32x16_bf16 v[16:31], v[96:99], v[100:103], v[16:31]
	v_mfma_f32_32x32x16_bf16 v[0:15], v[96:99], v[104:107], v[0:15]
	ds_read_b128 v[92:95], v87
	ds_read_b128 v[96:99], v87 offset:4096
	ds_read_b128 v[100:103], v81 offset:16384
	ds_read_b128 v[104:107], v81 offset:20480
	s_waitcnt vmcnt(0)
	s_waitcnt vmcnt(0) lgkmcnt(0)
	s_barrier
; #define MFMA(a, b, c) __builtin_amdgcn_mfma_f32_32x32x16_bf16(a, b, c, 0, 0, 0)
; #define ISSUE(k0, bf) do { char* A_ = lw + (bf) * BUF; \
;     _Pragma("unroll") for (int i_ = 0; i_ < 4; ++i_) { glds16(al.ptr(lrow + 32 * i_, (k0) + cg), A_ + i_ * 4096); glds16(bl.ptr(lrow + 32 * i_, (k0) + cg), A_ + ABYTES + i_ * 4096); } \
;     if (HALO) { if (wid == 0) glds16(gh + (k0), A_ + 16384); } } while (0)
; template <bool HALO, class AL, class BL>
; __device__ __forceinline__ void gemm_core(f32x16 (&acc)[2][2], f32x16& hacc, const AL& al, const BL& bl, int K, char* lds,
;                                           const u16* halo0, const u16* halo1, int brow0, int brow1) {
;     ...
;   for (int kt = 0; kt < nk; ++kt) {
;     asm volatile("s_waitcnt vmcnt(0)" ::: "memory");
;     __syncthreads();
;     if (kt + 1 < nk) ISSUE((kt + 1) * 64, (kt + 1) & 1);
;     const char* T = lds + (kt & 1) * BUF;
; #pragma unroll
;     for (int kk = 0; kk < 4; ++kk) {
;       const int c = kk * 2 + hi;
;       bf16x8 a0 = *(const bf16x8*)(T + oa + ((c ^ sa) << 4));
;       bf16x8 a1 = *(const bf16x8*)(T + oa + 4096 + ((c ^ sa) << 4));
;       bf16x8 b0 = *(const bf16x8*)(T + ob0 + ((c ^ sb0) << 4));
;       bf16x8 b1 = *(const bf16x8*)(T + ob1 + ((c ^ sb1) << 4));
;       acc[0][0] = MFMA(a0, b0, acc[0][0]); acc[0][1] = MFMA(a0, b1, acc[0][1]);
;       acc[1][0] = MFMA(a1, b0, acc[1][0]); acc[1][1] = MFMA(a1, b1, acc[1][1]);
;       if (HALO) { bf16x8 ah = *(const bf16x8*)(T + oh + ((c ^ sh) << 4)); hacc = MFMA(ah, b0, hacc); }
;     }
	v_mfma_f32_32x32x16_bf16 v[48:63], v[92:95], v[100:103], v[48:63]
	v_mfma_f32_32x32x16_bf16 v[32:47], v[92:95], v[104:107], v[32:47]
	v_lshl_add_u64 v[92:93], v[66:67], 0, s[88:89]
	global_load_lds_dwordx4 v[92:93], off
	v_lshl_add_u64 v[92:93], v[64:65], 0, s[88:89]
	s_mov_b32 m0, s92
	s_nop 0
	global_load_lds_dwordx4 v[92:93], off
	v_lshl_add_u64 v[92:93], v[70:71], 0, s[88:89]
	s_mov_b32 m0, s69
	v_mfma_f32_32x32x16_bf16 v[16:31], v[96:99], v[100:103], v[16:31]
	global_load_lds_dwordx4 v[92:93], off
	v_lshl_add_u64 v[92:93], v[68:69], 0, s[88:89]
	s_mov_b32 m0, s73
	s_nop 0
	global_load_lds_dwordx4 v[92:93], off
	v_lshl_add_u64 v[92:93], v[74:75], 0, s[88:89]
	s_mov_b32 m0, s64
	v_mfma_f32_32x32x16_bf16 v[0:15], v[96:99], v[104:107], v[0:15]
	global_load_lds_dwordx4 v[92:93], off
	v_lshl_add_u64 v[92:93], v[72:73], 0, s[88:89]
	s_mov_b32 m0, s65
	s_nop 0
	global_load_lds_dwordx4 v[92:93], off
	s_mov_b32 m0, s42
	s_nop 0
	global_load_lds_dwordx4 v[88:89], off
	v_lshl_add_u64 v[88:89], v[76:77], 0, s[88:89]
	s_mov_b32 m0, s43
	s_nop 0
	global_load_lds_dwordx4 v[88:89], off
	ds_read_b128 v[88:91], v80 offset:32768
	ds_read_b128 v[92:95], v80 offset:36864
	ds_read_b128 v[96:99], v82 offset:49152
	ds_read_b128 v[100:103], v82 offset:53248
	s_waitcnt lgkmcnt(0)
	v_mfma_f32_32x32x16_bf16 v[48:63], v[88:91], v[96:99], v[48:63]
	s_mov_b32 m0, s33
	v_mfma_f32_32x32x16_bf16 v[32:47], v[88:91], v[100:103], v[32:47]
	v_mfma_f32_32x32x16_bf16 v[16:31], v[92:95], v[96:99], v[16:31]
	v_mfma_f32_32x32x16_bf16 v[0:15], v[92:95], v[100:103], v[0:15]
	ds_read_b128 v[88:91], v85 offset:32768
	ds_read_b128 v[92:95], v85 offset:36864
	ds_read_b128 v[96:99], v83 offset:49152
	ds_read_b128 v[100:103], v83 offset:53248
	s_waitcnt lgkmcnt(0)
	v_mfma_f32_32x32x16_bf16 v[48:63], v[88:91], v[96:99], v[48:63]
	v_mfma_f32_32x32x16_bf16 v[32:47], v[88:91], v[100:103], v[32:47]
	v_mfma_f32_32x32x16_bf16 v[16:31], v[92:95], v[96:99], v[16:31]
	v_mfma_f32_32x32x16_bf16 v[0:15], v[92:95], v[100:103], v[0:15]
	ds_read_b128 v[88:91], v86 offset:32768
	ds_read_b128 v[92:95], v86 offset:36864
	ds_read_b128 v[96:99], v84 offset:49152
	ds_read_b128 v[100:103], v84 offset:53248
	s_waitcnt lgkmcnt(0)
	v_mfma_f32_32x32x16_bf16 v[48:63], v[88:91], v[96:99], v[48:63]
	v_mfma_f32_32x32x16_bf16 v[32:47], v[88:91], v[100:103], v[32:47]
	v_mfma_f32_32x32x16_bf16 v[16:31], v[92:95], v[96:99], v[16:31]
	v_mfma_f32_32x32x16_bf16 v[0:15], v[92:95], v[100:103], v[0:15]
	ds_read_b128 v[88:91], v87 offset:32768
	ds_read_b128 v[92:95], v87 offset:36864
	ds_read_b128 v[96:99], v81 offset:49152
	ds_read_b128 v[100:103], v81 offset:53248
	s_waitcnt vmcnt(0)
	s_waitcnt vmcnt(0) lgkmcnt(0)
	s_barrier
	v_mfma_f32_32x32x16_bf16 v[48:63], v[88:91], v[96:99], v[48:63]
	v_mfma_f32_32x32x16_bf16 v[32:47], v[88:91], v[100:103], v[32:47]
	v_lshl_add_u64 v[88:89], v[66:67], 0, s[22:23]
	global_load_lds_dwordx4 v[88:89], off
	v_lshl_add_u64 v[88:89], v[64:65], 0, s[22:23]
	s_mov_b32 m0, s72
	s_nop 0
	global_load_lds_dwordx4 v[88:89], off
	v_lshl_add_u64 v[88:89], v[70:71], 0, s[22:23]
	s_mov_b32 m0, s18
	v_mfma_f32_32x32x16_bf16 v[16:31], v[92:95], v[96:99], v[16:31]
	global_load_lds_dwordx4 v[88:89], off
	v_lshl_add_u64 v[88:89], v[68:69], 0, s[22:23]
	s_mov_b32 m0, s19
	s_nop 0
	global_load_lds_dwordx4 v[88:89], off
	v_lshl_add_u64 v[88:89], v[74:75], 0, s[22:23]
	s_mov_b32 m0, s7
	v_mfma_f32_32x32x16_bf16 v[0:15], v[92:95], v[100:103], v[0:15]
	global_load_lds_dwordx4 v[88:89], off
	v_lshl_add_u64 v[88:89], v[72:73], 0, s[22:23]
	s_mov_b32 m0, s8
	s_nop 0
	global_load_lds_dwordx4 v[88:89], off
	v_lshl_add_u64 v[88:89], v[78:79], 0, s[22:23]
	s_mov_b32 m0, s3
	s_nop 0
	global_load_lds_dwordx4 v[88:89], off
	v_lshl_add_u64 v[88:89], v[76:77], 0, s[22:23]
	s_mov_b32 m0, s6
	s_nop 0
	global_load_lds_dwordx4 v[88:89], off
	ds_read_b128 v[88:91], v80
	ds_read_b128 v[92:95], v80 offset:4096
	ds_read_b128 v[96:99], v82 offset:16384
	ds_read_b128 v[100:103], v82 offset:20480
	s_waitcnt lgkmcnt(0)
	v_mfma_f32_32x32x16_bf16 v[48:63], v[88:91], v[96:99], v[48:63]
	s_mov_b32 m0, s82
	v_mfma_f32_32x32x16_bf16 v[32:47], v[88:91], v[100:103], v[32:47]
	v_mfma_f32_32x32x16_bf16 v[16:31], v[92:95], v[96:99], v[16:31]
	v_mfma_f32_32x32x16_bf16 v[0:15], v[92:95], v[100:103], v[0:15]
	ds_read_b128 v[88:91], v85
	ds_read_b128 v[92:95], v85 offset:4096
	ds_read_b128 v[96:99], v83 offset:16384
	ds_read_b128 v[100:103], v83 offset:20480
	s_waitcnt lgkmcnt(0)
	v_mfma_f32_32x32x16_bf16 v[48:63], v[88:91], v[96:99], v[48:63]
	v_mfma_f32_32x32x16_bf16 v[32:47], v[88:91], v[100:103], v[32:47]
	v_mfma_f32_32x32x16_bf16 v[16:31], v[92:95], v[96:99], v[16:31]
	v_mfma_f32_32x32x16_bf16 v[0:15], v[92:95], v[100:103], v[0:15]
	ds_read_b128 v[88:91], v86
	ds_read_b128 v[92:95], v86 offset:4096
	ds_read_b128 v[96:99], v84 offset:16384
	ds_read_b128 v[100:103], v84 offset:20480
	s_waitcnt lgkmcnt(0)
	v_mfma_f32_32x32x16_bf16 v[48:63], v[88:91], v[96:99], v[48:63]
	v_mfma_f32_32x32x16_bf16 v[32:47], v[88:91], v[100:103], v[32:47]
	v_mfma_f32_32x32x16_bf16 v[16:31], v[92:95], v[96:99], v[16:31]
	v_mfma_f32_32x32x16_bf16 v[0:15], v[92:95], v[100:103], v[0:15]
	ds_read_b128 v[88:91], v87
	ds_read_b128 v[92:95], v87 offset:4096
	ds_read_b128 v[96:99], v81 offset:16384
	ds_read_b128 v[100:103], v81 offset:20480
	s_waitcnt vmcnt(0)
	s_waitcnt vmcnt(0) lgkmcnt(0)
	s_barrier
; #define MFMA(a, b, c) __builtin_amdgcn_mfma_f32_32x32x16_bf16(a, b, c, 0, 0, 0)
; #define ISSUE(k0, bf) do { char* A_ = lw + (bf) * BUF; \
;     _Pragma("unroll") for (int i_ = 0; i_ < 4; ++i_) { glds16(al.ptr(lrow + 32 * i_, (k0) + cg), A_ + i_ * 4096); glds16(bl.ptr(lrow + 32 * i_, (k0) + cg), A_ + ABYTES + i_ * 4096); } \
;     if (HALO) { if (wid == 0) glds16(gh + (k0), A_ + 16384); } } while (0)
; template <bool HALO, class AL, class BL>
; __device__ __forceinline__ void gemm_core(f32x16 (&acc)[2][2], f32x16& hacc, const AL& al, const BL& bl, int K, char* lds,
;                                           const u16* halo0, const u16* halo1, int brow0, int brow1) {
;     ...
;   for (int kt = 0; kt < nk; ++kt) {
;     asm volatile("s_waitcnt vmcnt(0)" ::: "memory");
;     __syncthreads();
;     if (kt + 1 < nk) ISSUE((kt + 1) * 64, (kt + 1) & 1);
;     const char* T = lds + (kt & 1) * BUF;
; #pragma unroll
;     for (int kk = 0; kk < 4; ++kk) {
;       const int c = kk * 2 + hi;
;       bf16x8 a0 = *(const bf16x8*)(T + oa + ((c ^ sa) << 4));
;       bf16x8 a1 = *(const bf16x8*)(T + oa + 4096 + ((c ^ sa) << 4));
;       bf16x8 b0 = *(const bf16x8*)(T + ob0 + ((c ^ sb0) << 4));
;       bf16x8 b1 = *(const bf16x8*)(T + ob1 + ((c ^ sb1) << 4));
;       acc[0][0] = MFMA(a0, b0, acc[0][0]); acc[0][1] = MFMA(a0, b1, acc[0][1]);
;       acc[1][0] = MFMA(a1, b0, acc[1][0]); acc[1][1] = MFMA(a1, b1, acc[1][1]);
;       if (HALO) { bf16x8 ah = *(const bf16x8*)(T + oh + ((c ^ sh) << 4)); hacc = MFMA(ah, b0, hacc); }
;     }
	v_mfma_f32_32x32x16_bf16 v[48:63], v[88:91], v[96:99], v[48:63]
	v_mfma_f32_32x32x16_bf16 v[32:47], v[88:91], v[100:103], v[32:47]
	v_lshl_add_u64 v[88:89], v[66:67], 0, s[90:91]
	global_load_lds_dwordx4 v[88:89], off
	v_lshl_add_u64 v[88:89], v[64:65], 0, s[90:91]
	s_mov_b32 m0, s92
	s_nop 0
	global_load_lds_dwordx4 v[88:89], off
	v_lshl_add_u64 v[88:89], v[70:71], 0, s[90:91]
	s_mov_b32 m0, s69
	v_mfma_f32_32x32x16_bf16 v[16:31], v[92:95], v[96:99], v[16:31]
	global_load_lds_dwordx4 v[88:89], off
	v_lshl_add_u64 v[88:89], v[68:69], 0, s[90:91]
	s_mov_b32 m0, s73
	s_nop 0
	global_load_lds_dwordx4 v[88:89], off
	v_lshl_add_u64 v[88:89], v[74:75], 0, s[90:91]
	s_mov_b32 m0, s64
	v_mfma_f32_32x32x16_bf16 v[0:15], v[92:95], v[100:103], v[0:15]
	global_load_lds_dwordx4 v[88:89], off
	v_lshl_add_u64 v[88:89], v[72:73], 0, s[90:91]
	s_mov_b32 m0, s65
	s_nop 0
	global_load_lds_dwordx4 v[88:89], off
	v_lshl_add_u64 v[88:89], v[78:79], 0, s[90:91]
	s_mov_b32 m0, s42
	s_nop 0
	global_load_lds_dwordx4 v[88:89], off
	v_lshl_add_u64 v[88:89], v[76:77], 0, s[90:91]
	s_mov_b32 m0, s43
	s_nop 0
	global_load_lds_dwordx4 v[88:89], off
	ds_read_b128 v[88:91], v80 offset:32768
	ds_read_b128 v[92:95], v80 offset:36864
	ds_read_b128 v[96:99], v82 offset:49152
	ds_read_b128 v[100:103], v82 offset:53248
	s_waitcnt lgkmcnt(0)
	v_mfma_f32_32x32x16_bf16 v[48:63], v[88:91], v[96:99], v[48:63]
	s_mov_b32 m0, s33
	v_mfma_f32_32x32x16_bf16 v[32:47], v[88:91], v[100:103], v[32:47]
	v_mfma_f32_32x32x16_bf16 v[16:31], v[92:95], v[96:99], v[16:31]
	v_mfma_f32_32x32x16_bf16 v[0:15], v[92:95], v[100:103], v[0:15]
	ds_read_b128 v[88:91], v85 offset:32768
	ds_read_b128 v[92:95], v85 offset:36864
	ds_read_b128 v[96:99], v83 offset:49152
	ds_read_b128 v[100:103], v83 offset:53248
	s_waitcnt lgkmcnt(0)
	v_mfma_f32_32x32x16_bf16 v[48:63], v[88:91], v[96:99], v[48:63]
	v_mfma_f32_32x32x16_bf16 v[32:47], v[88:91], v[100:103], v[32:47]
	v_mfma_f32_32x32x16_bf16 v[16:31], v[92:95], v[96:99], v[16:31]
	v_mfma_f32_32x32x16_bf16 v[0:15], v[92:95], v[100:103], v[0:15]
	ds_read_b128 v[88:91], v86 offset:32768
	ds_read_b128 v[92:95], v86 offset:36864
	ds_read_b128 v[96:99], v84 offset:49152
	ds_read_b128 v[100:103], v84 offset:53248
	s_waitcnt lgkmcnt(0)
	v_mfma_f32_32x32x16_bf16 v[48:63], v[88:91], v[96:99], v[48:63]
	v_mfma_f32_32x32x16_bf16 v[32:47], v[88:91], v[100:103], v[32:47]
	v_mfma_f32_32x32x16_bf16 v[16:31], v[92:95], v[96:99], v[16:31]
	v_mfma_f32_32x32x16_bf16 v[0:15], v[92:95], v[100:103], v[0:15]
	ds_read_b128 v[88:91], v87 offset:32768
	ds_read_b128 v[92:95], v87 offset:36864
	ds_read_b128 v[96:99], v81 offset:49152
	ds_read_b128 v[100:103], v81 offset:53248
	s_waitcnt vmcnt(0)
	s_waitcnt vmcnt(0) lgkmcnt(0)
	s_barrier
	v_mfma_f32_32x32x16_bf16 v[48:63], v[88:91], v[96:99], v[48:63]
	v_mfma_f32_32x32x16_bf16 v[32:47], v[88:91], v[100:103], v[32:47]
	v_lshl_add_u64 v[88:89], v[66:67], 0, s[0:1]
	global_load_lds_dwordx4 v[88:89], off
	v_lshl_add_u64 v[88:89], v[64:65], 0, s[0:1]
	s_mov_b32 m0, s72
	s_nop 0
	global_load_lds_dwordx4 v[88:89], off
	v_lshl_add_u64 v[88:89], v[70:71], 0, s[0:1]
	s_mov_b32 m0, s18
	v_mfma_f32_32x32x16_bf16 v[16:31], v[92:95], v[96:99], v[16:31]
	global_load_lds_dwordx4 v[88:89], off
	v_lshl_add_u64 v[88:89], v[68:69], 0, s[0:1]
	s_mov_b32 m0, s19
	s_nop 0
	global_load_lds_dwordx4 v[88:89], off
	v_lshl_add_u64 v[88:89], v[74:75], 0, s[0:1]
	s_mov_b32 m0, s7
	v_mfma_f32_32x32x16_bf16 v[0:15], v[92:95], v[100:103], v[0:15]
	global_load_lds_dwordx4 v[88:89], off
	v_lshl_add_u64 v[88:89], v[72:73], 0, s[0:1]
	s_mov_b32 m0, s8
	s_nop 0
	global_load_lds_dwordx4 v[88:89], off
	v_lshl_add_u64 v[88:89], v[78:79], 0, s[0:1]
	s_mov_b32 m0, s3
	s_nop 0
	global_load_lds_dwordx4 v[88:89], off
	v_lshl_add_u64 v[88:89], v[76:77], 0, s[0:1]
	s_mov_b32 m0, s6
	s_nop 0
	global_load_lds_dwordx4 v[88:89], off
	ds_read_b128 v[88:91], v80
	ds_read_b128 v[92:95], v80 offset:4096
	ds_read_b128 v[96:99], v82 offset:16384
	ds_read_b128 v[100:103], v82 offset:20480
	s_waitcnt lgkmcnt(0)
	v_mfma_f32_32x32x16_bf16 v[48:63], v[88:91], v[96:99], v[48:63]
	s_mov_b32 m0, s82
	v_mfma_f32_32x32x16_bf16 v[32:47], v[88:91], v[100:103], v[32:47]
	v_mfma_f32_32x32x16_bf16 v[16:31], v[92:95], v[96:99], v[16:31]
	v_mfma_f32_32x32x16_bf16 v[0:15], v[92:95], v[100:103], v[0:15]
	ds_read_b128 v[88:91], v85
	ds_read_b128 v[92:95], v85 offset:4096
	ds_read_b128 v[96:99], v83 offset:16384
	ds_read_b128 v[100:103], v83 offset:20480
	s_waitcnt lgkmcnt(0)
	v_mfma_f32_32x32x16_bf16 v[48:63], v[88:91], v[96:99], v[48:63]
	v_mfma_f32_32x32x16_bf16 v[32:47], v[88:91], v[100:103], v[32:47]
	v_mfma_f32_32x32x16_bf16 v[16:31], v[92:95], v[96:99], v[16:31]
	v_mfma_f32_32x32x16_bf16 v[0:15], v[92:95], v[100:103], v[0:15]
	ds_read_b128 v[88:91], v86
	ds_read_b128 v[92:95], v86 offset:4096
	ds_read_b128 v[96:99], v84 offset:16384
	ds_read_b128 v[100:103], v84 offset:20480
	s_waitcnt lgkmcnt(0)
	v_mfma_f32_32x32x16_bf16 v[48:63], v[88:91], v[96:99], v[48:63]
	v_mfma_f32_32x32x16_bf16 v[32:47], v[88:91], v[100:103], v[32:47]
	v_mfma_f32_32x32x16_bf16 v[16:31], v[92:95], v[96:99], v[16:31]
	v_mfma_f32_32x32x16_bf16 v[0:15], v[92:95], v[100:103], v[0:15]
	ds_read_b128 v[88:91], v87
	ds_read_b128 v[92:95], v87 offset:4096
	ds_read_b128 v[96:99], v81 offset:16384
	ds_read_b128 v[100:103], v81 offset:20480
	s_waitcnt vmcnt(0)
	s_waitcnt vmcnt(0) lgkmcnt(0)
	s_barrier
; #define MFMA(a, b, c) __builtin_amdgcn_mfma_f32_32x32x16_bf16(a, b, c, 0, 0, 0)
; #define ISSUE(k0, bf) do { char* A_ = lw + (bf) * BUF; \
;     _Pragma("unroll") for (int i_ = 0; i_ < 4; ++i_) { glds16(al.ptr(lrow + 32 * i_, (k0) + cg), A_ + i_ * 4096); glds16(bl.ptr(lrow + 32 * i_, (k0) + cg), A_ + ABYTES + i_ * 4096); } \
;     if (HALO) { if (wid == 0) glds16(gh + (k0), A_ + 16384); } } while (0)
; template <bool HALO, class AL, class BL>
; __device__ __forceinline__ void gemm_core(f32x16 (&acc)[2][2], f32x16& hacc, const AL& al, const BL& bl, int K, char* lds,
;                                           const u16* halo0, const u16* halo1, int brow0, int brow1) {
;     ...
;   for (int kt = 0; kt < nk; ++kt) {
;     asm volatile("s_waitcnt vmcnt(0)" ::: "memory");
;     __syncthreads();
;     if (kt + 1 < nk) ISSUE((kt + 1) * 64, (kt + 1) & 1);
;     const char* T = lds + (kt & 1) * BUF;
; #pragma unroll
;     for (int kk = 0; kk < 4; ++kk) {
;       const int c = kk * 2 + hi;
;       bf16x8 a0 = *(const bf16x8*)(T + oa + ((c ^ sa) << 4));
;       bf16x8 a1 = *(const bf16x8*)(T + oa + 4096 + ((c ^ sa) << 4));
;       bf16x8 b0 = *(const bf16x8*)(T + ob0 + ((c ^ sb0) << 4));
;       bf16x8 b1 = *(const bf16x8*)(T + ob1 + ((c ^ sb1) << 4));
;       acc[0][0] = MFMA(a0, b0, acc[0][0]); acc[0][1] = MFMA(a0, b1, acc[0][1]);
;       acc[1][0] = MFMA(a1, b0, acc[1][0]); acc[1][1] = MFMA(a1, b1, acc[1][1]);
;       if (HALO) { bf16x8 ah = *(const bf16x8*)(T + oh + ((c ^ sh) << 4)); hacc = MFMA(ah, b0, hacc); }
;     }
	v_mfma_f32_32x32x16_bf16 v[48:63], v[88:91], v[96:99], v[48:63]
	v_mfma_f32_32x32x16_bf16 v[32:47], v[88:91], v[100:103], v[32:47]
	v_lshl_add_u64 v[88:89], v[66:67], 0, s[34:35]
	global_load_lds_dwordx4 v[88:89], off
	v_lshl_add_u64 v[88:89], v[64:65], 0, s[34:35]
	s_mov_b32 m0, s92
	v_lshl_add_u64 v[66:67], v[66:67], 0, s[38:39]
	global_load_lds_dwordx4 v[88:89], off
	v_lshl_add_u64 v[88:89], v[70:71], 0, s[34:35]
	s_mov_b32 m0, s69
	v_mfma_f32_32x32x16_bf16 v[0:15], v[92:95], v[100:103], v[0:15]
	global_load_lds_dwordx4 v[88:89], off
	v_lshl_add_u64 v[88:89], v[68:69], 0, s[34:35]
	s_mov_b32 m0, s73
	v_lshl_add_u64 v[64:65], v[64:65], 0, s[38:39]
	global_load_lds_dwordx4 v[88:89], off
	v_lshl_add_u64 v[88:89], v[74:75], 0, s[34:35]
	s_mov_b32 m0, s64
	v_mfma_f32_32x32x16_bf16 v[16:31], v[92:95], v[96:99], v[16:31]
	global_load_lds_dwordx4 v[88:89], off
	v_lshl_add_u64 v[88:89], v[72:73], 0, s[34:35]
	s_mov_b32 m0, s65
	s_nop 0
	global_load_lds_dwordx4 v[88:89], off
	v_lshl_add_u64 v[88:89], v[78:79], 0, s[34:35]
	s_mov_b32 m0, s42
	s_nop 0
	global_load_lds_dwordx4 v[88:89], off
	v_lshl_add_u64 v[88:89], v[76:77], 0, s[34:35]
	s_mov_b32 m0, s43
	s_nop 0
	global_load_lds_dwordx4 v[88:89], off
	ds_read_b128 v[88:91], v80 offset:32768
	ds_read_b128 v[92:95], v80 offset:36864
	ds_read_b128 v[96:99], v82 offset:49152
	ds_read_b128 v[100:103], v82 offset:53248
	s_waitcnt lgkmcnt(0)
	v_mfma_f32_32x32x16_bf16 v[0:15], v[92:95], v[100:103], v[0:15]
	s_mov_b32 m0, s33
	v_mfma_f32_32x32x16_bf16 v[48:63], v[88:91], v[96:99], v[48:63]
	v_mfma_f32_32x32x16_bf16 v[32:47], v[88:91], v[100:103], v[32:47]
	v_mfma_f32_32x32x16_bf16 v[16:31], v[92:95], v[96:99], v[16:31]
	ds_read_b128 v[88:91], v85 offset:32768
	ds_read_b128 v[92:95], v85 offset:36864
	ds_read_b128 v[96:99], v83 offset:49152
	ds_read_b128 v[100:103], v83 offset:53248
	s_waitcnt lgkmcnt(0)
	v_mfma_f32_32x32x16_bf16 v[0:15], v[92:95], v[100:103], v[0:15]
	v_mfma_f32_32x32x16_bf16 v[48:63], v[88:91], v[96:99], v[48:63]
	v_mfma_f32_32x32x16_bf16 v[32:47], v[88:91], v[100:103], v[32:47]
	v_mfma_f32_32x32x16_bf16 v[16:31], v[92:95], v[96:99], v[16:31]
	ds_read_b128 v[88:91], v86 offset:32768
	ds_read_b128 v[92:95], v86 offset:36864
	ds_read_b128 v[96:99], v84 offset:49152
	ds_read_b128 v[100:103], v84 offset:53248
	s_waitcnt lgkmcnt(0)
	v_mfma_f32_32x32x16_bf16 v[0:15], v[92:95], v[100:103], v[0:15]
	v_mfma_f32_32x32x16_bf16 v[48:63], v[88:91], v[96:99], v[48:63]
	v_mfma_f32_32x32x16_bf16 v[32:47], v[88:91], v[100:103], v[32:47]
	v_mfma_f32_32x32x16_bf16 v[16:31], v[92:95], v[96:99], v[16:31]
	ds_read_b128 v[88:91], v87 offset:32768
	ds_read_b128 v[92:95], v87 offset:36864
	ds_read_b128 v[96:99], v81 offset:49152
	ds_read_b128 v[100:103], v81 offset:53248
	s_waitcnt vmcnt(0)
	s_waitcnt vmcnt(0) lgkmcnt(0)
	s_barrier
	global_load_lds_dwordx4 v[66:67], off
	s_mov_b32 m0, s72
	v_mfma_f32_32x32x16_bf16 v[0:15], v[92:95], v[100:103], v[0:15]
	global_load_lds_dwordx4 v[64:65], off
	v_lshl_add_u64 v[64:65], v[70:71], 0, s[38:39]
	s_mov_b32 m0, s18
	s_nop 0
	global_load_lds_dwordx4 v[64:65], off
	v_lshl_add_u64 v[64:65], v[68:69], 0, s[38:39]
	s_mov_b32 m0, s19
	v_mfma_f32_32x32x16_bf16 v[48:63], v[88:91], v[96:99], v[48:63]
	global_load_lds_dwordx4 v[64:65], off
	v_lshl_add_u64 v[64:65], v[74:75], 0, s[38:39]
	s_mov_b32 m0, s7
	s_mov_b64 s[18:19], 0x4000
	global_load_lds_dwordx4 v[64:65], off
	v_lshl_add_u64 v[64:65], v[72:73], 0, s[38:39]
	s_mov_b32 m0, s8
	v_mfma_f32_32x32x16_bf16 v[32:47], v[88:91], v[100:103], v[32:47]
	global_load_lds_dwordx4 v[64:65], off
	v_lshl_add_u64 v[64:65], v[78:79], 0, s[38:39]
	s_mov_b32 m0, s3
	s_lshl_b32 s3, s85, 16
	global_load_lds_dwordx4 v[64:65], off
	v_lshl_add_u64 v[64:65], v[76:77], 0, s[38:39]
	s_mov_b32 m0, s6
	v_mfma_f32_32x32x16_bf16 v[16:31], v[92:95], v[96:99], v[16:31]
	global_load_lds_dwordx4 v[64:65], off
	ds_read_b128 v[64:67], v80
	ds_read_b128 v[68:71], v80 offset:4096
	ds_read_b128 v[72:75], v82 offset:16384
	ds_read_b128 v[76:79], v82 offset:20480
	v_readlane_b32 s6, v255, 23
	s_add_u32 s72, s6, s3
	v_readlane_b32 s3, v255, 24
	s_addc_u32 s73, s3, 0
	s_waitcnt lgkmcnt(0)
	v_mfma_f32_32x32x16_bf16 v[0:15], v[68:71], v[76:79], v[0:15]
	s_lshl_b64 s[6:7], s[62:63], 16
	v_readlane_b32 s3, v255, 21
	s_add_u32 s6, s3, s6
	v_readlane_b32 s3, v255, 22
	s_addc_u32 s7, s3, s7
	v_mfma_f32_32x32x16_bf16 v[48:63], v[64:67], v[72:75], v[48:63]
	v_mfma_f32_32x32x16_bf16 v[32:47], v[64:67], v[76:79], v[32:47]
	v_mfma_f32_32x32x16_bf16 v[16:31], v[68:71], v[72:75], v[16:31]
	ds_read_b128 v[64:67], v85
	ds_read_b128 v[68:71], v85 offset:4096
	ds_read_b128 v[72:75], v83 offset:16384
	ds_read_b128 v[76:79], v83 offset:20480
	s_waitcnt lgkmcnt(0)
	v_mfma_f32_32x32x16_bf16 v[0:15], v[68:71], v[76:79], v[0:15]
	v_mfma_f32_32x32x16_bf16 v[48:63], v[64:67], v[72:75], v[48:63]
	v_mfma_f32_32x32x16_bf16 v[32:47], v[64:67], v[76:79], v[32:47]
	v_mfma_f32_32x32x16_bf16 v[16:31], v[68:71], v[72:75], v[16:31]
	ds_read_b128 v[64:67], v86
	ds_read_b128 v[68:71], v86 offset:4096
	ds_read_b128 v[72:75], v84 offset:16384
	ds_read_b128 v[76:79], v84 offset:20480
	s_waitcnt lgkmcnt(0)
	v_mfma_f32_32x32x16_bf16 v[0:15], v[68:71], v[76:79], v[0:15]
	v_mfma_f32_32x32x16_bf16 v[48:63], v[64:67], v[72:75], v[48:63]
	v_mfma_f32_32x32x16_bf16 v[32:47], v[64:67], v[76:79], v[32:47]
	v_mfma_f32_32x32x16_bf16 v[16:31], v[68:71], v[72:75], v[16:31]
	ds_read_b128 v[64:67], v87
	ds_read_b128 v[68:71], v87 offset:4096
	ds_read_b128 v[72:75], v81 offset:16384
	ds_read_b128 v[76:79], v81 offset:20480
	s_waitcnt vmcnt(0)
	s_waitcnt vmcnt(0) lgkmcnt(0)
	s_barrier
; __device__ __forceinline__ float sigmoidf_(float x) { return __builtin_amdgcn_rcpf(1.f + __expf(-x)); }
; #define MFMA(a, b, c) __builtin_amdgcn_mfma_f32_32x32x16_bf16(a, b, c, 0, 0, 0)
; template <bool HALO, class AL, class BL>
; __device__ __forceinline__ void gemm_core(f32x16 (&acc)[2][2], f32x16& hacc, const AL& al, const BL& bl, int K, char* lds,
;                                           const u16* halo0, const u16* halo1, int brow0, int brow1) {
;     ...
;     for (int kk = 0; kk < 4; ++kk) {
;       const int c = kk * 2 + hi;
;       bf16x8 a0 = *(const bf16x8*)(T + oa + ((c ^ sa) << 4));
;       bf16x8 a1 = *(const bf16x8*)(T + oa + 4096 + ((c ^ sa) << 4));
;       bf16x8 b0 = *(const bf16x8*)(T + ob0 + ((c ^ sb0) << 4));
;       bf16x8 b1 = *(const bf16x8*)(T + ob1 + ((c ^ sb1) << 4));
;       acc[0][0] = MFMA(a0, b0, acc[0][0]); acc[0][1] = MFMA(a0, b1, acc[0][1]);
;       acc[1][0] = MFMA(a1, b0, acc[1][0]); acc[1][1] = MFMA(a1, b1, acc[1][1]);
;       if (HALO) { bf16x8 ah = *(const bf16x8*)(T + oh + ((c ^ sh) << 4)); hacc = MFMA(ah, b0, hacc); }
;     }
; __device__ __forceinline__ void phase_ffn_down(const P& p, int layer, char* lds) {
;     ...
; #pragma unroll
;     for (int mi = 0; mi < 2; ++mi)
; #pragma unroll
;       for (int ni = 0; ni < 2; ++ni)
; #pragma unroll
;         for (int r = 0; r < 16; ++r) acc[mi][ni][r] = sigmoidf_(acc[mi][ni][r]);
	v_mfma_f32_32x32x16_bf16 v[0:15], v[68:71], v[76:79], v[0:15]
	v_mfma_f32_32x32x16_bf16 v[48:63], v[64:67], v[72:75], v[48:63]
	v_mfma_f32_32x32x16_bf16 v[32:47], v[64:67], v[76:79], v[32:47]
	v_mfma_f32_32x32x16_bf16 v[16:31], v[68:71], v[72:75], v[16:31]
	ds_read_b128 v[64:67], v80 offset:32768
	ds_read_b128 v[68:71], v80 offset:36864
	ds_read_b128 v[72:75], v82 offset:49152
	ds_read_b128 v[76:79], v82 offset:53248
	s_waitcnt lgkmcnt(0)
	v_mfma_f32_32x32x16_bf16 v[0:15], v[68:71], v[76:79], v[0:15]
	v_mfma_f32_32x32x16_bf16 v[48:63], v[64:67], v[72:75], v[48:63]
	v_mfma_f32_32x32x16_bf16 v[32:47], v[64:67], v[76:79], v[32:47]
	v_mfma_f32_32x32x16_bf16 v[16:31], v[68:71], v[72:75], v[16:31]
	ds_read_b128 v[64:67], v85 offset:32768
	ds_read_b128 v[68:71], v85 offset:36864
	ds_read_b128 v[72:75], v83 offset:49152
	ds_read_b128 v[76:79], v83 offset:53248
	s_waitcnt lgkmcnt(0)
	v_mfma_f32_32x32x16_bf16 v[0:15], v[68:71], v[76:79], v[0:15]
	v_mfma_f32_32x32x16_bf16 v[48:63], v[64:67], v[72:75], v[48:63]
	v_mfma_f32_32x32x16_bf16 v[32:47], v[64:67], v[76:79], v[32:47]
	v_mfma_f32_32x32x16_bf16 v[16:31], v[68:71], v[72:75], v[16:31]
	ds_read_b128 v[64:67], v86 offset:32768
	ds_read_b128 v[68:71], v86 offset:36864
	ds_read_b128 v[72:75], v84 offset:49152
	ds_read_b128 v[76:79], v84 offset:53248
	s_waitcnt lgkmcnt(0)
	v_mfma_f32_32x32x16_bf16 v[0:15], v[68:71], v[76:79], v[0:15]
	v_mfma_f32_32x32x16_bf16 v[48:63], v[64:67], v[72:75], v[48:63]
	v_mfma_f32_32x32x16_bf16 v[32:47], v[64:67], v[76:79], v[32:47]
	v_mfma_f32_32x32x16_bf16 v[16:31], v[68:71], v[72:75], v[16:31]
	ds_read_b128 v[64:67], v87 offset:32768
	ds_read_b128 v[68:71], v87 offset:36864
	ds_read_b128 v[72:75], v81 offset:49152
	ds_read_b128 v[76:79], v81 offset:53248
	s_waitcnt lgkmcnt(0)
	v_mfma_f32_32x32x16_bf16 v[0:15], v[68:71], v[76:79], v[0:15]
	v_mfma_f32_32x32x16_bf16 v[16:31], v[68:71], v[72:75], v[16:31]
	s_nop 10
	v_mul_f32_e32 v0, 0xbfb8aa3b, v0
	v_exp_f32_e32 v0, v0
	s_nop 0
	v_add_f32_e32 v0, 1.0, v0
	v_rcp_f32_e32 v110, v0
	v_mul_f32_e32 v0, 0xbfb8aa3b, v1
	v_exp_f32_e32 v0, v0
	v_mul_f32_e32 v16, 0xbfb8aa3b, v16
	v_exp_f32_e32 v16, v16
	v_mov_b32_e32 v1, v229
	v_add_f32_e32 v0, 1.0, v0
	v_rcp_f32_e32 v111, v0
	v_mul_f32_e32 v0, 0xbfb8aa3b, v2
	v_exp_f32_e32 v0, v0
	v_add_f32_e32 v16, 1.0, v16
	v_rcp_f32_e32 v96, v16
	v_mul_f32_e32 v16, 0xbfb8aa3b, v17
	v_add_f32_e32 v0, 1.0, v0
	v_rcp_f32_e32 v114, v0
	v_mul_f32_e32 v0, 0xbfb8aa3b, v3
	v_exp_f32_e32 v0, v0
	v_exp_f32_e32 v16, v16
	v_mfma_f32_32x32x16_bf16 v[48:63], v[64:67], v[72:75], v[48:63]
	v_add_f32_e32 v0, 1.0, v0
	v_rcp_f32_e32 v115, v0
	v_mul_f32_e32 v0, 0xbfb8aa3b, v4
	v_exp_f32_e32 v0, v0
	v_add_f32_e32 v16, 1.0, v16
	v_rcp_f32_e32 v97, v16
	v_mul_f32_e32 v16, 0xbfb8aa3b, v18
	v_add_f32_e32 v0, 1.0, v0
	v_rcp_f32_e32 v116, v0
	v_mul_f32_e32 v0, 0xbfb8aa3b, v5
	v_exp_f32_e32 v0, v0
	v_exp_f32_e32 v16, v16
	v_mfma_f32_32x32x16_bf16 v[32:47], v[64:67], v[76:79], v[32:47]
	v_mul_f32_e32 v48, 0xbfb8aa3b, v48
	v_add_f32_e32 v0, 1.0, v0
	v_rcp_f32_e32 v117, v0
	v_mul_f32_e32 v0, 0xbfb8aa3b, v6
	v_exp_f32_e32 v0, v0
	v_add_f32_e32 v16, 1.0, v16
	v_rcp_f32_e32 v98, v16
	v_mul_f32_e32 v16, 0xbfb8aa3b, v19
	v_add_f32_e32 v0, 1.0, v0
	v_rcp_f32_e32 v118, v0
	v_mul_f32_e32 v0, 0xbfb8aa3b, v7
	v_exp_f32_e32 v0, v0
	v_exp_f32_e32 v16, v16
	v_mov_b32_e32 v6, v229
	v_add_f32_e32 v0, 1.0, v0
	v_add_f32_e32 v16, 1.0, v16
	v_rcp_f32_e32 v119, v0
	v_mul_f32_e32 v0, 0xbfb8aa3b, v8
	v_rcp_f32_e32 v99, v16
	v_mul_f32_e32 v16, 0xbfb8aa3b, v20
	v_exp_f32_e32 v0, v0
	v_exp_f32_e32 v16, v16
	v_and_b32_e32 v7, 31, v6
	v_lshrrev_b32_e32 v2, 4, v6
	v_add_f32_e32 v0, 1.0, v0
	v_add_f32_e32 v16, 1.0, v16
	v_rcp_f32_e32 v120, v0
	v_mul_f32_e32 v0, 0xbfb8aa3b, v9
	v_rcp_f32_e32 v100, v16
	v_mul_f32_e32 v16, 0xbfb8aa3b, v21
	v_exp_f32_e32 v0, v0
	v_exp_f32_e32 v16, v16
	v_xor_b32_e32 v4, v2, v6
	v_lshlrev_b32_e32 v4, 4, v4
	v_add_f32_e32 v0, 1.0, v0
	v_add_f32_e32 v16, 1.0, v16
	v_rcp_f32_e32 v121, v0
	v_mul_f32_e32 v0, 0xbfb8aa3b, v10
	v_rcp_f32_e32 v101, v16
	v_mul_f32_e32 v16, 0xbfb8aa3b, v22
	v_exp_f32_e32 v0, v0
	v_exp_f32_e32 v16, v16
	v_and_b32_e32 v200, 0x70, v4
	v_lshl_add_u32 v9, v6, 4, 0
	v_add_f32_e32 v0, 1.0, v0
	v_add_f32_e32 v16, 1.0, v16
	v_rcp_f32_e32 v122, v0
	v_mul_f32_e32 v0, 0xbfb8aa3b, v11
	v_rcp_f32_e32 v102, v16
	v_mul_f32_e32 v16, 0xbfb8aa3b, v23
	v_exp_f32_e32 v0, v0
	v_exp_f32_e32 v16, v16
	v_and_or_b32 v11, v1, 64, v7
	v_add_u32_e32 v5, 0x4000, v9
	v_add_f32_e32 v0, 1.0, v0
	v_add_f32_e32 v16, 1.0, v16
	v_rcp_f32_e32 v123, v0
	v_mul_f32_e32 v0, 0xbfb8aa3b, v12
	v_rcp_f32_e32 v103, v16
	v_mul_f32_e32 v16, 0xbfb8aa3b, v24
	v_exp_f32_e32 v0, v0
	v_exp_f32_e32 v16, v16
	v_readfirstlane_b32 s43, v5
	v_readfirstlane_b32 s42, v9
	v_add_f32_e32 v0, 1.0, v0
	v_add_f32_e32 v16, 1.0, v16
	v_rcp_f32_e32 v124, v0
	v_mul_f32_e32 v0, 0xbfb8aa3b, v13
	v_rcp_f32_e32 v104, v16
	v_mul_f32_e32 v16, 0xbfb8aa3b, v25
	v_exp_f32_e32 v0, v0
	v_exp_f32_e32 v16, v16
	s_mov_b32 m0, s42
	v_add_f32_e32 v0, 1.0, v0
	v_add_f32_e32 v16, 1.0, v16
	v_rcp_f32_e32 v125, v0
	v_mul_f32_e32 v0, 0xbfb8aa3b, v14
	v_rcp_f32_e32 v105, v16
	v_mul_f32_e32 v16, 0xbfb8aa3b, v26
	v_exp_f32_e32 v0, v0
	v_exp_f32_e32 v16, v16
	s_barrier
; __device__ __forceinline__ float sigmoidf_(float x) { return __builtin_amdgcn_rcpf(1.f + __expf(-x)); }
; __device__ __forceinline__ int ltid() { int t = (int)threadIdx.x; asm volatile("" : "+v"(t)); return t; }
; #define ISSUE(k0, bf) do { char* A_ = lw + (bf) * BUF; \
;     _Pragma("unroll") for (int i_ = 0; i_ < 4; ++i_) { glds16(al.ptr(lrow + 32 * i_, (k0) + cg), A_ + i_ * 4096); glds16(bl.ptr(lrow + 32 * i_, (k0) + cg), A_ + ABYTES + i_ * 4096); } \
;     if (HALO) { if (wid == 0) glds16(gh + (k0), A_ + 16384); } } while (0)
; template <bool HALO, class AL, class BL>
; __device__ __forceinline__ void gemm_core(f32x16 (&acc)[2][2], f32x16& hacc, const AL& al, const BL& bl, int K, char* lds,
;                                           const u16* halo0, const u16* halo1, int brow0, int brow1) {
;     ...
;   const int tid = ltid(), lane = tid & 63, wid = tid >> 6, wr = wid >> 1, r32 = lane & 31, hi = lane >> 5;
;   const int lrow = tid >> 3, cg = ((tid & 7) ^ ((lrow >> 1) & 7)) * 8;
;   const u16* gh = nullptr;
;   if (HALO) { const int c = ((lane & 7) ^ ((lane >> 4) & 7)) * 8; gh = ((lane < 8) ? halo0 : halo1) + c; }
;   char* lw = lds + tid * 16;
;     ...
;   const int sa = ((wr * 64 + r32) >> 1) & 7, sb0 = ((brow0 + r32) >> 1) & 7, sb1 = ((brow1 + r32) >> 1) & 7, sh = (r32 >> 1) & 7;
;   const int oa = (wr * 64 + r32) * 128, ob0 = ABYTES + (brow0 + r32) * 128, ob1 = ABYTES + (brow1 + r32) * 128, oh = (128 + r32) * 128;
;   __syncthreads();
;   ISSUE(0, 0);
;   const int nk = K >> 6;
;   for (int kt = 0; kt < nk; ++kt) {
;     asm volatile("s_waitcnt vmcnt(0)" ::: "memory");
;     __syncthreads();
;     if (kt + 1 < nk) ISSUE((kt + 1) * 64, (kt + 1) & 1);
; __device__ __forceinline__ void phase_ffn_down(const P& p, int layer, char* lds) {
;     ...
; #pragma unroll
;     for (int mi = 0; mi < 2; ++mi)
; #pragma unroll
;       for (int ni = 0; ni < 2; ++ni)
; #pragma unroll
;         for (int r = 0; r < 16; ++r) acc[mi][ni][r] = sigmoidf_(acc[mi][ni][r]);
	v_add_f32_e32 v0, 1.0, v0
	v_add_f32_e32 v16, 1.0, v16
	v_rcp_f32_e32 v126, v0
	v_mul_f32_e32 v0, 0xbfb8aa3b, v15
	v_rcp_f32_e32 v106, v16
	v_mul_f32_e32 v16, 0xbfb8aa3b, v27
	v_exp_f32_e32 v0, v0
	v_exp_f32_e32 v16, v16
	v_lshrrev_b32_e32 v8, 5, v6
	v_bfe_u32 v12, v6, 1, 3
	v_add_f32_e32 v0, 1.0, v0
	v_add_f32_e32 v16, 1.0, v16
	v_rcp_f32_e32 v127, v0
	v_ashrrev_i32_e32 v0, 3, v6
	v_rcp_f32_e32 v107, v16
	v_mul_f32_e32 v16, 0xbfb8aa3b, v28
	v_ashrrev_i32_e32 v1, 31, v0
	v_exp_f32_e32 v16, v16
	v_lshlrev_b64 v[0:1], 9, v[0:1]
	v_lshl_add_u64 v[2:3], s[72:73], 0, v[0:1]
	v_lshl_add_u64 v[130:131], v[2:3], 0, v[200:201]
	v_lshl_add_u64 v[2:3], s[6:7], 0, v[0:1]
	v_lshl_add_u64 v[128:129], v[2:3], 0, v[200:201]
	v_lshl_add_u64 v[2:3], v[0:1], 0, s[18:19]
	v_add_f32_e32 v16, 1.0, v16
	v_lshl_add_u64 v[4:5], s[72:73], 0, v[2:3]
	v_lshl_add_u64 v[2:3], s[6:7], 0, v[2:3]
	v_rcp_f32_e32 v108, v16
	v_mul_f32_e32 v16, 0xbfb8aa3b, v29
	v_lshl_add_u64 v[134:135], v[2:3], 0, v[200:201]
	v_add_u32_e32 v2, 0x5000, v9
	v_exp_f32_e32 v16, v16
	v_lshl_add_u64 v[132:133], v[4:5], 0, v[200:201]
	v_add_u32_e32 v4, 0x1000, v9
	v_readfirstlane_b32 s65, v2
	v_lshl_add_u64 v[2:3], v[0:1], 0, s[36:37]
	global_load_lds_dwordx4 v[130:131], off
	s_mov_b32 m0, s43
	v_readfirstlane_b32 s64, v4
	v_lshl_add_u64 v[4:5], s[72:73], 0, v[2:3]
	v_lshl_add_u64 v[2:3], s[6:7], 0, v[2:3]
	s_mov_b64 s[18:19], 0xc000
	global_load_lds_dwordx4 v[128:129], off
	s_mov_b32 m0, s64
	v_lshl_add_u64 v[136:137], v[4:5], 0, v[200:201]
	v_add_u32_e32 v4, 0x2000, v9
	v_lshl_add_u64 v[138:139], v[2:3], 0, v[200:201]
	v_add_u32_e32 v2, 0x6000, v9
	v_lshl_add_u64 v[0:1], v[0:1], 0, s[18:19]
	global_load_lds_dwordx4 v[132:133], off
	s_mov_b32 m0, s65
	v_readfirstlane_b32 s69, v4
	v_readfirstlane_b32 s70, v2
	v_lshl_add_u64 v[2:3], s[72:73], 0, v[0:1]
	v_lshl_add_u64 v[0:1], s[6:7], 0, v[0:1]
	v_add_f32_e32 v16, 1.0, v16
	global_load_lds_dwordx4 v[134:135], off
	s_mov_b32 m0, s69
	v_lshl_add_u64 v[140:141], v[2:3], 0, v[200:201]
	v_add_u32_e32 v2, 0x3000, v9
	v_lshl_add_u64 v[142:143], v[0:1], 0, v[200:201]
	v_add_u32_e32 v0, 0x7000, v9
	v_rcp_f32_e32 v109, v16
	v_mul_f32_e32 v16, 0xbfb8aa3b, v30
	global_load_lds_dwordx4 v[136:137], off
	s_mov_b32 m0, s70
	v_readfirstlane_b32 s71, v2
	v_readfirstlane_b32 s72, v0
	v_bfe_u32 v0, v6, 5, 1
	v_bitop3_b32 v1, v8, v12, 1 bitop3:0x6c
	v_exp_f32_e32 v16, v16
	global_load_lds_dwordx4 v[138:139], off
	s_mov_b32 m0, s71
	v_lshlrev_b32_e32 v3, 4, v1
	v_bitop3_b32 v1, v0, v12, 2 bitop3:0x36
	v_add_u32_e32 v4, 0x8000, v9
	global_load_lds_dwordx4 v[140:141], off
	s_mov_b32 m0, s72
	v_lshlrev_b32_e32 v148, 4, v1
	v_bitop3_b32 v1, v0, v12, 4 bitop3:0x36
	v_bitop3_b32 v0, v0, v12, 6 bitop3:0x36
	v_add_u32_e32 v5, 0xc000, v9
	v_readfirstlane_b32 s3, v4
	global_load_lds_dwordx4 v[142:143], off
	v_lshlrev_b32_e32 v166, 4, v1
	v_lshlrev_b32_e32 v168, 4, v0
	v_lshl_add_u64 v[0:1], v[130:131], 0, s[78:79]
	s_mov_b32 m0, s3
	v_readfirstlane_b32 s6, v5
	v_add_u32_e32 v4, 0x9000, v9
	s_waitcnt vmcnt(0)
	s_waitcnt vmcnt(0) lgkmcnt(0)
	s_barrier
	global_load_lds_dwordx4 v[0:1], off
	v_lshl_add_u64 v[0:1], v[128:129], 0, s[78:79]
	s_mov_b32 m0, s6
	v_readfirstlane_b32 s7, v4
	v_add_u32_e32 v4, 0xd000, v9
	v_add_f32_e32 v16, 1.0, v16
	global_load_lds_dwordx4 v[0:1], off
	v_lshl_add_u64 v[0:1], v[132:133], 0, s[78:79]
	s_mov_b32 m0, s7
	v_readfirstlane_b32 s8, v4
	v_add_u32_e32 v4, 0xa000, v9
	v_rcp_f32_e32 v112, v16
	v_mul_f32_e32 v16, 0xbfb8aa3b, v31
	global_load_lds_dwordx4 v[0:1], off
	v_lshl_add_u64 v[0:1], v[134:135], 0, s[78:79]
	s_mov_b32 m0, s8
	v_readfirstlane_b32 s18, v4
	v_add_u32_e32 v4, 0xe000, v9
	v_exp_f32_e32 v16, v16
	global_load_lds_dwordx4 v[0:1], off
	v_lshl_add_u64 v[0:1], v[136:137], 0, s[78:79]
	s_mov_b32 m0, s18
	v_readfirstlane_b32 s19, v4
	v_add_u32_e32 v4, 0xb000, v9
	v_lshrrev_b32_e32 v10, 1, v6
	global_load_lds_dwordx4 v[0:1], off
	v_lshl_add_u64 v[0:1], v[138:139], 0, s[78:79]
	s_mov_b32 m0, s19
	v_readfirstlane_b32 s33, v4
	v_add_u32_e32 v4, 0xf000, v9
	v_and_or_b32 v2, v10, s52, v7
	global_load_lds_dwordx4 v[0:1], off
	v_lshl_add_u64 v[0:1], v[140:141], 0, s[78:79]
	s_mov_b32 m0, s33
	v_readfirstlane_b32 s63, v4
	global_load_lds_dwordx4 v[0:1], off
	v_lshl_add_u64 v[0:1], v[142:143], 0, s[78:79]
	s_mov_b32 m0, s63
	v_lshl_add_u32 v169, v2, 7, 0
	v_lshl_add_u32 v170, v11, 7, 0
	v_add_f32_e32 v16, 1.0, v16
	global_load_lds_dwordx4 v[0:1], off
	v_add_u32_e32 v147, v169, v3
	v_add_u32_e32 v146, v170, v3
	v_rcp_f32_e32 v113, v16
	ds_read_b128 v[16:19], v147
	ds_read_b128 v[64:67], v147 offset:4096
	ds_read_b128 v[68:71], v146 offset:16384
	ds_read_b128 v[72:75], v146 offset:20480
	s_waitcnt lgkmcnt(0)
	v_mfma_f32_32x32x16_bf16 v[0:15], v[16:19], v[68:71], 0
	v_add_u32_e32 v149, v169, v148
	v_add_u32_e32 v148, v170, v148
	ds_read_b128 v[150:153], v149
	ds_read_b128 v[154:157], v149 offset:4096
	ds_read_b128 v[158:161], v148 offset:16384
	ds_read_b128 v[162:165], v148 offset:20480
	s_mov_b32 m0, s42
	v_mul_f32_e32 v49, 0xbfb8aa3b, v49
	v_mul_f32_e32 v58, 0xbfb8aa3b, v58
	v_mfma_f32_32x32x16_bf16 v[16:31], v[16:19], v[72:75], 0
	v_mul_f32_e32 v59, 0xbfb8aa3b, v59
	v_exp_f32_e32 v48, v48
	v_exp_f32_e32 v49, v49
	v_mul_f32_e32 v56, 0xbfb8aa3b, v56
	v_mul_f32_e32 v57, 0xbfb8aa3b, v57
	v_exp_f32_e32 v58, v58
	v_exp_f32_e32 v59, v59
	v_mfma_f32_32x32x16_bf16 v[80:95], v[64:67], v[68:71], 0
	v_mul_f32_e32 v60, 0xbfb8aa3b, v60
	v_mul_f32_e32 v61, 0xbfb8aa3b, v61
	v_mul_f32_e32 v54, 0xbfb8aa3b, v54
	v_mul_f32_e32 v55, 0xbfb8aa3b, v55
	v_exp_f32_e32 v56, v56
	v_exp_f32_e32 v57, v57
	v_exp_f32_e32 v60, v60
	v_mfma_f32_32x32x16_bf16 v[64:79], v[64:67], v[72:75], 0
	v_exp_f32_e32 v61, v61
	v_mul_f32_e32 v52, 0xbfb8aa3b, v52
	v_mul_f32_e32 v53, 0xbfb8aa3b, v53
	v_exp_f32_e32 v54, v54
	v_exp_f32_e32 v55, v55
	v_mul_f32_e32 v50, 0xbfb8aa3b, v50
	v_mul_f32_e32 v51, 0xbfb8aa3b, v51
	s_waitcnt lgkmcnt(0)
; __device__ __forceinline__ float sigmoidf_(float x) { return __builtin_amdgcn_rcpf(1.f + __expf(-x)); }
; #define MFMA(a, b, c) __builtin_amdgcn_mfma_f32_32x32x16_bf16(a, b, c, 0, 0, 0)
; #define ISSUE(k0, bf) do { char* A_ = lw + (bf) * BUF; \
;     _Pragma("unroll") for (int i_ = 0; i_ < 4; ++i_) { glds16(al.ptr(lrow + 32 * i_, (k0) + cg), A_ + i_ * 4096); glds16(bl.ptr(lrow + 32 * i_, (k0) + cg), A_ + ABYTES + i_ * 4096); } \
;     if (HALO) { if (wid == 0) glds16(gh + (k0), A_ + 16384); } } while (0)
; template <bool HALO, class AL, class BL>
; __device__ __forceinline__ void gemm_core(f32x16 (&acc)[2][2], f32x16& hacc, const AL& al, const BL& bl, int K, char* lds,
;                                           const u16* halo0, const u16* halo1, int brow0, int brow1) {
;     ...
;   for (int kt = 0; kt < nk; ++kt) {
;     asm volatile("s_waitcnt vmcnt(0)" ::: "memory");
;     __syncthreads();
;     if (kt + 1 < nk) ISSUE((kt + 1) * 64, (kt + 1) & 1);
;     const char* T = lds + (kt & 1) * BUF;
; #pragma unroll
;     for (int kk = 0; kk < 4; ++kk) {
;       const int c = kk * 2 + hi;
;       bf16x8 a0 = *(const bf16x8*)(T + oa + ((c ^ sa) << 4));
;       bf16x8 a1 = *(const bf16x8*)(T + oa + 4096 + ((c ^ sa) << 4));
;       bf16x8 b0 = *(const bf16x8*)(T + ob0 + ((c ^ sb0) << 4));
;       bf16x8 b1 = *(const bf16x8*)(T + ob1 + ((c ^ sb1) << 4));
;       acc[0][0] = MFMA(a0, b0, acc[0][0]); acc[0][1] = MFMA(a0, b1, acc[0][1]);
;       acc[1][0] = MFMA(a1, b0, acc[1][0]); acc[1][1] = MFMA(a1, b1, acc[1][1]);
;       if (HALO) { bf16x8 ah = *(const bf16x8*)(T + oh + ((c ^ sh) << 4)); hacc = MFMA(ah, b0, hacc); }
;     }
; __device__ __forceinline__ void phase_ffn_down(const P& p, int layer, char* lds) {
;     ...
; #pragma unroll
;     for (int mi = 0; mi < 2; ++mi)
; #pragma unroll
;       for (int ni = 0; ni < 2; ++ni)
; #pragma unroll
;         for (int r = 0; r < 16; ++r) acc[mi][ni][r] = sigmoidf_(acc[mi][ni][r]);
	v_mfma_f32_32x32x16_bf16 v[0:15], v[150:153], v[158:161], v[0:15]
	v_exp_f32_e32 v52, v52
	v_exp_f32_e32 v53, v53
	v_add_f32_e32 v48, 1.0, v48
	v_add_f32_e32 v49, 1.0, v49
	v_exp_f32_e32 v50, v50
	v_exp_f32_e32 v51, v51
	v_add_f32_e32 v58, 1.0, v58
	v_mfma_f32_32x32x16_bf16 v[16:31], v[150:153], v[162:165], v[16:31]
	v_add_u32_e32 v151, v169, v166
	v_add_u32_e32 v150, v170, v166
	v_add_f32_e32 v59, 1.0, v59
	v_rcp_f32_e32 v48, v48
	v_rcp_f32_e32 v49, v49
	v_add_f32_e32 v56, 1.0, v56
	v_add_f32_e32 v57, 1.0, v57
	v_mfma_f32_32x32x16_bf16 v[80:95], v[154:157], v[158:161], v[80:95]
	v_rcp_f32_e32 v58, v58
	v_rcp_f32_e32 v59, v59
	v_add_f32_e32 v60, 1.0, v60
	v_add_f32_e32 v61, 1.0, v61
	v_mul_f32_e32 v62, 0xbfb8aa3b, v62
	v_mul_f32_e32 v63, 0xbfb8aa3b, v63
	v_add_f32_e32 v54, 1.0, v54
	v_mfma_f32_32x32x16_bf16 v[64:79], v[154:157], v[162:165], v[64:79]
	ds_read_b128 v[152:155], v151
	ds_read_b128 v[156:159], v151 offset:4096
	ds_read_b128 v[160:163], v150 offset:16384
	ds_read_b128 v[164:167], v150 offset:20480
	v_add_f32_e32 v55, 1.0, v55
	v_rcp_f32_e32 v56, v56
	v_rcp_f32_e32 v57, v57
	v_rcp_f32_e32 v60, v60
	v_rcp_f32_e32 v61, v61
	s_waitcnt lgkmcnt(0)
	v_mfma_f32_32x32x16_bf16 v[0:15], v[152:155], v[160:163], v[0:15]
	v_exp_f32_e32 v62, v62
	v_exp_f32_e32 v63, v63
	v_add_f32_e32 v52, 1.0, v52
	v_add_f32_e32 v53, 1.0, v53
	v_rcp_f32_e32 v54, v54
	v_rcp_f32_e32 v55, v55
	v_mul_f32_e32 v32, 0xbfb8aa3b, v32
	v_mfma_f32_32x32x16_bf16 v[16:31], v[152:155], v[164:167], v[16:31]
	v_add_u32_e32 v153, v169, v168
	v_add_u32_e32 v152, v170, v168
	v_mul_f32_e32 v33, 0xbfb8aa3b, v33
	v_add_f32_e32 v50, 1.0, v50
	v_add_f32_e32 v51, 1.0, v51
	v_rcp_f32_e32 v52, v52
	v_rcp_f32_e32 v53, v53
	v_mfma_f32_32x32x16_bf16 v[80:95], v[156:159], v[160:163], v[80:95]
	v_exp_f32_e32 v32, v32
	v_exp_f32_e32 v33, v33
	v_rcp_f32_e32 v50, v50
	v_rcp_f32_e32 v51, v51
	v_add_f32_e32 v62, 1.0, v62
	v_add_f32_e32 v63, 1.0, v63
	v_rcp_f32_e32 v62, v62
	v_mfma_f32_32x32x16_bf16 v[64:79], v[156:159], v[164:167], v[64:79]
	ds_read_b128 v[154:157], v153
	ds_read_b128 v[158:161], v153 offset:4096
	ds_read_b128 v[162:165], v152 offset:16384
	ds_read_b128 v[166:169], v152 offset:20480
	s_waitcnt vmcnt(0)
	s_waitcnt vmcnt(0) lgkmcnt(0)
	s_barrier
	v_rcp_f32_e32 v63, v63
	v_mfma_f32_32x32x16_bf16 v[0:15], v[154:157], v[162:165], v[0:15]
	v_add_f32_e32 v32, 1.0, v32
	v_add_f32_e32 v33, 1.0, v33
	v_rcp_f32_e32 v32, v32
	v_rcp_f32_e32 v33, v33
	v_mul_f32_e32 v34, 0xbfb8aa3b, v34
	v_mul_f32_e32 v35, 0xbfb8aa3b, v35
	v_mul_f32_e32 v36, 0xbfb8aa3b, v36
	v_mfma_f32_32x32x16_bf16 v[16:31], v[154:157], v[166:169], v[16:31]
	v_lshl_add_u64 v[154:155], v[130:131], 0, s[24:25]
	global_load_lds_dwordx4 v[154:155], off
	v_lshl_add_u64 v[154:155], v[128:129], 0, s[24:25]
	s_mov_b32 m0, s43
	v_lshl_add_u64 v[130:131], v[130:131], 0, s[74:75]
	global_load_lds_dwordx4 v[154:155], off
	v_lshl_add_u64 v[154:155], v[132:133], 0, s[24:25]
	s_mov_b32 m0, s64
	v_mfma_f32_32x32x16_bf16 v[64:79], v[158:161], v[166:169], v[64:79]
	global_load_lds_dwordx4 v[154:155], off
	v_lshl_add_u64 v[154:155], v[134:135], 0, s[24:25]
	s_mov_b32 m0, s65
	v_lshl_add_u64 v[128:129], v[128:129], 0, s[74:75]
	global_load_lds_dwordx4 v[154:155], off
	v_lshl_add_u64 v[154:155], v[136:137], 0, s[24:25]
	s_mov_b32 m0, s69
	v_mfma_f32_32x32x16_bf16 v[80:95], v[158:161], v[162:165], v[80:95]
	global_load_lds_dwordx4 v[154:155], off
	v_lshl_add_u64 v[154:155], v[138:139], 0, s[24:25]
	s_mov_b32 m0, s70
	v_mul_f32_e32 v37, 0xbfb8aa3b, v37
	global_load_lds_dwordx4 v[154:155], off
	v_lshl_add_u64 v[154:155], v[140:141], 0, s[24:25]
	s_mov_b32 m0, s71
	v_mul_f32_e32 v38, 0xbfb8aa3b, v38
	global_load_lds_dwordx4 v[154:155], off
	v_lshl_add_u64 v[154:155], v[142:143], 0, s[24:25]
	s_mov_b32 m0, s72
	v_mul_f32_e32 v39, 0xbfb8aa3b, v39
	global_load_lds_dwordx4 v[154:155], off
	ds_read_b128 v[154:157], v147 offset:32768
	ds_read_b128 v[158:161], v147 offset:36864
	ds_read_b128 v[162:165], v146 offset:49152
	ds_read_b128 v[166:169], v146 offset:53248
	s_waitcnt lgkmcnt(0)
	v_mfma_f32_32x32x16_bf16 v[0:15], v[154:157], v[162:165], v[0:15]
	s_mov_b32 m0, s3
	s_mul_i32 s3, s85, 0xb0000
	v_mul_f32_e32 v40, 0xbfb8aa3b, v40
	v_mul_f32_e32 v41, 0xbfb8aa3b, v41
	v_mul_f32_e32 v42, 0xbfb8aa3b, v42
	v_mul_f32_e32 v43, 0xbfb8aa3b, v43
	v_mul_f32_e32 v44, 0xbfb8aa3b, v44
	v_mfma_f32_32x32x16_bf16 v[64:79], v[158:161], v[166:169], v[64:79]
	v_mul_f32_e32 v45, 0xbfb8aa3b, v45
	v_mul_f32_e32 v46, 0xbfb8aa3b, v46
	v_mul_f32_e32 v47, 0xbfb8aa3b, v47
	v_exp_f32_e32 v34, v34
	v_exp_f32_e32 v35, v35
	v_exp_f32_e32 v36, v36
	v_exp_f32_e32 v37, v37
	v_mfma_f32_32x32x16_bf16 v[16:31], v[154:157], v[166:169], v[16:31]
	v_exp_f32_e32 v38, v38
	v_exp_f32_e32 v39, v39
	v_exp_f32_e32 v40, v40
	v_exp_f32_e32 v41, v41
	v_exp_f32_e32 v42, v42
	v_exp_f32_e32 v43, v43
	v_exp_f32_e32 v44, v44
	v_mfma_f32_32x32x16_bf16 v[80:95], v[158:161], v[162:165], v[80:95]
	ds_read_b128 v[154:157], v149 offset:32768
	ds_read_b128 v[158:161], v149 offset:36864
	ds_read_b128 v[162:165], v148 offset:49152
	ds_read_b128 v[166:169], v148 offset:53248
	v_exp_f32_e32 v45, v45
	v_exp_f32_e32 v46, v46
	v_exp_f32_e32 v47, v47
	v_add_f32_e32 v34, 1.0, v34
	v_add_f32_e32 v35, 1.0, v35
	v_add_f32_e32 v36, 1.0, v36
	s_waitcnt lgkmcnt(0)
	v_mfma_f32_32x32x16_bf16 v[0:15], v[154:157], v[162:165], v[0:15]
	v_add_f32_e32 v37, 1.0, v37
	v_add_f32_e32 v38, 1.0, v38
	v_add_f32_e32 v39, 1.0, v39
	v_add_f32_e32 v40, 1.0, v40
	v_add_f32_e32 v41, 1.0, v41
	v_add_f32_e32 v42, 1.0, v42
	v_add_f32_e32 v43, 1.0, v43
	v_mfma_f32_32x32x16_bf16 v[64:79], v[158:161], v[166:169], v[64:79]
	v_add_f32_e32 v44, 1.0, v44
	v_add_f32_e32 v45, 1.0, v45
	v_add_f32_e32 v46, 1.0, v46
	v_add_f32_e32 v47, 1.0, v47
	v_rcp_f32_e32 v34, v34
	v_rcp_f32_e32 v35, v35
	v_rcp_f32_e32 v36, v36
	v_mfma_f32_32x32x16_bf16 v[16:31], v[154:157], v[166:169], v[16:31]
	v_rcp_f32_e32 v37, v37
	v_rcp_f32_e32 v38, v38
	v_rcp_f32_e32 v39, v39
	v_rcp_f32_e32 v40, v40
	v_rcp_f32_e32 v41, v41
	v_rcp_f32_e32 v42, v42
	v_rcp_f32_e32 v43, v43
	v_mfma_f32_32x32x16_bf16 v[80:95], v[158:161], v[162:165], v[80:95]
	ds_read_b128 v[154:157], v151 offset:32768
	ds_read_b128 v[158:161], v151 offset:36864
	ds_read_b128 v[162:165], v150 offset:49152
	ds_read_b128 v[166:169], v150 offset:53248
	v_rcp_f32_e32 v44, v44
	v_rcp_f32_e32 v45, v45
	v_rcp_f32_e32 v46, v46
	v_rcp_f32_e32 v47, v47
	s_waitcnt lgkmcnt(0)
	v_mfma_f32_32x32x16_bf16 v[0:15], v[154:157], v[162:165], v[0:15]
	v_mfma_f32_32x32x16_bf16 v[64:79], v[158:161], v[166:169], v[64:79]
	v_mfma_f32_32x32x16_bf16 v[16:31], v[154:157], v[166:169], v[16:31]
	v_mfma_f32_32x32x16_bf16 v[80:95], v[158:161], v[162:165], v[80:95]
	ds_read_b128 v[154:157], v153 offset:32768
	ds_read_b128 v[158:161], v153 offset:36864
	ds_read_b128 v[162:165], v152 offset:49152
	ds_read_b128 v[166:169], v152 offset:53248
	s_waitcnt vmcnt(0)
	s_waitcnt vmcnt(0) lgkmcnt(0)
	s_barrier
; #define MFMA(a, b, c) __builtin_amdgcn_mfma_f32_32x32x16_bf16(a, b, c, 0, 0, 0)
; #define ISSUE(k0, bf) do { char* A_ = lw + (bf) * BUF; \
;     _Pragma("unroll") for (int i_ = 0; i_ < 4; ++i_) { glds16(al.ptr(lrow + 32 * i_, (k0) + cg), A_ + i_ * 4096); glds16(bl.ptr(lrow + 32 * i_, (k0) + cg), A_ + ABYTES + i_ * 4096); } \
;     if (HALO) { if (wid == 0) glds16(gh + (k0), A_ + 16384); } } while (0)
; template <bool HALO, class AL, class BL>
; __device__ __forceinline__ void gemm_core(f32x16 (&acc)[2][2], f32x16& hacc, const AL& al, const BL& bl, int K, char* lds,
;                                           const u16* halo0, const u16* halo1, int brow0, int brow1) {
;     ...
;   for (int kt = 0; kt < nk; ++kt) {
;     asm volatile("s_waitcnt vmcnt(0)" ::: "memory");
;     __syncthreads();
;     if (kt + 1 < nk) ISSUE((kt + 1) * 64, (kt + 1) & 1);
;     const char* T = lds + (kt & 1) * BUF;
; #pragma unroll
;     for (int kk = 0; kk < 4; ++kk) {
;       const int c = kk * 2 + hi;
;       bf16x8 a0 = *(const bf16x8*)(T + oa + ((c ^ sa) << 4));
;       bf16x8 a1 = *(const bf16x8*)(T + oa + 4096 + ((c ^ sa) << 4));
;       bf16x8 b0 = *(const bf16x8*)(T + ob0 + ((c ^ sb0) << 4));
;       bf16x8 b1 = *(const bf16x8*)(T + ob1 + ((c ^ sb1) << 4));
;       acc[0][0] = MFMA(a0, b0, acc[0][0]); acc[0][1] = MFMA(a0, b1, acc[0][1]);
;       acc[1][0] = MFMA(a1, b0, acc[1][0]); acc[1][1] = MFMA(a1, b1, acc[1][1]);
;       if (HALO) { bf16x8 ah = *(const bf16x8*)(T + oh + ((c ^ sh) << 4)); hacc = MFMA(ah, b0, hacc); }
;     }
; __device__ __forceinline__ void phase_ffn_down(const P& p, int layer, char* lds) {
;     ...
; #pragma unroll
;     for (int mi = 0; mi < 2; ++mi)
; #pragma unroll
;       for (int ni = 0; ni < 2; ++ni) acc[mi][ni] = acc[mi][ni] * acc2[mi][ni];
;     { LdBf al{ab + (long)tm * 128 * DFF, DFF}, bl{wd + (long)tn * 128 * DFF, DFF}; gemm_plain(acc, al, bl, DFF, lds); }
	global_load_lds_dwordx4 v[130:131], off
	s_mov_b32 m0, s6
	v_mfma_f32_32x32x16_bf16 v[0:15], v[154:157], v[162:165], v[0:15]
	global_load_lds_dwordx4 v[128:129], off
	v_lshl_add_u64 v[128:129], v[132:133], 0, s[74:75]
	s_mov_b32 m0, s7
	s_add_u32 s6, s53, s3
	global_load_lds_dwordx4 v[128:129], off
	v_lshl_add_u64 v[128:129], v[134:135], 0, s[74:75]
	s_mov_b32 m0, s8
	v_mfma_f32_32x32x16_bf16 v[64:79], v[158:161], v[166:169], v[64:79]
	global_load_lds_dwordx4 v[128:129], off
	v_lshl_add_u64 v[128:129], v[136:137], 0, s[74:75]
	s_mov_b32 m0, s18
	s_addc_u32 s7, s95, 0
	global_load_lds_dwordx4 v[128:129], off
	v_lshl_add_u64 v[128:129], v[138:139], 0, s[74:75]
	s_mov_b32 m0, s19
	v_mfma_f32_32x32x16_bf16 v[16:31], v[154:157], v[166:169], v[16:31]
	global_load_lds_dwordx4 v[128:129], off
	v_lshl_add_u64 v[128:129], v[140:141], 0, s[74:75]
	s_mov_b32 m0, s33
	s_mul_i32 s8, s62, 0xb0000
	global_load_lds_dwordx4 v[128:129], off
	v_lshl_add_u64 v[128:129], v[142:143], 0, s[74:75]
	s_mov_b32 m0, s63
	v_mfma_f32_32x32x16_bf16 v[80:95], v[158:161], v[162:165], v[80:95]
	global_load_lds_dwordx4 v[128:129], off
	ds_read_b128 v[128:131], v147
	ds_read_b128 v[132:135], v147 offset:4096
	ds_read_b128 v[136:139], v146 offset:16384
	ds_read_b128 v[140:143], v146 offset:20480
	s_mul_hi_i32 s3, s62, 0xb0000
	s_add_u32 s18, vcc_hi, s8
	v_readlane_b32 s8, v255, 15
	s_addc_u32 s19, s8, s3
	s_waitcnt lgkmcnt(0)
	v_mfma_f32_32x32x16_bf16 v[0:15], v[128:131], v[136:139], v[0:15]
	v_mfma_f32_32x32x16_bf16 v[64:79], v[132:135], v[140:143], v[64:79]
	v_mfma_f32_32x32x16_bf16 v[16:31], v[128:131], v[140:143], v[16:31]
	v_mfma_f32_32x32x16_bf16 v[80:95], v[132:135], v[136:139], v[80:95]
	ds_read_b128 v[128:131], v149
	ds_read_b128 v[132:135], v149 offset:4096
	ds_read_b128 v[136:139], v148 offset:16384
	ds_read_b128 v[140:143], v148 offset:20480
	s_waitcnt lgkmcnt(0)
	v_mfma_f32_32x32x16_bf16 v[0:15], v[128:131], v[136:139], v[0:15]
	v_mfma_f32_32x32x16_bf16 v[64:79], v[132:135], v[140:143], v[64:79]
	v_mfma_f32_32x32x16_bf16 v[16:31], v[128:131], v[140:143], v[16:31]
	v_mfma_f32_32x32x16_bf16 v[80:95], v[132:135], v[136:139], v[80:95]
	ds_read_b128 v[128:131], v151
	ds_read_b128 v[132:135], v151 offset:4096
	ds_read_b128 v[136:139], v150 offset:16384
	ds_read_b128 v[140:143], v150 offset:20480
	s_waitcnt lgkmcnt(0)
	v_mfma_f32_32x32x16_bf16 v[0:15], v[128:131], v[136:139], v[0:15]
	v_mfma_f32_32x32x16_bf16 v[64:79], v[132:135], v[140:143], v[64:79]
	v_mfma_f32_32x32x16_bf16 v[16:31], v[128:131], v[140:143], v[16:31]
	v_mfma_f32_32x32x16_bf16 v[80:95], v[132:135], v[136:139], v[80:95]
	ds_read_b128 v[128:131], v153
	ds_read_b128 v[132:135], v153 offset:4096
	ds_read_b128 v[136:139], v152 offset:16384
	ds_read_b128 v[140:143], v152 offset:20480
	s_waitcnt vmcnt(0)
	s_waitcnt vmcnt(0) lgkmcnt(0)
	s_barrier
	v_mfma_f32_32x32x16_bf16 v[0:15], v[128:131], v[136:139], v[0:15]
	v_mfma_f32_32x32x16_bf16 v[64:79], v[132:135], v[140:143], v[64:79]
	v_mfma_f32_32x32x16_bf16 v[16:31], v[128:131], v[140:143], v[16:31]
	v_mfma_f32_32x32x16_bf16 v[80:95], v[132:135], v[136:139], v[80:95]
	ds_read_b128 v[128:131], v147 offset:32768
	ds_read_b128 v[132:135], v147 offset:36864
	ds_read_b128 v[136:139], v146 offset:49152
	ds_read_b128 v[140:143], v146 offset:53248
	s_waitcnt lgkmcnt(1)
	v_mfma_f32_32x32x16_bf16 v[0:15], v[128:131], v[136:139], v[0:15]
	s_waitcnt lgkmcnt(0)
	v_mfma_f32_32x32x16_bf16 v[64:79], v[132:135], v[140:143], v[64:79]
	v_mfma_f32_32x32x16_bf16 v[16:31], v[128:131], v[140:143], v[16:31]
	v_mfma_f32_32x32x16_bf16 v[80:95], v[132:135], v[136:139], v[80:95]
	ds_read_b128 v[128:131], v149 offset:32768
	ds_read_b128 v[132:135], v149 offset:36864
	ds_read_b128 v[136:139], v148 offset:49152
	ds_read_b128 v[140:143], v148 offset:53248
	s_waitcnt lgkmcnt(1)
	v_mfma_f32_32x32x16_bf16 v[0:15], v[128:131], v[136:139], v[0:15]
	s_waitcnt lgkmcnt(0)
	v_mfma_f32_32x32x16_bf16 v[64:79], v[132:135], v[140:143], v[64:79]
	v_mfma_f32_32x32x16_bf16 v[16:31], v[128:131], v[140:143], v[16:31]
	v_mfma_f32_32x32x16_bf16 v[80:95], v[132:135], v[136:139], v[80:95]
	ds_read_b128 v[128:131], v151 offset:32768
	ds_read_b128 v[132:135], v151 offset:36864
	ds_read_b128 v[136:139], v150 offset:49152
	ds_read_b128 v[140:143], v150 offset:53248
	s_waitcnt lgkmcnt(1)
	v_mfma_f32_32x32x16_bf16 v[0:15], v[128:131], v[136:139], v[0:15]
	s_waitcnt lgkmcnt(0)
	v_mfma_f32_32x32x16_bf16 v[64:79], v[132:135], v[140:143], v[64:79]
	v_mfma_f32_32x32x16_bf16 v[16:31], v[128:131], v[140:143], v[16:31]
	v_mfma_f32_32x32x16_bf16 v[80:95], v[132:135], v[136:139], v[80:95]
	ds_read_b128 v[128:131], v153 offset:32768
	ds_read_b128 v[132:135], v153 offset:36864
	ds_read_b128 v[136:139], v152 offset:49152
	ds_read_b128 v[140:143], v152 offset:53248
	s_waitcnt lgkmcnt(1)
	v_mfma_f32_32x32x16_bf16 v[0:15], v[128:131], v[136:139], v[0:15]
	s_waitcnt lgkmcnt(0)
	v_mfma_f32_32x32x16_bf16 v[64:79], v[132:135], v[140:143], v[64:79]
	s_nop 9
	v_mul_f32_e64 v58, v58, v10
	v_mul_f32_e64 v59, v59, v11
	v_mul_f32_e64 v48, v48, v0
	v_mul_f32_e64 v49, v49, v1
	v_mul_f32_e64 v60, v60, v12
	v_mul_f32_e64 v61, v61, v13
	v_pk_mul_f32 v[56:57], v[56:57], v[8:9]
	v_pk_mul_f32 v[54:55], v[54:55], v[6:7]
	v_pk_mul_f32 v[52:53], v[52:53], v[4:5]
	v_pk_mul_f32 v[50:51], v[50:51], v[2:3]
	v_mfma_f32_32x32x16_bf16 v[16:31], v[128:131], v[140:143], v[16:31]
	v_mul_f32_e64 v10, v122, v74
	v_mul_f32_e64 v11, v123, v75
	v_mul_f32_e64 v0, v110, v64
	v_mul_f32_e64 v1, v111, v65
	v_mov_b32_e32 v64, v229
	v_mov_b32_e32 v75, v229
	v_pk_mul_f32 v[12:13], v[124:125], v[76:77]
	v_pk_mul_f32 v[8:9], v[120:121], v[72:73]
	v_mfma_f32_32x32x16_bf16 v[80:95], v[132:135], v[136:139], v[80:95]
	v_mul_f32_e64 v6, v118, v70
	v_mul_f32_e64 v7, v119, v71
	v_and_b32_e32 v72, 31, v75
	v_lshrrev_b32_e32 v77, 4, v75
	v_xor_b32_e32 v70, v77, v75
	v_and_or_b32 v64, v64, 64, v72
	v_pk_mul_f32 v[4:5], v[116:117], v[68:69]
	v_ashrrev_i32_e32 v76, 3, v75
	v_lshl_add_u32 v69, v75, 4, 0
	v_lshlrev_b32_e32 v68, 7, v64
	v_mov_b64_e32 v[64:65], s[6:7]
	v_lshlrev_b32_e32 v70, 4, v70
	v_pk_mul_f32 v[2:3], v[114:115], v[66:67]
	v_mad_i64_i32 v[66:67], s[6:7], v76, s9, v[64:65]
	v_and_b32_e32 v200, 0x70, v70
	v_readfirstlane_b32 s3, v69
	v_lshl_add_u64 v[66:67], v[66:67], 0, v[200:201]
	s_mov_b32 m0, s3
	v_pk_mul_f32 v[62:63], v[62:63], v[14:15]
	v_pk_mul_f32 v[14:15], v[126:127], v[78:79]
	s_barrier
; #define ISSUE(k0, bf) do { char* A_ = lw + (bf) * BUF; \
;     _Pragma("unroll") for (int i_ = 0; i_ < 4; ++i_) { glds16(al.ptr(lrow + 32 * i_, (k0) + cg), A_ + i_ * 4096); glds16(bl.ptr(lrow + 32 * i_, (k0) + cg), A_ + ABYTES + i_ * 4096); } \
;     if (HALO) { if (wid == 0) glds16(gh + (k0), A_ + 16384); } } while (0)
; template <bool HALO, class AL, class BL>
; __device__ __forceinline__ void gemm_core(f32x16 (&acc)[2][2], f32x16& hacc, const AL& al, const BL& bl, int K, char* lds,
;                                           const u16* halo0, const u16* halo1, int brow0, int brow1) {
;     ...
;   const int sa = ((wr * 64 + r32) >> 1) & 7, sb0 = ((brow0 + r32) >> 1) & 7, sb1 = ((brow1 + r32) >> 1) & 7, sh = (r32 >> 1) & 7;
;   const int oa = (wr * 64 + r32) * 128, ob0 = ABYTES + (brow0 + r32) * 128, ob1 = ABYTES + (brow1 + r32) * 128, oh = (128 + r32) * 128;
;   __syncthreads();
;   ISSUE(0, 0);
;   const int nk = K >> 6;
;   for (int kt = 0; kt < nk; ++kt) {
;     asm volatile("s_waitcnt vmcnt(0)" ::: "memory");
;     __syncthreads();
;     if (kt + 1 < nk) ISSUE((kt + 1) * 64, (kt + 1) & 1);
; __device__ __forceinline__ void phase_ffn_down(const P& p, int layer, char* lds) {
;     ...
;     { LdBf al{ab + (long)tm * 128 * DFF, DFF}, bl{wd + (long)tn * 128 * DFF, DFF}; gemm_plain(acc, al, bl, DFF, lds); }
	v_add_u32_e32 v79, 0x4000, v69
	global_load_lds_dwordx4 v[66:67], off
	v_mov_b64_e32 v[66:67], s[18:19]
	v_mad_i64_i32 v[70:71], s[6:7], v76, s9, v[66:67]
	v_readfirstlane_b32 s3, v79
	v_pk_mul_f32 v[32:33], v[32:33], v[16:17]
	v_pk_mul_f32 v[16:17], v[96:97], v[80:81]
	v_lshl_add_u64 v[70:71], v[70:71], 0, v[200:201]
	s_mov_b32 m0, s3
	v_add_u32_e32 v79, 32, v76
	v_add_u32_e32 v80, 0x1000, v69
	global_load_lds_dwordx4 v[70:71], off
	v_mad_i64_i32 v[70:71], s[6:7], v79, s9, v[64:65]
	v_readfirstlane_b32 s3, v80
	v_lshl_add_u64 v[70:71], v[70:71], 0, v[200:201]
	s_mov_b32 m0, s3
	v_add_u32_e32 v80, 0x2000, v69
	global_load_lds_dwordx4 v[70:71], off
	v_mad_i64_i32 v[70:71], s[6:7], v79, s9, v[66:67]
	v_add_u32_e32 v79, 0x5000, v69
	v_lshl_add_u64 v[70:71], v[70:71], 0, v[200:201]
	v_readfirstlane_b32 s3, v79
	s_mov_b32 m0, s3
	v_add_u32_e32 v79, 64, v76
	global_load_lds_dwordx4 v[70:71], off
	v_mad_i64_i32 v[70:71], s[6:7], v79, s9, v[64:65]
	v_readfirstlane_b32 s3, v80
	v_lshl_add_u64 v[70:71], v[70:71], 0, v[200:201]
	s_mov_b32 m0, s3
	v_lshrrev_b32_e32 v74, 1, v75
	global_load_lds_dwordx4 v[70:71], off
	v_mad_i64_i32 v[70:71], s[6:7], v79, s9, v[66:67]
	v_add_u32_e32 v79, 0x6000, v69
	v_lshl_add_u64 v[70:71], v[70:71], 0, v[200:201]
	v_readfirstlane_b32 s3, v79
	s_mov_b32 m0, s3
	v_lshrrev_b32_e32 v73, 5, v75
	global_load_lds_dwordx4 v[70:71], off
	v_add_u32_e32 v70, 0x60, v76
	v_add_u32_e32 v71, 0x3000, v69
	v_mad_i64_i32 v[64:65], s[6:7], v70, s9, v[64:65]
	v_readfirstlane_b32 s3, v71
	v_lshl_add_u64 v[64:65], v[64:65], 0, v[200:201]
	s_mov_b32 m0, s3
	v_bfe_u32 v78, v75, 1, 3
	global_load_lds_dwordx4 v[64:65], off
	v_mad_i64_i32 v[64:65], s[6:7], v70, s9, v[66:67]
	v_add_u32_e32 v66, 0x7000, v69
	v_lshl_add_u64 v[64:65], v[64:65], 0, v[200:201]
	v_readfirstlane_b32 s3, v66
	s_mov_b32 m0, s3
	s_add_i32 s3, vcc_lo, s80
	global_load_lds_dwordx4 v[64:65], off
	v_and_or_b32 v65, v74, s52, v72
	v_bfe_u32 v64, v75, 5, 1
	v_lshlrev_b32_e32 v74, 7, v65
	v_bitop3_b32 v65, v73, v78, 1 bitop3:0x6c
	v_lshlrev_b32_e32 v73, 4, v65
	v_bitop3_b32 v65, v64, v78, 2 bitop3:0x36
	v_lshlrev_b32_e32 v72, 4, v65
	v_bitop3_b32 v65, v64, v78, 4 bitop3:0x36
	v_bitop3_b32 v64, v64, v78, 6 bitop3:0x36
	s_bfe_u32 s3, s3, 0x50006
	v_lshlrev_b32_e32 v70, 4, v64
	v_mad_i64_i32 v[66:67], s[6:7], v76, s9, 0
	v_mov_b32_e32 v64, 0xb0000
	s_mul_i32 s3, s3, 0x580000
	v_lshlrev_b32_e32 v71, 4, v65
	v_mad_i64_i32 v[64:65], s[6:7], s62, v64, v[66:67]
	v_bitop3_b32 v75, v77, 7, v75 bitop3:0x48
	s_add_i32 s3, s3, s81
	v_lshlrev_b32_e32 v75, 4, v75
	s_add_u32 s6, s50, s3
	v_or_b32_e32 v64, v64, v75
	v_or_b32_e32 v66, v66, v75
	s_addc_u32 s7, s51, 0
	v_pk_mul_f32 v[46:47], v[46:47], v[30:31]
	v_pk_mul_f32 v[44:45], v[44:45], v[28:29]
	v_pk_mul_f32 v[42:43], v[42:43], v[26:27]
	v_pk_mul_f32 v[40:41], v[40:41], v[24:25]
	v_pk_mul_f32 v[38:39], v[38:39], v[22:23]
	v_pk_mul_f32 v[36:37], v[36:37], v[20:21]
	v_pk_mul_f32 v[34:35], v[34:35], v[18:19]
	v_pk_mul_f32 v[30:31], v[112:113], v[94:95]
	v_pk_mul_f32 v[28:29], v[108:109], v[92:93]
	v_pk_mul_f32 v[26:27], v[106:107], v[90:91]
	v_pk_mul_f32 v[24:25], v[104:105], v[88:89]
	v_pk_mul_f32 v[22:23], v[102:103], v[86:87]
	v_pk_mul_f32 v[20:21], v[100:101], v[84:85]
	v_pk_mul_f32 v[18:19], v[98:99], v[82:83]
	v_lshl_add_u64 v[64:65], s[54:55], 0, v[64:65]
	v_lshl_add_u64 v[66:67], s[6:7], 0, v[66:67]
	s_mov_b64 s[80:81], 0
	s_mov_b32 s6, 0
	s_nop 1
	v_readfirstlane_b32 s80, v66
	v_readfirstlane_b32 s81, v67
	v_readfirstlane_b32 s98, v64
	v_readfirstlane_b32 s99, v65
	s_nop 3
	s_sub_u32 s80, s80, 0x1000
	s_subb_u32 s81, s81, 0
	s_sub_u32 s98, s98, 0x1000
	s_subb_u32 s99, s99, 0
	s_nop 1
	v_subrev_u32_e32 v93, s80, v66
	v_subrev_u32_e32 v94, s98, v64
	s_add_u32 s80, s80, 0xa0cff80
	s_addc_u32 s81, s81, 0
	s_add_u32 s98, s98, 0x2500080
	s_addc_u32 s99, s99, 0
	s_nop 1
	global_load_dwordx4 v[128:131], v93, s[80:81]
	global_load_dwordx4 v[132:135], v94, s[98:99]
	s_add_u32 s18, s80, 0x2c000
	s_addc_u32 s19, s81, 0
	global_load_dwordx4 v[136:139], v93, s[18:19]
	s_add_u32 s18, s98, 0x2c000
	s_addc_u32 s19, s99, 0
	global_load_dwordx4 v[140:143], v94, s[18:19]
	s_add_u32 s18, s80, 0x58000
	s_addc_u32 s19, s81, 0
	global_load_dwordx4 v[146:149], v93, s[18:19]
	s_add_u32 s18, s98, 0x58000
	s_addc_u32 s19, s99, 0
	global_load_dwordx4 v[150:153], v94, s[18:19]
	s_add_u32 s18, s80, 0x84000
	s_addc_u32 s19, s81, 0
	global_load_dwordx4 v[154:157], v93, s[18:19]
	s_add_u32 s18, s98, 0x84000
	s_addc_u32 s19, s99, 0
	global_load_dwordx4 v[158:161], v94, s[18:19]
	s_add_u32 s80, s80, 0x80
	s_addc_u32 s81, s81, 0
	s_add_u32 s98, s98, 0x80
	s_addc_u32 s99, s99, 0
	s_movk_i32 s6, 21
	s_waitcnt vmcnt(8)
; #define MFMA(a, b, c) __builtin_amdgcn_mfma_f32_32x32x16_bf16(a, b, c, 0, 0, 0)
; #define ISSUE(k0, bf) do { char* A_ = lw + (bf) * BUF; \
;     _Pragma("unroll") for (int i_ = 0; i_ < 4; ++i_) { glds16(al.ptr(lrow + 32 * i_, (k0) + cg), A_ + i_ * 4096); glds16(bl.ptr(lrow + 32 * i_, (k0) + cg), A_ + ABYTES + i_ * 4096); } \
;     if (HALO) { if (wid == 0) glds16(gh + (k0), A_ + 16384); } } while (0)
; template <bool HALO, class AL, class BL>
; __device__ __forceinline__ void gemm_core(f32x16 (&acc)[2][2], f32x16& hacc, const AL& al, const BL& bl, int K, char* lds,
;                                           const u16* halo0, const u16* halo1, int brow0, int brow1) {
;     ...
;   for (int kt = 0; kt < nk; ++kt) {
;     asm volatile("s_waitcnt vmcnt(0)" ::: "memory");
;     __syncthreads();
;     if (kt + 1 < nk) ISSUE((kt + 1) * 64, (kt + 1) & 1);
;     const char* T = lds + (kt & 1) * BUF;
; #pragma unroll
;     for (int kk = 0; kk < 4; ++kk) {
;       const int c = kk * 2 + hi;
;       bf16x8 a0 = *(const bf16x8*)(T + oa + ((c ^ sa) << 4));
;       bf16x8 a1 = *(const bf16x8*)(T + oa + 4096 + ((c ^ sa) << 4));
;       bf16x8 b0 = *(const bf16x8*)(T + ob0 + ((c ^ sb0) << 4));
;       bf16x8 b1 = *(const bf16x8*)(T + ob1 + ((c ^ sb1) << 4));
;       acc[0][0] = MFMA(a0, b0, acc[0][0]); acc[0][1] = MFMA(a0, b1, acc[0][1]);
;       acc[1][0] = MFMA(a1, b0, acc[1][0]); acc[1][1] = MFMA(a1, b1, acc[1][1]);
;       if (HALO) { bf16x8 ah = *(const bf16x8*)(T + oh + ((c ^ sh) << 4)); hacc = MFMA(ah, b0, hacc); }
;     }
.Ldn_loop:
	s_waitcnt lgkmcnt(0)
	s_barrier
	v_add_u32_e32 v75, v74, v73
	v_add_u32_e32 v92, v68, v73
	ds_read_b128 v[76:79], v75 offset:0
	ds_read_b128 v[80:83], v92 offset:16384
	ds_read_b128 v[84:87], v92 offset:20480
	ds_read_b128 v[88:91], v75 offset:4096
	v_add_u32_e32 v95, v74, v72
	v_add_u32_e32 v170, v68, v72
	ds_read_b128 v[166:169], v95 offset:0
	ds_read_b128 v[162:165], v170 offset:16384
	global_load_dwordx4 v[96:99], v93, s[80:81]
	global_load_dwordx4 v[100:103], v94, s[98:99]
	s_add_u32 s18, s80, 0x2c000
	s_addc_u32 s19, s81, 0
	global_load_dwordx4 v[104:107], v93, s[18:19]
	s_add_u32 s18, s98, 0x2c000
	s_addc_u32 s19, s99, 0
	global_load_dwordx4 v[108:111], v94, s[18:19]
	s_add_u32 s18, s80, 0x58000
	s_addc_u32 s19, s81, 0
	global_load_dwordx4 v[112:115], v93, s[18:19]
	s_add_u32 s18, s98, 0x58000
	s_addc_u32 s19, s99, 0
	global_load_dwordx4 v[116:119], v94, s[18:19]
	s_add_u32 s18, s80, 0x84000
	s_addc_u32 s19, s81, 0
	global_load_dwordx4 v[120:123], v93, s[18:19]
	s_add_u32 s18, s98, 0x84000
	s_addc_u32 s19, s99, 0
	global_load_dwordx4 v[124:127], v94, s[18:19]
	s_add_u32 s80, s80, 0x80
	s_addc_u32 s81, s81, 0
	s_add_u32 s98, s98, 0x80
	s_addc_u32 s99, s99, 0
	s_waitcnt lgkmcnt(4)
	v_mfma_f32_32x32x16_bf16 v[48:63], v[76:79], v[80:83], v[48:63]
	s_waitcnt lgkmcnt(3)
	v_mfma_f32_32x32x16_bf16 v[32:47], v[76:79], v[84:87], v[32:47]
	v_add_u32_e32 v75, v74, v71
	v_add_u32_e32 v92, v68, v71
	ds_read_b128 v[76:79], v75 offset:0
	s_waitcnt lgkmcnt(3)
	v_mfma_f32_32x32x16_bf16 v[0:15], v[88:91], v[84:87], v[0:15]
	ds_read_b128 v[84:87], v170 offset:20480
	v_mfma_f32_32x32x16_bf16 v[16:31], v[88:91], v[80:83], v[16:31]
	ds_read_b128 v[88:91], v95 offset:4096
	ds_read_b128 v[80:83], v92 offset:16384
	s_waitcnt lgkmcnt(4)
	v_mfma_f32_32x32x16_bf16 v[48:63], v[166:169], v[162:165], v[48:63]
	s_waitcnt lgkmcnt(2)
	v_mfma_f32_32x32x16_bf16 v[32:47], v[166:169], v[84:87], v[32:47]
	v_add_u32_e32 v95, v74, v70
	v_add_u32_e32 v170, v68, v70
	ds_read_b128 v[166:169], v95 offset:0
	s_waitcnt lgkmcnt(2)
	v_mfma_f32_32x32x16_bf16 v[0:15], v[88:91], v[84:87], v[0:15]
	ds_read_b128 v[84:87], v92 offset:20480
	v_mfma_f32_32x32x16_bf16 v[16:31], v[88:91], v[162:165], v[16:31]
	ds_read_b128 v[88:91], v75 offset:4096
	ds_read_b128 v[162:165], v170 offset:16384
	s_waitcnt lgkmcnt(4)
	v_mfma_f32_32x32x16_bf16 v[48:63], v[76:79], v[80:83], v[48:63]
	s_waitcnt lgkmcnt(2)
	v_mfma_f32_32x32x16_bf16 v[32:47], v[76:79], v[84:87], v[32:47]
	s_waitcnt lgkmcnt(1)
	v_mfma_f32_32x32x16_bf16 v[0:15], v[88:91], v[84:87], v[0:15]
	ds_read_b128 v[84:87], v170 offset:20480
	v_mfma_f32_32x32x16_bf16 v[16:31], v[88:91], v[80:83], v[16:31]
	ds_read_b128 v[88:91], v95 offset:4096
	s_waitcnt lgkmcnt(2)
	v_mfma_f32_32x32x16_bf16 v[48:63], v[166:169], v[162:165], v[48:63]
	s_waitcnt lgkmcnt(1)
	v_mfma_f32_32x32x16_bf16 v[32:47], v[166:169], v[84:87], v[32:47]
	s_waitcnt lgkmcnt(0)
	v_mfma_f32_32x32x16_bf16 v[0:15], v[88:91], v[84:87], v[0:15]
	v_mfma_f32_32x32x16_bf16 v[16:31], v[88:91], v[162:165], v[16:31]
	s_waitcnt vmcnt(8)
	ds_write_b128 v69, v[128:131] offset:32768
	ds_write_b128 v69, v[132:135] offset:49152
	ds_write_b128 v69, v[136:139] offset:36864
	ds_write_b128 v69, v[140:143] offset:53248
	ds_write_b128 v69, v[146:149] offset:40960
	ds_write_b128 v69, v[150:153] offset:57344
	ds_write_b128 v69, v[154:157] offset:45056
	ds_write_b128 v69, v[158:161] offset:61440
	s_waitcnt lgkmcnt(0)
	s_barrier
	v_add_u32_e32 v75, v74, v73
	v_add_u32_e32 v92, v68, v73
	ds_read_b128 v[76:79], v75 offset:32768
	ds_read_b128 v[80:83], v92 offset:49152
	ds_read_b128 v[84:87], v92 offset:53248
	ds_read_b128 v[88:91], v75 offset:36864
	v_add_u32_e32 v95, v74, v72
	v_add_u32_e32 v170, v68, v72
	ds_read_b128 v[166:169], v95 offset:32768
	ds_read_b128 v[162:165], v170 offset:49152
	global_load_dwordx4 v[128:131], v93, s[80:81]
	global_load_dwordx4 v[132:135], v94, s[98:99]
	s_add_u32 s18, s80, 0x2c000
	s_addc_u32 s19, s81, 0
	global_load_dwordx4 v[136:139], v93, s[18:19]
	s_add_u32 s18, s98, 0x2c000
	s_addc_u32 s19, s99, 0
	global_load_dwordx4 v[140:143], v94, s[18:19]
	s_add_u32 s18, s80, 0x58000
	s_addc_u32 s19, s81, 0
	global_load_dwordx4 v[146:149], v93, s[18:19]
	s_add_u32 s18, s98, 0x58000
	s_addc_u32 s19, s99, 0
	global_load_dwordx4 v[150:153], v94, s[18:19]
	s_add_u32 s18, s80, 0x84000
	s_addc_u32 s19, s81, 0
	global_load_dwordx4 v[154:157], v93, s[18:19]
	s_add_u32 s18, s98, 0x84000
	s_addc_u32 s19, s99, 0
	global_load_dwordx4 v[158:161], v94, s[18:19]
	s_add_u32 s80, s80, 0x80
	s_addc_u32 s81, s81, 0
	s_add_u32 s98, s98, 0x80
	s_addc_u32 s99, s99, 0
	s_waitcnt lgkmcnt(4)
	v_mfma_f32_32x32x16_bf16 v[48:63], v[76:79], v[80:83], v[48:63]
	s_waitcnt lgkmcnt(3)
	v_mfma_f32_32x32x16_bf16 v[32:47], v[76:79], v[84:87], v[32:47]
	v_add_u32_e32 v75, v74, v71
	v_add_u32_e32 v92, v68, v71
	ds_read_b128 v[76:79], v75 offset:32768
	s_waitcnt lgkmcnt(3)
	v_mfma_f32_32x32x16_bf16 v[0:15], v[88:91], v[84:87], v[0:15]
	ds_read_b128 v[84:87], v170 offset:53248
	v_mfma_f32_32x32x16_bf16 v[16:31], v[88:91], v[80:83], v[16:31]
	ds_read_b128 v[88:91], v95 offset:36864
	ds_read_b128 v[80:83], v92 offset:49152
	s_waitcnt lgkmcnt(4)
	v_mfma_f32_32x32x16_bf16 v[48:63], v[166:169], v[162:165], v[48:63]
	s_waitcnt lgkmcnt(2)
	v_mfma_f32_32x32x16_bf16 v[32:47], v[166:169], v[84:87], v[32:47]
	v_add_u32_e32 v95, v74, v70
	v_add_u32_e32 v170, v68, v70
	ds_read_b128 v[166:169], v95 offset:32768
	s_waitcnt lgkmcnt(2)
	v_mfma_f32_32x32x16_bf16 v[0:15], v[88:91], v[84:87], v[0:15]
	ds_read_b128 v[84:87], v92 offset:53248
	v_mfma_f32_32x32x16_bf16 v[16:31], v[88:91], v[162:165], v[16:31]
	ds_read_b128 v[88:91], v75 offset:36864
	ds_read_b128 v[162:165], v170 offset:49152
	s_waitcnt lgkmcnt(4)
	v_mfma_f32_32x32x16_bf16 v[48:63], v[76:79], v[80:83], v[48:63]
	s_waitcnt lgkmcnt(2)
	v_mfma_f32_32x32x16_bf16 v[32:47], v[76:79], v[84:87], v[32:47]
	s_waitcnt lgkmcnt(1)
	v_mfma_f32_32x32x16_bf16 v[0:15], v[88:91], v[84:87], v[0:15]
	ds_read_b128 v[84:87], v170 offset:53248
	v_mfma_f32_32x32x16_bf16 v[16:31], v[88:91], v[80:83], v[16:31]
	ds_read_b128 v[88:91], v95 offset:36864
	s_waitcnt lgkmcnt(2)
	v_mfma_f32_32x32x16_bf16 v[48:63], v[166:169], v[162:165], v[48:63]
	s_waitcnt lgkmcnt(1)
	v_mfma_f32_32x32x16_bf16 v[32:47], v[166:169], v[84:87], v[32:47]
	s_waitcnt lgkmcnt(0)
	v_mfma_f32_32x32x16_bf16 v[0:15], v[88:91], v[84:87], v[0:15]
	v_mfma_f32_32x32x16_bf16 v[16:31], v[88:91], v[162:165], v[16:31]
	s_waitcnt vmcnt(8)
	ds_write_b128 v69, v[96:99] offset:0
	ds_write_b128 v69, v[100:103] offset:16384
	ds_write_b128 v69, v[104:107] offset:4096
	ds_write_b128 v69, v[108:111] offset:20480
	ds_write_b128 v69, v[112:115] offset:8192
	ds_write_b128 v69, v[116:119] offset:24576
	ds_write_b128 v69, v[120:123] offset:12288
	ds_write_b128 v69, v[124:127] offset:28672
	s_add_i32 s6, s6, -1
	s_cmp_eq_u32 s6, 0
	s_cbranch_scc0 .Ldn_loop
; __device__ __forceinline__ float bf2f(u16 v) { return __uint_as_float(((unsigned)v) << 16); }
; __device__ __forceinline__ int opq() { int z = 0; asm volatile("" : "+v"(z)); return z; }
; #define MFMA(a, b, c) __builtin_amdgcn_mfma_f32_32x32x16_bf16(a, b, c, 0, 0, 0)
; #define ISSUE(k0, bf) do { char* A_ = lw + (bf) * BUF; \
;     _Pragma("unroll") for (int i_ = 0; i_ < 4; ++i_) { glds16(al.ptr(lrow + 32 * i_, (k0) + cg), A_ + i_ * 4096); glds16(bl.ptr(lrow + 32 * i_, (k0) + cg), A_ + ABYTES + i_ * 4096); } \
;     if (HALO) { if (wid == 0) glds16(gh + (k0), A_ + 16384); } } while (0)
; template <bool HALO, class AL, class BL>
; __device__ __forceinline__ void gemm_core(f32x16 (&acc)[2][2], f32x16& hacc, const AL& al, const BL& bl, int K, char* lds,
;                                           const u16* halo0, const u16* halo1, int brow0, int brow1) {
;     ...
;   for (int kt = 0; kt < nk; ++kt) {
;     asm volatile("s_waitcnt vmcnt(0)" ::: "memory");
;     __syncthreads();
;     if (kt + 1 < nk) ISSUE((kt + 1) * 64, (kt + 1) & 1);
;     const char* T = lds + (kt & 1) * BUF;
; #pragma unroll
;     for (int kk = 0; kk < 4; ++kk) {
;       const int c = kk * 2 + hi;
;       bf16x8 a0 = *(const bf16x8*)(T + oa + ((c ^ sa) << 4));
;       bf16x8 a1 = *(const bf16x8*)(T + oa + 4096 + ((c ^ sa) << 4));
;       bf16x8 b0 = *(const bf16x8*)(T + ob0 + ((c ^ sb0) << 4));
;       bf16x8 b1 = *(const bf16x8*)(T + ob1 + ((c ^ sb1) << 4));
;       acc[0][0] = MFMA(a0, b0, acc[0][0]); acc[0][1] = MFMA(a0, b1, acc[0][1]);
;       acc[1][0] = MFMA(a1, b0, acc[1][0]); acc[1][1] = MFMA(a1, b1, acc[1][1]);
;       if (HALO) { bf16x8 ah = *(const bf16x8*)(T + oh + ((c ^ sh) << 4)); hacc = MFMA(ah, b0, hacc); }
;     }
; __device__ __forceinline__ void phase_ffn_down(const P& p, int layer, char* lds) {
;     ...
;     const unsigned rb = (unsigned)(tm * 128 + wr * 64 + 4 * hi + opq());
; #pragma unroll
;     for (int mi = 0; mi < 2; ++mi) {
; #pragma unroll
;       for (int ni = 0; ni < 2; ++ni)
; #pragma unroll
;         for (int r = 0; r < 16; ++r) {
;           const unsigned row = rb + mi * 32 + (r & 3) + 8 * (r >> 2); const unsigned col = tn * 128 + wc * 64 + ni * 32 + r32;
;           ((_Float16*)(p.ws + OFF_PRE2))[row * DM + col] = (_Float16)(ALPHA * bf2f(xb[row * DM + col]) + acc[mi][ni][r]);
;         }
	s_waitcnt lgkmcnt(0)
	s_barrier
	v_add_u32_e32 v75, v74, v73
	v_add_u32_e32 v92, v68, v73
	ds_read_b128 v[76:79], v75 offset:0
	ds_read_b128 v[80:83], v92 offset:16384
	ds_read_b128 v[84:87], v92 offset:20480
	ds_read_b128 v[88:91], v75 offset:4096
	v_add_u32_e32 v95, v74, v72
	v_add_u32_e32 v170, v68, v72
	ds_read_b128 v[166:169], v95 offset:0
	ds_read_b128 v[162:165], v170 offset:16384
	s_waitcnt lgkmcnt(4)
	v_mfma_f32_32x32x16_bf16 v[48:63], v[76:79], v[80:83], v[48:63]
	s_waitcnt lgkmcnt(3)
	v_mfma_f32_32x32x16_bf16 v[32:47], v[76:79], v[84:87], v[32:47]
	v_add_u32_e32 v75, v74, v71
	v_add_u32_e32 v92, v68, v71
	ds_read_b128 v[76:79], v75 offset:0
	s_waitcnt lgkmcnt(3)
	v_mfma_f32_32x32x16_bf16 v[0:15], v[88:91], v[84:87], v[0:15]
	ds_read_b128 v[84:87], v170 offset:20480
	v_mfma_f32_32x32x16_bf16 v[16:31], v[88:91], v[80:83], v[16:31]
	ds_read_b128 v[88:91], v95 offset:4096
	ds_read_b128 v[80:83], v92 offset:16384
	s_waitcnt lgkmcnt(4)
	v_mfma_f32_32x32x16_bf16 v[48:63], v[166:169], v[162:165], v[48:63]
	s_waitcnt lgkmcnt(2)
	v_mfma_f32_32x32x16_bf16 v[32:47], v[166:169], v[84:87], v[32:47]
	v_add_u32_e32 v95, v74, v70
	v_add_u32_e32 v170, v68, v70
	ds_read_b128 v[166:169], v95 offset:0
	s_waitcnt lgkmcnt(2)
	v_mfma_f32_32x32x16_bf16 v[0:15], v[88:91], v[84:87], v[0:15]
	ds_read_b128 v[84:87], v92 offset:20480
	v_mfma_f32_32x32x16_bf16 v[16:31], v[88:91], v[162:165], v[16:31]
	ds_read_b128 v[88:91], v75 offset:4096
	ds_read_b128 v[162:165], v170 offset:16384
	s_waitcnt lgkmcnt(4)
	v_mfma_f32_32x32x16_bf16 v[48:63], v[76:79], v[80:83], v[48:63]
	s_waitcnt lgkmcnt(2)
	v_mfma_f32_32x32x16_bf16 v[32:47], v[76:79], v[84:87], v[32:47]
	s_waitcnt lgkmcnt(1)
	v_mfma_f32_32x32x16_bf16 v[0:15], v[88:91], v[84:87], v[0:15]
	ds_read_b128 v[84:87], v170 offset:20480
	v_mfma_f32_32x32x16_bf16 v[16:31], v[88:91], v[80:83], v[16:31]
	ds_read_b128 v[88:91], v95 offset:4096
	s_waitcnt lgkmcnt(2)
	v_mfma_f32_32x32x16_bf16 v[48:63], v[166:169], v[162:165], v[48:63]
	s_waitcnt lgkmcnt(1)
	v_mfma_f32_32x32x16_bf16 v[32:47], v[166:169], v[84:87], v[32:47]
	s_waitcnt lgkmcnt(0)
	v_mfma_f32_32x32x16_bf16 v[0:15], v[88:91], v[84:87], v[0:15]
	v_mfma_f32_32x32x16_bf16 v[16:31], v[88:91], v[162:165], v[16:31]
	s_waitcnt vmcnt(0)
	ds_write_b128 v69, v[128:131] offset:32768
	ds_write_b128 v69, v[132:135] offset:49152
	ds_write_b128 v69, v[136:139] offset:36864
	ds_write_b128 v69, v[140:143] offset:53248
	ds_write_b128 v69, v[146:149] offset:40960
	ds_write_b128 v69, v[150:153] offset:57344
	ds_write_b128 v69, v[154:157] offset:45056
	ds_write_b128 v69, v[158:161] offset:61440
	s_waitcnt lgkmcnt(0)
	v_add_u32_e32 v69, 0, v74
	v_add_u32_e32 v68, 0, v68
	v_add_u32_e32 v74, v69, v73
	v_add_u32_e32 v73, v68, v73
	s_waitcnt vmcnt(0)
	s_waitcnt vmcnt(0)
	s_barrier
	ds_read_b128 v[64:67], v74 offset:32768
	ds_read_b128 v[74:77], v74 offset:36864
	ds_read_b128 v[78:81], v73 offset:49152
	ds_read_b128 v[82:85], v73 offset:53248
	s_waitcnt lgkmcnt(1)
	v_mfma_f32_32x32x16_bf16 v[48:63], v[64:67], v[78:81], v[48:63]
	v_add_u32_e32 v73, v69, v72
	v_add_u32_e32 v72, v68, v72
	s_waitcnt lgkmcnt(0)
	v_mfma_f32_32x32x16_bf16 v[32:47], v[64:67], v[82:85], v[32:47]
	v_mfma_f32_32x32x16_bf16 v[16:31], v[74:77], v[78:81], v[16:31]
	v_mfma_f32_32x32x16_bf16 v[0:15], v[74:77], v[82:85], v[0:15]
	ds_read_b128 v[64:67], v73 offset:32768
	ds_read_b128 v[74:77], v73 offset:36864
	ds_read_b128 v[78:81], v72 offset:49152
	ds_read_b128 v[82:85], v72 offset:53248
	v_add_u32_e32 v72, v69, v71
	v_add_u32_e32 v71, v68, v71
	v_add_u32_e32 v69, v69, v70
	s_waitcnt lgkmcnt(1)
	v_mfma_f32_32x32x16_bf16 v[48:63], v[64:67], v[78:81], v[48:63]
	s_waitcnt lgkmcnt(0)
	v_mfma_f32_32x32x16_bf16 v[32:47], v[64:67], v[82:85], v[32:47]
	v_mfma_f32_32x32x16_bf16 v[16:31], v[74:77], v[78:81], v[16:31]
	v_mfma_f32_32x32x16_bf16 v[0:15], v[74:77], v[82:85], v[0:15]
	ds_read_b128 v[64:67], v72 offset:32768
	ds_read_b128 v[72:75], v72 offset:36864
	ds_read_b128 v[76:79], v71 offset:49152
	ds_read_b128 v[80:83], v71 offset:53248
	s_waitcnt lgkmcnt(1)
	v_mfma_f32_32x32x16_bf16 v[48:63], v[64:67], v[76:79], v[48:63]
	s_waitcnt lgkmcnt(0)
	v_mfma_f32_32x32x16_bf16 v[32:47], v[64:67], v[80:83], v[32:47]
	v_mfma_f32_32x32x16_bf16 v[16:31], v[72:75], v[76:79], v[16:31]
	v_add_u32_e32 v76, v68, v70
	v_mfma_f32_32x32x16_bf16 v[0:15], v[72:75], v[80:83], v[0:15]
	ds_read_b128 v[64:67], v69 offset:32768
	ds_read_b128 v[72:75], v69 offset:36864
	ds_read_b128 v[68:71], v76 offset:49152
	ds_read_b128 v[76:79], v76 offset:53248
	s_waitcnt lgkmcnt(1)
	v_mfma_f32_32x32x16_bf16 v[48:63], v[64:67], v[68:71], v[48:63]
	s_waitcnt lgkmcnt(0)
	v_mfma_f32_32x32x16_bf16 v[32:47], v[64:67], v[76:79], v[32:47]
	v_mov_b32_e32 v66, v201
	v_lshl_add_u32 v67, s85, 7, v144
	v_lshl_or_b32 v65, s62, 7, v145
	v_add_lshl_u32 v66, v67, v66, 10
	v_add_u32_e32 v200, v66, v65
	v_or_b32_e32 v64, 32, v65
	v_mfma_f32_32x32x16_bf16 v[16:31], v[72:75], v[68:71], v[16:31]
	v_lshlrev_b64 v[68:69], 1, v[200:201]
	v_lshl_add_u64 v[70:71], s[40:41], 0, v[68:69]
	global_load_ushort v67, v[70:71], off
	v_lshl_add_u64 v[68:69], s[60:61], 0, v[68:69]
	s_waitcnt vmcnt(0)
	v_lshlrev_b32_e32 v67, 16, v67
	v_fma_mixlo_f16 v48, v67, s12, v48
	global_store_short v[68:69], v48, off
	v_add_u32_e32 v48, 0x400, v66
	v_add_u32_e32 v200, v48, v65
	v_lshlrev_b64 v[68:69], 1, v[200:201]
	v_lshl_add_u64 v[70:71], s[40:41], 0, v[68:69]
	global_load_ushort v67, v[70:71], off
	v_lshl_add_u64 v[68:69], s[60:61], 0, v[68:69]
	v_mfma_f32_32x32x16_bf16 v[0:15], v[72:75], v[76:79], v[0:15]
	s_waitcnt vmcnt(0)
; __device__ __forceinline__ float bf2f(u16 v) { return __uint_as_float(((unsigned)v) << 16); }
; __device__ __forceinline__ int opq() { int z = 0; asm volatile("" : "+v"(z)); return z; }
; #define SBAR() __builtin_amdgcn_sched_barrier(0)
; __device__ __forceinline__ void phase_ffn_down(const P& p, int layer, char* lds) {
;     ...
;     const unsigned rb = (unsigned)(tm * 128 + wr * 64 + 4 * hi + opq());
; #pragma unroll
;     for (int mi = 0; mi < 2; ++mi) {
; #pragma unroll
;       for (int ni = 0; ni < 2; ++ni)
; #pragma unroll
;         for (int r = 0; r < 16; ++r) {
;           const unsigned row = rb + mi * 32 + (r & 3) + 8 * (r >> 2); const unsigned col = tn * 128 + wc * 64 + ni * 32 + r32;
;           ((_Float16*)(p.ws + OFF_PRE2))[row * DM + col] = (_Float16)(ALPHA * bf2f(xb[row * DM + col]) + acc[mi][ni][r]);
;         }
;       SBAR();
;     }
	v_lshlrev_b32_e32 v67, 16, v67
	v_fma_mixlo_f16 v49, v67, s12, v49
	global_store_short v[68:69], v49, off
	v_add_u32_e32 v49, 0x800, v66
	v_add_u32_e32 v200, v49, v65
	v_lshlrev_b64 v[68:69], 1, v[200:201]
	v_lshl_add_u64 v[70:71], s[40:41], 0, v[68:69]
	global_load_ushort v67, v[70:71], off
	v_lshl_add_u64 v[68:69], s[60:61], 0, v[68:69]
	s_waitcnt vmcnt(0)
	v_lshlrev_b32_e32 v67, 16, v67
	v_fma_mixlo_f16 v50, v67, s12, v50
	global_store_short v[68:69], v50, off
	v_add_u32_e32 v50, 0xc00, v66
	v_add_u32_e32 v200, v50, v65
	v_lshlrev_b64 v[68:69], 1, v[200:201]
	v_lshl_add_u64 v[70:71], s[40:41], 0, v[68:69]
	global_load_ushort v67, v[70:71], off
	v_lshl_add_u64 v[68:69], s[60:61], 0, v[68:69]
	s_waitcnt vmcnt(0)
	v_lshlrev_b32_e32 v67, 16, v67
	v_fma_mixlo_f16 v51, v67, s12, v51
	global_store_short v[68:69], v51, off
	v_add_u32_e32 v51, 0x2000, v66
	v_add_u32_e32 v200, v51, v65
	v_lshlrev_b64 v[68:69], 1, v[200:201]
	v_lshl_add_u64 v[70:71], s[40:41], 0, v[68:69]
	global_load_ushort v67, v[70:71], off
	v_lshl_add_u64 v[68:69], s[60:61], 0, v[68:69]
	s_waitcnt vmcnt(0)
	v_lshlrev_b32_e32 v67, 16, v67
	v_fma_mixlo_f16 v52, v67, s12, v52
	global_store_short v[68:69], v52, off
	v_add_u32_e32 v52, 0x2400, v66
	v_add_u32_e32 v200, v52, v65
	v_lshlrev_b64 v[68:69], 1, v[200:201]
	v_lshl_add_u64 v[70:71], s[40:41], 0, v[68:69]
	global_load_ushort v67, v[70:71], off
	v_lshl_add_u64 v[68:69], s[60:61], 0, v[68:69]
	s_waitcnt vmcnt(0)
	v_lshlrev_b32_e32 v67, 16, v67
	v_fma_mixlo_f16 v53, v67, s12, v53
	global_store_short v[68:69], v53, off
	v_add_u32_e32 v53, 0x2800, v66
	v_add_u32_e32 v200, v53, v65
	v_lshlrev_b64 v[68:69], 1, v[200:201]
	v_lshl_add_u64 v[70:71], s[40:41], 0, v[68:69]
	global_load_ushort v67, v[70:71], off
	v_lshl_add_u64 v[68:69], s[60:61], 0, v[68:69]
	s_waitcnt vmcnt(0)
	v_lshlrev_b32_e32 v67, 16, v67
	v_fma_mixlo_f16 v54, v67, s12, v54
	global_store_short v[68:69], v54, off
	v_add_u32_e32 v54, 0x2c00, v66
	v_add_u32_e32 v200, v54, v65
	v_lshlrev_b64 v[68:69], 1, v[200:201]
	v_lshl_add_u64 v[70:71], s[40:41], 0, v[68:69]
	global_load_ushort v67, v[70:71], off
	v_lshl_add_u64 v[68:69], s[60:61], 0, v[68:69]
	s_waitcnt vmcnt(0)
	v_lshlrev_b32_e32 v67, 16, v67
	v_fma_mixlo_f16 v55, v67, s12, v55
	global_store_short v[68:69], v55, off
	v_add_u32_e32 v55, 0x4000, v66
	v_add_u32_e32 v200, v55, v65
	v_lshlrev_b64 v[68:69], 1, v[200:201]
	v_lshl_add_u64 v[70:71], s[40:41], 0, v[68:69]
	global_load_ushort v67, v[70:71], off
	v_lshl_add_u64 v[68:69], s[60:61], 0, v[68:69]
	s_waitcnt vmcnt(0)
	v_lshlrev_b32_e32 v67, 16, v67
	v_fma_mixlo_f16 v56, v67, s12, v56
	global_store_short v[68:69], v56, off
	v_add_u32_e32 v56, 0x4400, v66
	v_add_u32_e32 v200, v56, v65
	v_lshlrev_b64 v[68:69], 1, v[200:201]
	v_lshl_add_u64 v[70:71], s[40:41], 0, v[68:69]
	global_load_ushort v67, v[70:71], off
	v_lshl_add_u64 v[68:69], s[60:61], 0, v[68:69]
	s_waitcnt vmcnt(0)
	v_lshlrev_b32_e32 v67, 16, v67
	v_fma_mixlo_f16 v57, v67, s12, v57
	global_store_short v[68:69], v57, off
	v_add_u32_e32 v57, 0x4800, v66
	v_add_u32_e32 v200, v57, v65
	v_lshlrev_b64 v[68:69], 1, v[200:201]
	v_lshl_add_u64 v[70:71], s[40:41], 0, v[68:69]
	global_load_ushort v67, v[70:71], off
	v_lshl_add_u64 v[68:69], s[60:61], 0, v[68:69]
	s_waitcnt vmcnt(0)
	v_lshlrev_b32_e32 v67, 16, v67
	v_fma_mixlo_f16 v58, v67, s12, v58
	global_store_short v[68:69], v58, off
	v_add_u32_e32 v58, 0x4c00, v66
	v_add_u32_e32 v200, v58, v65
	v_lshlrev_b64 v[68:69], 1, v[200:201]
	v_lshl_add_u64 v[70:71], s[40:41], 0, v[68:69]
	global_load_ushort v67, v[70:71], off
	v_lshl_add_u64 v[68:69], s[60:61], 0, v[68:69]
	s_waitcnt vmcnt(0)
	v_lshlrev_b32_e32 v67, 16, v67
	v_fma_mixlo_f16 v59, v67, s12, v59
	global_store_short v[68:69], v59, off
	v_add_u32_e32 v59, 0x6000, v66
	v_add_u32_e32 v200, v59, v65
	v_lshlrev_b64 v[68:69], 1, v[200:201]
	v_lshl_add_u64 v[70:71], s[40:41], 0, v[68:69]
	global_load_ushort v67, v[70:71], off
	v_lshl_add_u64 v[68:69], s[60:61], 0, v[68:69]
	s_waitcnt vmcnt(0)
	v_lshlrev_b32_e32 v67, 16, v67
	v_fma_mixlo_f16 v60, v67, s12, v60
	v_add_u32_e32 v67, 0x6400, v66
	v_add_u32_e32 v200, v67, v65
	global_store_short v[68:69], v60, off
	v_lshlrev_b64 v[68:69], 1, v[200:201]
	v_lshl_add_u64 v[70:71], s[40:41], 0, v[68:69]
	global_load_ushort v60, v[70:71], off
	v_add_u32_e32 v71, 0x6c00, v66
	s_waitcnt vmcnt(0)
	v_lshlrev_b32_e32 v60, 16, v60
	v_fma_mixlo_f16 v70, v60, s12, v61
	v_lshl_add_u64 v[60:61], s[60:61], 0, v[68:69]
	global_store_short v[60:61], v70, off
	v_add_u32_e32 v70, 0x6800, v66
	v_add_u32_e32 v200, v70, v65
	v_lshlrev_b64 v[60:61], 1, v[200:201]
	v_lshl_add_u64 v[68:69], s[40:41], 0, v[60:61]
	global_load_ushort v68, v[68:69], off
	v_lshl_add_u64 v[60:61], s[60:61], 0, v[60:61]
	v_add_u32_e32 v200, v71, v65
	s_waitcnt vmcnt(0)
	v_lshlrev_b32_e32 v68, 16, v68
	v_fma_mixlo_f16 v62, v68, s12, v62
	global_store_short v[60:61], v62, off
	v_lshlrev_b64 v[60:61], 1, v[200:201]
	v_lshl_add_u64 v[68:69], s[40:41], 0, v[60:61]
	global_load_ushort v62, v[68:69], off
	v_lshl_add_u64 v[60:61], s[60:61], 0, v[60:61]
	v_add_u32_e32 v200, v66, v64
	s_waitcnt vmcnt(0)
	v_lshlrev_b32_e32 v62, 16, v62
	v_fma_mixlo_f16 v62, v62, s12, v63
	global_store_short v[60:61], v62, off
	v_lshlrev_b64 v[60:61], 1, v[200:201]
	v_lshl_add_u64 v[62:63], s[40:41], 0, v[60:61]
	global_load_ushort v62, v[62:63], off
	v_lshl_add_u64 v[60:61], s[60:61], 0, v[60:61]
	v_add_u32_e32 v200, v48, v64
	s_waitcnt vmcnt(0)
	v_lshlrev_b32_e32 v62, 16, v62
	v_fma_mixlo_f16 v32, v62, s12, v32
	global_store_short v[60:61], v32, off
	v_lshlrev_b64 v[60:61], 1, v[200:201]
	v_lshl_add_u64 v[62:63], s[40:41], 0, v[60:61]
	global_load_ushort v32, v[62:63], off
	v_add_u32_e32 v200, v49, v64
	s_waitcnt vmcnt(0)
; __device__ __forceinline__ float bf2f(u16 v) { return __uint_as_float(((unsigned)v) << 16); }
; __device__ __forceinline__ int opq() { int z = 0; asm volatile("" : "+v"(z)); return z; }
; #define SBAR() __builtin_amdgcn_sched_barrier(0)
; __device__ __forceinline__ void phase_ffn_down(const P& p, int layer, char* lds) {
;     ...
;     const unsigned rb = (unsigned)(tm * 128 + wr * 64 + 4 * hi + opq());
; #pragma unroll
;     for (int mi = 0; mi < 2; ++mi) {
; #pragma unroll
;       for (int ni = 0; ni < 2; ++ni)
; #pragma unroll
;         for (int r = 0; r < 16; ++r) {
;           const unsigned row = rb + mi * 32 + (r & 3) + 8 * (r >> 2); const unsigned col = tn * 128 + wc * 64 + ni * 32 + r32;
;           ((_Float16*)(p.ws + OFF_PRE2))[row * DM + col] = (_Float16)(ALPHA * bf2f(xb[row * DM + col]) + acc[mi][ni][r]);
;         }
;       SBAR();
;     }
	v_lshlrev_b32_e32 v32, 16, v32
	v_fma_mixlo_f16 v48, v32, s12, v33
	v_lshl_add_u64 v[32:33], s[60:61], 0, v[60:61]
	global_store_short v[32:33], v48, off
	v_lshlrev_b64 v[32:33], 1, v[200:201]
	v_lshl_add_u64 v[48:49], s[40:41], 0, v[32:33]
	global_load_ushort v48, v[48:49], off
	v_lshl_add_u64 v[32:33], s[60:61], 0, v[32:33]
	v_add_u32_e32 v200, v50, v64
	s_waitcnt vmcnt(0)
	v_lshlrev_b32_e32 v48, 16, v48
	v_fma_mixlo_f16 v34, v48, s12, v34
	global_store_short v[32:33], v34, off
	v_lshlrev_b64 v[32:33], 1, v[200:201]
	v_lshl_add_u64 v[48:49], s[40:41], 0, v[32:33]
	global_load_ushort v34, v[48:49], off
	v_lshl_add_u64 v[32:33], s[60:61], 0, v[32:33]
	v_add_u32_e32 v200, v51, v64
	s_waitcnt vmcnt(0)
	v_lshlrev_b32_e32 v34, 16, v34
	v_fma_mixlo_f16 v34, v34, s12, v35
	global_store_short v[32:33], v34, off
	v_lshlrev_b64 v[32:33], 1, v[200:201]
	v_lshl_add_u64 v[34:35], s[40:41], 0, v[32:33]
	global_load_ushort v34, v[34:35], off
	v_lshl_add_u64 v[32:33], s[60:61], 0, v[32:33]
	v_add_u32_e32 v200, v52, v64
	s_waitcnt vmcnt(0)
	v_lshlrev_b32_e32 v34, 16, v34
	v_fma_mixlo_f16 v34, v34, s12, v36
	global_store_short v[32:33], v34, off
	v_lshlrev_b64 v[32:33], 1, v[200:201]
	v_lshl_add_u64 v[34:35], s[40:41], 0, v[32:33]
	global_load_ushort v34, v[34:35], off
	v_lshl_add_u64 v[32:33], s[60:61], 0, v[32:33]
	v_add_u32_e32 v200, v53, v64
	s_waitcnt vmcnt(0)
	v_lshlrev_b32_e32 v34, 16, v34
	v_fma_mixlo_f16 v34, v34, s12, v37
	global_store_short v[32:33], v34, off
	v_lshlrev_b64 v[32:33], 1, v[200:201]
	v_lshl_add_u64 v[34:35], s[40:41], 0, v[32:33]
	global_load_ushort v34, v[34:35], off
	v_lshl_add_u64 v[32:33], s[60:61], 0, v[32:33]
	v_add_u32_e32 v200, v54, v64
	s_waitcnt vmcnt(0)
	v_lshlrev_b32_e32 v34, 16, v34
	v_fma_mixlo_f16 v34, v34, s12, v38
	global_store_short v[32:33], v34, off
	v_lshlrev_b64 v[32:33], 1, v[200:201]
	v_lshl_add_u64 v[34:35], s[40:41], 0, v[32:33]
	global_load_ushort v34, v[34:35], off
	v_lshl_add_u64 v[32:33], s[60:61], 0, v[32:33]
	v_add_u32_e32 v200, v55, v64
	s_waitcnt vmcnt(0)
	v_lshlrev_b32_e32 v34, 16, v34
	v_fma_mixlo_f16 v34, v34, s12, v39
	global_store_short v[32:33], v34, off
	v_lshlrev_b64 v[32:33], 1, v[200:201]
	v_lshl_add_u64 v[34:35], s[40:41], 0, v[32:33]
	global_load_ushort v34, v[34:35], off
	v_lshl_add_u64 v[32:33], s[60:61], 0, v[32:33]
	v_add_u32_e32 v200, v56, v64
	s_waitcnt vmcnt(0)
	v_lshlrev_b32_e32 v34, 16, v34
	v_fma_mixlo_f16 v34, v34, s12, v40
	global_store_short v[32:33], v34, off
	v_lshlrev_b64 v[32:33], 1, v[200:201]
	v_lshl_add_u64 v[34:35], s[40:41], 0, v[32:33]
	global_load_ushort v34, v[34:35], off
	v_lshl_add_u64 v[32:33], s[60:61], 0, v[32:33]
	v_add_u32_e32 v200, v57, v64
	s_waitcnt vmcnt(0)
	v_lshlrev_b32_e32 v34, 16, v34
	v_fma_mixlo_f16 v34, v34, s12, v41
	global_store_short v[32:33], v34, off
	v_lshlrev_b64 v[32:33], 1, v[200:201]
	v_lshl_add_u64 v[34:35], s[40:41], 0, v[32:33]
	global_load_ushort v34, v[34:35], off
	v_lshl_add_u64 v[32:33], s[60:61], 0, v[32:33]
	v_add_u32_e32 v200, v58, v64
	s_waitcnt vmcnt(0)
	v_lshlrev_b32_e32 v34, 16, v34
	v_fma_mixlo_f16 v34, v34, s12, v42
	global_store_short v[32:33], v34, off
	v_lshlrev_b64 v[32:33], 1, v[200:201]
	v_lshl_add_u64 v[34:35], s[40:41], 0, v[32:33]
	global_load_ushort v34, v[34:35], off
	v_lshl_add_u64 v[32:33], s[60:61], 0, v[32:33]
	v_add_u32_e32 v200, v59, v64
	s_waitcnt vmcnt(0)
	v_lshlrev_b32_e32 v34, 16, v34
	v_fma_mixlo_f16 v34, v34, s12, v43
	global_store_short v[32:33], v34, off
	v_lshlrev_b64 v[32:33], 1, v[200:201]
	v_lshl_add_u64 v[34:35], s[40:41], 0, v[32:33]
	global_load_ushort v34, v[34:35], off
	v_lshl_add_u64 v[32:33], s[60:61], 0, v[32:33]
	v_add_u32_e32 v200, v67, v64
	s_waitcnt vmcnt(0)
	v_lshlrev_b32_e32 v34, 16, v34
	v_fma_mixlo_f16 v34, v34, s12, v44
	global_store_short v[32:33], v34, off
	v_lshlrev_b64 v[32:33], 1, v[200:201]
	v_lshl_add_u64 v[34:35], s[40:41], 0, v[32:33]
	global_load_ushort v34, v[34:35], off
	v_lshl_add_u64 v[32:33], s[60:61], 0, v[32:33]
	v_add_u32_e32 v200, v70, v64
	s_waitcnt vmcnt(0)
	v_lshlrev_b32_e32 v34, 16, v34
	v_fma_mixlo_f16 v34, v34, s12, v45
	global_store_short v[32:33], v34, off
	v_lshlrev_b64 v[32:33], 1, v[200:201]
	v_lshl_add_u64 v[34:35], s[40:41], 0, v[32:33]
	global_load_ushort v34, v[34:35], off
	v_lshl_add_u64 v[32:33], s[60:61], 0, v[32:33]
	v_add_u32_e32 v200, v71, v64
	s_waitcnt vmcnt(0)
	v_lshlrev_b32_e32 v34, 16, v34
	v_fma_mixlo_f16 v34, v34, s12, v46
	global_store_short v[32:33], v34, off
	v_lshlrev_b64 v[32:33], 1, v[200:201]
	v_lshl_add_u64 v[34:35], s[40:41], 0, v[32:33]
	global_load_ushort v34, v[34:35], off
	v_lshl_add_u64 v[32:33], s[60:61], 0, v[32:33]
	s_waitcnt vmcnt(0)
	v_lshlrev_b32_e32 v34, 16, v34
	v_fma_mixlo_f16 v34, v34, s12, v47
	global_store_short v[32:33], v34, off
	v_add_u32_e32 v32, 0x8000, v66
	v_add_u32_e32 v200, v32, v65
	v_lshlrev_b64 v[34:35], 1, v[200:201]
	v_lshl_add_u64 v[36:37], s[40:41], 0, v[34:35]
	global_load_ushort v33, v[36:37], off
	v_lshl_add_u64 v[34:35], s[60:61], 0, v[34:35]
	s_waitcnt vmcnt(0)
	v_lshlrev_b32_e32 v33, 16, v33
	v_fma_mixlo_f16 v16, v33, s12, v16
	global_store_short v[34:35], v16, off
	v_add_u32_e32 v16, 0x8400, v66
	v_add_u32_e32 v200, v16, v65
	v_lshlrev_b64 v[34:35], 1, v[200:201]
	v_lshl_add_u64 v[36:37], s[40:41], 0, v[34:35]
	global_load_ushort v33, v[36:37], off
	v_lshl_add_u64 v[34:35], s[60:61], 0, v[34:35]
	s_waitcnt vmcnt(0)
	v_lshlrev_b32_e32 v33, 16, v33
	v_fma_mixlo_f16 v17, v33, s12, v17
	global_store_short v[34:35], v17, off
	v_add_u32_e32 v17, 0x8800, v66
	v_add_u32_e32 v200, v17, v65
	v_lshlrev_b64 v[34:35], 1, v[200:201]
	v_lshl_add_u64 v[36:37], s[40:41], 0, v[34:35]
	global_load_ushort v33, v[36:37], off
	v_lshl_add_u64 v[34:35], s[60:61], 0, v[34:35]
	s_waitcnt vmcnt(0)
; __device__ __forceinline__ float bf2f(u16 v) { return __uint_as_float(((unsigned)v) << 16); }
; __device__ __forceinline__ int opq() { int z = 0; asm volatile("" : "+v"(z)); return z; }
; #define SBAR() __builtin_amdgcn_sched_barrier(0)
; __device__ __forceinline__ void phase_ffn_down(const P& p, int layer, char* lds) {
;     ...
;     const unsigned rb = (unsigned)(tm * 128 + wr * 64 + 4 * hi + opq());
; #pragma unroll
;     for (int mi = 0; mi < 2; ++mi) {
; #pragma unroll
;       for (int ni = 0; ni < 2; ++ni)
; #pragma unroll
;         for (int r = 0; r < 16; ++r) {
;           const unsigned row = rb + mi * 32 + (r & 3) + 8 * (r >> 2); const unsigned col = tn * 128 + wc * 64 + ni * 32 + r32;
;           ((_Float16*)(p.ws + OFF_PRE2))[row * DM + col] = (_Float16)(ALPHA * bf2f(xb[row * DM + col]) + acc[mi][ni][r]);
;         }
;       SBAR();
;     }
	v_lshlrev_b32_e32 v33, 16, v33
	v_fma_mixlo_f16 v18, v33, s12, v18
	global_store_short v[34:35], v18, off
	v_add_u32_e32 v18, 0x8c00, v66
	v_add_u32_e32 v200, v18, v65
	v_lshlrev_b64 v[34:35], 1, v[200:201]
	v_lshl_add_u64 v[36:37], s[40:41], 0, v[34:35]
	global_load_ushort v33, v[36:37], off
	v_lshl_add_u64 v[34:35], s[60:61], 0, v[34:35]
	s_waitcnt vmcnt(0)
	v_lshlrev_b32_e32 v33, 16, v33
	v_fma_mixlo_f16 v19, v33, s12, v19
	global_store_short v[34:35], v19, off
	v_add_u32_e32 v19, 0xa000, v66
	v_add_u32_e32 v200, v19, v65
	v_lshlrev_b64 v[34:35], 1, v[200:201]
	v_lshl_add_u64 v[36:37], s[40:41], 0, v[34:35]
	global_load_ushort v33, v[36:37], off
	v_lshl_add_u64 v[34:35], s[60:61], 0, v[34:35]
	s_waitcnt vmcnt(0)
	v_lshlrev_b32_e32 v33, 16, v33
	v_fma_mixlo_f16 v20, v33, s12, v20
	global_store_short v[34:35], v20, off
	v_add_u32_e32 v20, 0xa400, v66
	v_add_u32_e32 v200, v20, v65
	v_lshlrev_b64 v[34:35], 1, v[200:201]
	v_lshl_add_u64 v[36:37], s[40:41], 0, v[34:35]
	global_load_ushort v33, v[36:37], off
	v_lshl_add_u64 v[34:35], s[60:61], 0, v[34:35]
	s_waitcnt vmcnt(0)
	v_lshlrev_b32_e32 v33, 16, v33
	v_fma_mixlo_f16 v21, v33, s12, v21
	global_store_short v[34:35], v21, off
	v_add_u32_e32 v21, 0xa800, v66
	v_add_u32_e32 v200, v21, v65
	v_lshlrev_b64 v[34:35], 1, v[200:201]
	v_lshl_add_u64 v[36:37], s[40:41], 0, v[34:35]
	global_load_ushort v33, v[36:37], off
	v_lshl_add_u64 v[34:35], s[60:61], 0, v[34:35]
	s_waitcnt vmcnt(0)
	v_lshlrev_b32_e32 v33, 16, v33
	v_fma_mixlo_f16 v22, v33, s12, v22
	global_store_short v[34:35], v22, off
	v_add_u32_e32 v22, 0xac00, v66
	v_add_u32_e32 v200, v22, v65
	v_lshlrev_b64 v[34:35], 1, v[200:201]
	v_lshl_add_u64 v[36:37], s[40:41], 0, v[34:35]
	global_load_ushort v33, v[36:37], off
	v_lshl_add_u64 v[34:35], s[60:61], 0, v[34:35]
	s_waitcnt vmcnt(0)
	v_lshlrev_b32_e32 v33, 16, v33
	v_fma_mixlo_f16 v23, v33, s12, v23
	global_store_short v[34:35], v23, off
	v_add_u32_e32 v23, 0xc000, v66
	v_add_u32_e32 v200, v23, v65
	v_lshlrev_b64 v[34:35], 1, v[200:201]
	v_lshl_add_u64 v[36:37], s[40:41], 0, v[34:35]
	global_load_ushort v33, v[36:37], off
	v_lshl_add_u64 v[34:35], s[60:61], 0, v[34:35]
	s_waitcnt vmcnt(0)
	v_lshlrev_b32_e32 v33, 16, v33
	v_fma_mixlo_f16 v24, v33, s12, v24
	global_store_short v[34:35], v24, off
	v_add_u32_e32 v24, 0xc400, v66
	v_add_u32_e32 v200, v24, v65
	v_lshlrev_b64 v[34:35], 1, v[200:201]
	v_lshl_add_u64 v[36:37], s[40:41], 0, v[34:35]
	global_load_ushort v33, v[36:37], off
	v_lshl_add_u64 v[34:35], s[60:61], 0, v[34:35]
	s_waitcnt vmcnt(0)
	v_lshlrev_b32_e32 v33, 16, v33
	v_fma_mixlo_f16 v25, v33, s12, v25
	global_store_short v[34:35], v25, off
	v_add_u32_e32 v25, 0xc800, v66
	v_add_u32_e32 v200, v25, v65
	v_lshlrev_b64 v[34:35], 1, v[200:201]
	v_lshl_add_u64 v[36:37], s[40:41], 0, v[34:35]
	global_load_ushort v33, v[36:37], off
	v_lshl_add_u64 v[34:35], s[60:61], 0, v[34:35]
	s_waitcnt vmcnt(0)
	v_lshlrev_b32_e32 v33, 16, v33
	v_fma_mixlo_f16 v26, v33, s12, v26
	global_store_short v[34:35], v26, off
	v_add_u32_e32 v26, 0xcc00, v66
	v_add_u32_e32 v200, v26, v65
	v_lshlrev_b64 v[34:35], 1, v[200:201]
	v_lshl_add_u64 v[36:37], s[40:41], 0, v[34:35]
	global_load_ushort v33, v[36:37], off
	v_lshl_add_u64 v[34:35], s[60:61], 0, v[34:35]
	s_waitcnt vmcnt(0)
	v_lshlrev_b32_e32 v33, 16, v33
	v_fma_mixlo_f16 v27, v33, s12, v27
	global_store_short v[34:35], v27, off
	v_add_u32_e32 v27, 0xe000, v66
	v_add_u32_e32 v200, v27, v65
	v_lshlrev_b64 v[34:35], 1, v[200:201]
	v_lshl_add_u64 v[36:37], s[40:41], 0, v[34:35]
	global_load_ushort v33, v[36:37], off
	v_lshl_add_u64 v[34:35], s[60:61], 0, v[34:35]
	s_waitcnt vmcnt(0)
	v_lshlrev_b32_e32 v33, 16, v33
	v_fma_mixlo_f16 v28, v33, s12, v28
	v_add_u32_e32 v33, 0xe400, v66
	v_add_u32_e32 v200, v33, v65
	global_store_short v[34:35], v28, off
	v_lshlrev_b64 v[34:35], 1, v[200:201]
	v_lshl_add_u64 v[36:37], s[40:41], 0, v[34:35]
	global_load_ushort v28, v[36:37], off
	v_add_u32_e32 v37, 0xec00, v66
	s_waitcnt vmcnt(0)
	v_lshlrev_b32_e32 v28, 16, v28
	v_fma_mixlo_f16 v36, v28, s12, v29
	v_lshl_add_u64 v[28:29], s[60:61], 0, v[34:35]
	global_store_short v[28:29], v36, off
	v_add_u32_e32 v36, 0xe800, v66
	v_add_u32_e32 v200, v36, v65
	v_lshlrev_b64 v[28:29], 1, v[200:201]
	v_lshl_add_u64 v[34:35], s[40:41], 0, v[28:29]
	global_load_ushort v34, v[34:35], off
	v_lshl_add_u64 v[28:29], s[60:61], 0, v[28:29]
	v_add_u32_e32 v200, v37, v65
	s_waitcnt vmcnt(0)
	v_lshlrev_b32_e32 v34, 16, v34
	v_fma_mixlo_f16 v30, v34, s12, v30
	global_store_short v[28:29], v30, off
	v_lshlrev_b64 v[28:29], 1, v[200:201]
	v_lshl_add_u64 v[34:35], s[40:41], 0, v[28:29]
	global_load_ushort v30, v[34:35], off
	v_lshl_add_u64 v[28:29], s[60:61], 0, v[28:29]
	v_add_u32_e32 v200, v32, v64
	s_waitcnt vmcnt(0)
	v_lshlrev_b32_e32 v30, 16, v30
	v_fma_mixlo_f16 v30, v30, s12, v31
	global_store_short v[28:29], v30, off
	v_lshlrev_b64 v[28:29], 1, v[200:201]
	v_lshl_add_u64 v[30:31], s[40:41], 0, v[28:29]
	global_load_ushort v30, v[30:31], off
	v_lshl_add_u64 v[28:29], s[60:61], 0, v[28:29]
	v_add_u32_e32 v200, v16, v64
	s_waitcnt vmcnt(0)
; __device__ __forceinline__ float bf2f(u16 v) { return __uint_as_float(((unsigned)v) << 16); }
; __device__ __forceinline__ int opq() { int z = 0; asm volatile("" : "+v"(z)); return z; }
; #define SBAR() __builtin_amdgcn_sched_barrier(0)
; __device__ __forceinline__ bool tile_at(int it, int nM, int nN, int& tm, int& tn) {
;   const int total = nM * nN, per = (total + 7) / 8, x = blockIdx.x & 7, lb = blockIdx.x >> 3, nlb = gridDim.x >> 3;
;   const int i = lb + it * nlb; if (i >= per) return false;
;   const int idx = x * per + i; if (idx >= total) return false;
;   const int grp = idx / (8 * nN), rem = idx - grp * 8 * nN;
;   tm = grp * 8 + (rem & 7); tn = rem >> 3; return true;
; __device__ __forceinline__ void phase_ffn_down(const P& p, int layer, char* lds) {
;     ...
;     const unsigned rb = (unsigned)(tm * 128 + wr * 64 + 4 * hi + opq());
; #pragma unroll
;     for (int mi = 0; mi < 2; ++mi) {
; #pragma unroll
;       for (int ni = 0; ni < 2; ++ni)
; #pragma unroll
;         for (int r = 0; r < 16; ++r) {
;           const unsigned row = rb + mi * 32 + (r & 3) + 8 * (r >> 2); const unsigned col = tn * 128 + wc * 64 + ni * 32 + r32;
;           ((_Float16*)(p.ws + OFF_PRE2))[row * DM + col] = (_Float16)(ALPHA * bf2f(xb[row * DM + col]) + acc[mi][ni][r]);
;         }
;       SBAR();
;     }
	v_lshlrev_b32_e32 v30, 16, v30
	v_fma_mixlo_f16 v0, v30, s12, v0
	global_store_short v[28:29], v0, off
	v_lshlrev_b64 v[28:29], 1, v[200:201]
	v_lshl_add_u64 v[30:31], s[40:41], 0, v[28:29]
	global_load_ushort v0, v[30:31], off
	v_add_u32_e32 v200, v17, v64
	s_waitcnt vmcnt(0)
	v_lshlrev_b32_e32 v0, 16, v0
	v_fma_mixlo_f16 v16, v0, s12, v1
	v_lshl_add_u64 v[0:1], s[60:61], 0, v[28:29]
	global_store_short v[0:1], v16, off
	v_lshlrev_b64 v[0:1], 1, v[200:201]
	v_lshl_add_u64 v[16:17], s[40:41], 0, v[0:1]
	global_load_ushort v16, v[16:17], off
	v_lshl_add_u64 v[0:1], s[60:61], 0, v[0:1]
	v_add_u32_e32 v200, v18, v64
	s_waitcnt vmcnt(0)
	v_lshlrev_b32_e32 v16, 16, v16
	v_fma_mixlo_f16 v2, v16, s12, v2
	global_store_short v[0:1], v2, off
	v_lshlrev_b64 v[0:1], 1, v[200:201]
	v_lshl_add_u64 v[16:17], s[40:41], 0, v[0:1]
	global_load_ushort v2, v[16:17], off
	v_lshl_add_u64 v[0:1], s[60:61], 0, v[0:1]
	v_add_u32_e32 v200, v19, v64
	s_waitcnt vmcnt(0)
	v_lshlrev_b32_e32 v2, 16, v2
	v_fma_mixlo_f16 v2, v2, s12, v3
	global_store_short v[0:1], v2, off
	v_lshlrev_b64 v[0:1], 1, v[200:201]
	v_lshl_add_u64 v[2:3], s[40:41], 0, v[0:1]
	global_load_ushort v2, v[2:3], off
	v_lshl_add_u64 v[0:1], s[60:61], 0, v[0:1]
	v_add_u32_e32 v200, v20, v64
	s_waitcnt vmcnt(0)
	v_lshlrev_b32_e32 v2, 16, v2
	v_fma_mixlo_f16 v2, v2, s12, v4
	global_store_short v[0:1], v2, off
	v_lshlrev_b64 v[0:1], 1, v[200:201]
	v_lshl_add_u64 v[2:3], s[40:41], 0, v[0:1]
	global_load_ushort v2, v[2:3], off
	v_lshl_add_u64 v[0:1], s[60:61], 0, v[0:1]
	v_add_u32_e32 v200, v21, v64
	s_waitcnt vmcnt(0)
	v_lshlrev_b32_e32 v2, 16, v2
	v_fma_mixlo_f16 v2, v2, s12, v5
	global_store_short v[0:1], v2, off
	v_lshlrev_b64 v[0:1], 1, v[200:201]
	v_lshl_add_u64 v[2:3], s[40:41], 0, v[0:1]
	global_load_ushort v2, v[2:3], off
	v_lshl_add_u64 v[0:1], s[60:61], 0, v[0:1]
	v_add_u32_e32 v200, v22, v64
	s_waitcnt vmcnt(0)
	v_lshlrev_b32_e32 v2, 16, v2
	v_fma_mixlo_f16 v2, v2, s12, v6
	global_store_short v[0:1], v2, off
	v_lshlrev_b64 v[0:1], 1, v[200:201]
	v_lshl_add_u64 v[2:3], s[40:41], 0, v[0:1]
	global_load_ushort v2, v[2:3], off
	v_lshl_add_u64 v[0:1], s[60:61], 0, v[0:1]
	v_add_u32_e32 v200, v23, v64
	s_waitcnt vmcnt(0)
	v_lshlrev_b32_e32 v2, 16, v2
	v_fma_mixlo_f16 v2, v2, s12, v7
	global_store_short v[0:1], v2, off
	v_lshlrev_b64 v[0:1], 1, v[200:201]
	v_lshl_add_u64 v[2:3], s[40:41], 0, v[0:1]
	global_load_ushort v2, v[2:3], off
	v_lshl_add_u64 v[0:1], s[60:61], 0, v[0:1]
	v_add_u32_e32 v200, v24, v64
	s_waitcnt vmcnt(0)
	v_lshlrev_b32_e32 v2, 16, v2
	v_fma_mixlo_f16 v2, v2, s12, v8
	global_store_short v[0:1], v2, off
	v_lshlrev_b64 v[0:1], 1, v[200:201]
	v_lshl_add_u64 v[2:3], s[40:41], 0, v[0:1]
	global_load_ushort v2, v[2:3], off
	v_lshl_add_u64 v[0:1], s[60:61], 0, v[0:1]
	v_add_u32_e32 v200, v25, v64
	s_waitcnt vmcnt(0)
	v_lshlrev_b32_e32 v2, 16, v2
	v_fma_mixlo_f16 v2, v2, s12, v9
	global_store_short v[0:1], v2, off
	v_lshlrev_b64 v[0:1], 1, v[200:201]
	v_lshl_add_u64 v[2:3], s[40:41], 0, v[0:1]
	global_load_ushort v2, v[2:3], off
	v_lshl_add_u64 v[0:1], s[60:61], 0, v[0:1]
	v_add_u32_e32 v200, v26, v64
	s_waitcnt vmcnt(0)
	v_lshlrev_b32_e32 v2, 16, v2
	v_fma_mixlo_f16 v2, v2, s12, v10
	global_store_short v[0:1], v2, off
	v_lshlrev_b64 v[0:1], 1, v[200:201]
	v_lshl_add_u64 v[2:3], s[40:41], 0, v[0:1]
	global_load_ushort v2, v[2:3], off
	v_lshl_add_u64 v[0:1], s[60:61], 0, v[0:1]
	v_add_u32_e32 v200, v27, v64
	s_waitcnt vmcnt(0)
	v_lshlrev_b32_e32 v2, 16, v2
	v_fma_mixlo_f16 v2, v2, s12, v11
	global_store_short v[0:1], v2, off
	v_lshlrev_b64 v[0:1], 1, v[200:201]
	v_lshl_add_u64 v[2:3], s[40:41], 0, v[0:1]
	global_load_ushort v2, v[2:3], off
	v_lshl_add_u64 v[0:1], s[60:61], 0, v[0:1]
	v_add_u32_e32 v200, v33, v64
	s_waitcnt vmcnt(0)
	v_lshlrev_b32_e32 v2, 16, v2
	v_fma_mixlo_f16 v2, v2, s12, v12
	global_store_short v[0:1], v2, off
	v_lshlrev_b64 v[0:1], 1, v[200:201]
	v_lshl_add_u64 v[2:3], s[40:41], 0, v[0:1]
	global_load_ushort v2, v[2:3], off
	v_lshl_add_u64 v[0:1], s[60:61], 0, v[0:1]
	v_add_u32_e32 v200, v36, v64
	s_waitcnt vmcnt(0)
	v_lshlrev_b32_e32 v2, 16, v2
	v_fma_mixlo_f16 v2, v2, s12, v13
	global_store_short v[0:1], v2, off
	v_lshlrev_b64 v[0:1], 1, v[200:201]
	v_lshl_add_u64 v[2:3], s[40:41], 0, v[0:1]
	global_load_ushort v2, v[2:3], off
	v_lshl_add_u64 v[0:1], s[60:61], 0, v[0:1]
	v_add_u32_e32 v200, v37, v64
	s_waitcnt vmcnt(0)
	v_lshlrev_b32_e32 v2, 16, v2
	v_fma_mixlo_f16 v2, v2, s12, v14
	global_store_short v[0:1], v2, off
	v_lshlrev_b64 v[0:1], 1, v[200:201]
	v_lshl_add_u64 v[2:3], s[40:41], 0, v[0:1]
	global_load_ushort v2, v[2:3], off
	v_lshl_add_u64 v[0:1], s[60:61], 0, v[0:1]
	s_waitcnt vmcnt(0)
	v_lshlrev_b32_e32 v2, 16, v2
	v_fma_mixlo_f16 v2, v2, s12, v15
	global_store_short v[0:1], v2, off
	s_add_i32 s84, s84, 1
	v_readlane_b32 s3, v255, 25
	s_mul_i32 s3, s84, s3
	s_add_i32 s80, s3, s13
	s_cmpk_gt_u32 s80, 0xff
	s_cbranch_scc0 .LBB0_155
